# GEMM K-loops: the two k-step MFMAs of each accumulator issued back to back (SrcC forwarding chain) instead of 8 MFMAs apart; plus no s_setprio
# speedup vs baseline: 1.0162x; 1.0071x over previous
; #define PG8_STAGE(bufoff, gbase, voff) do { _Pragma("unroll") for (int _i = 0; _i < 2; ++_i) \
;         __builtin_amdgcn_global_load_lds((const GAS unsigned*)((const GAS char*)(gbase) + (voff)[_i]), (PG8_LAS unsigned*)(lds + (bufoff) + ldsw + _i * 8192), 16, 0, 0); } while (0)
; #define PG8_LDA(dst, b, h) do { _Pragma("unroll") for (int m = 0; m < 4; ++m) _Pragma("unroll") for (int k = 0; k < 2; ++k) dst[m][k] = *(const PG8_LAS bf16x8*)(lds + PG8_SA(b, h) + aoff + m * 2048 + k * 1024); } while (0)
; #define PG8_LDB(dst, b, h) do { _Pragma("unroll") for (int n = 0; n < 2; ++n) _Pragma("unroll") for (int k = 0; k < 2; ++k) dst[n][k] = *(const PG8_LAS bf16x8*)(lds + PG8_SB(b, h) + boff + n * 2048 + k * 1024); } while (0)
; #define PG8_MMA(ai, bj, At, Bt) do { __builtin_amdgcn_s_setprio(1); _Pragma("unroll") for (int m = 0; m < 4; ++m) _Pragma("unroll") for (int n = 0; n < 2; ++n) _Pragma("unroll") for (int k = 0; k < 2; ++k) \
;         acc[ai][bj][m][n] = __builtin_amdgcn_mfma_f32_16x16x32_bf16(Bt[n][k], At[m][k], acc[ai][bj][m][n], 0, 0, 0); __builtin_amdgcn_s_setprio(0); } while (0)
; #define PG8_WAIT_V(n) asm volatile("s_waitcnt vmcnt(" #n ")" ::: "memory")
; #define PG8_WAIT_L(n) asm volatile("s_waitcnt lgkmcnt(" #n ")" ::: "memory")
; #define PG8_BAR __builtin_amdgcn_s_barrier()
; #define PG8_SCHED __builtin_amdgcn_sched_barrier(0)
; #define PG8_STAGE(bufoff, gbase, voff) do { _Pragma("unroll") for (int _i = 0; _i < 2; ++_i) \
;         __builtin_amdgcn_global_load_lds((const GAS unsigned*)((const GAS char*)(gbase) + (voff)[_i]), (PG8_LAS unsigned*)(lds + (bufoff) + ldsw + _i * 8192), 16, 0, 0); } while (0)
; #define PG8_LDA(dst, b, h) do { _Pragma("unroll") for (int m = 0; m < 4; ++m) _Pragma("unroll") for (int k = 0; k < 2; ++k) dst[m][k] = *(const PG8_LAS bf16x8*)(lds + PG8_SA(b, h) + aoff + m * 2048 + k * 1024); } while (0)
; #define PG8_BAR __builtin_amdgcn_s_barrier()
; template <class Epi, class Sched>
; __device__ __forceinline__ void gemm_phase_strip(PG8_LAS unsigned char* lds, PG8_LAS unsigned char* slds, PG8_LAS unsigned char* pf, const Gemm g, const Sched& S, const Epi& E, int wv) {
;     ...
;             PG8_LDB(B0, 0, 0); PG8_LDB(B1, 0, 1); PG8_SCHED; PG8_LDA(At, 0, 0); PG8_STAGE(PG8_SA(1, 1), a1 + PG8_HS, voffA);
;             PG8_WAIT_V(8); PG8_WAIT_L(0); PG8_BAR; PG8_MMA(0, 0, At, B0); PG8_MMA(0, 1, At, B1); PG8_BAR; PG8_SCHED;
.LBB0_244:
	s_cmp_eq_u32 s24, s94
	s_cselect_b64 s[2:3], -1, 0
	s_add_u32 s25, s42, s94
	s_addc_u32 s28, s43, s95
	s_add_u32 s25, s25, 0x100
	s_addc_u32 s40, s28, 0
	s_and_b64 s[28:29], s[2:3], exec
	s_cselect_b32 s29, s7, s40
	s_cselect_b32 s28, s6, s25
	s_add_u32 s25, s48, s94
	s_addc_u32 s44, s85, s95
	s_add_i32 s66, 0, 0x10000
	v_add_u32_e32 v128, s66, v247
	s_add_i32 s67, 0, 0x14000
	ds_read_b128 v[156:159], v128
	ds_read_b128 v[152:155], v128 offset:1024
	ds_read_b128 v[174:177], v128 offset:2048
	ds_read_b128 v[170:173], v128 offset:3072
	v_add_u32_e32 v128, s67, v247
	ds_read_b128 v[166:169], v128
	ds_read_b128 v[162:165], v128 offset:1024
	ds_read_b128 v[182:185], v128 offset:2048
	ds_read_b128 v[178:181], v128 offset:3072
	s_and_b64 s[40:41], s[2:3], exec
	s_cselect_b32 s45, s1, s44
	s_cselect_b32 s44, s11, s25
	v_lshl_add_u64 v[136:137], v[228:229], 0, s[94:95]
	s_add_i32 m0, s53, 0xc000
	ds_read_b128 v[128:131], v250
	ds_read_b128 v[132:135], v250 offset:1024
	ds_read_b128 v[186:189], v250 offset:2048
	ds_read_b128 v[190:193], v250 offset:3072
	ds_read_b128 v[194:197], v250 offset:4096
	ds_read_b128 v[198:201], v250 offset:5120
	ds_read_b128 v[202:205], v250 offset:6144
	ds_read_b128 v[206:209], v250 offset:7168
	global_load_lds_dwordx4 v[136:137], off
	v_lshl_add_u64 v[136:137], v[226:227], 0, s[94:95]
	s_add_i32 m0, s53, 0xe000
	s_nop 0
	global_load_lds_dwordx4 v[136:137], off
	s_waitcnt vmcnt(8)
	s_waitcnt lgkmcnt(0)
	s_barrier
	s_waitcnt lgkmcnt(0)
	v_mfma_f32_16x16x32_bf16 v[136:139], v[156:159], v[128:131], v[148:151]
	v_mfma_f32_16x16x32_bf16 v[140:143], v[174:177], v[128:131], v[144:147]
	v_mfma_f32_16x16x32_bf16 v[116:119], v[156:159], v[186:189], v[116:119]
	v_mfma_f32_16x16x32_bf16 v[112:115], v[174:177], v[186:189], v[112:115]
	v_mfma_f32_16x16x32_bf16 v[100:103], v[156:159], v[194:197], v[100:103]
	v_mfma_f32_16x16x32_bf16 v[96:99], v[174:177], v[194:197], v[96:99]
	v_mfma_f32_16x16x32_bf16 v[84:87], v[156:159], v[202:205], v[84:87]
	v_mfma_f32_16x16x32_bf16 v[80:83], v[174:177], v[202:205], v[80:83]
	v_mfma_f32_16x16x32_bf16 v[136:139], v[152:155], v[132:135], v[136:139]
	v_mfma_f32_16x16x32_bf16 v[140:143], v[170:173], v[132:135], v[140:143]
	v_mfma_f32_16x16x32_bf16 v[116:119], v[152:155], v[190:193], v[116:119]
	v_mfma_f32_16x16x32_bf16 v[112:115], v[170:173], v[190:193], v[112:115]
	v_mfma_f32_16x16x32_bf16 v[100:103], v[152:155], v[198:201], v[100:103]
	v_mfma_f32_16x16x32_bf16 v[96:99], v[170:173], v[198:201], v[96:99]
	v_mfma_f32_16x16x32_bf16 v[84:87], v[152:155], v[206:209], v[84:87]
	v_mfma_f32_16x16x32_bf16 v[80:83], v[170:173], v[206:209], v[80:83]
	v_mfma_f32_16x16x32_bf16 v[124:127], v[166:169], v[128:131], v[124:127]
	v_mfma_f32_16x16x32_bf16 v[124:127], v[162:165], v[132:135], v[124:127]
	v_mfma_f32_16x16x32_bf16 v[120:123], v[182:185], v[128:131], v[120:123]
	v_mfma_f32_16x16x32_bf16 v[120:123], v[178:181], v[132:135], v[120:123]
	v_mfma_f32_16x16x32_bf16 v[108:111], v[166:169], v[186:189], v[108:111]
	v_mfma_f32_16x16x32_bf16 v[108:111], v[162:165], v[190:193], v[108:111]
	v_mfma_f32_16x16x32_bf16 v[104:107], v[182:185], v[186:189], v[104:107]
	v_mfma_f32_16x16x32_bf16 v[104:107], v[178:181], v[190:193], v[104:107]
	v_mfma_f32_16x16x32_bf16 v[92:95], v[166:169], v[194:197], v[92:95]
	v_mfma_f32_16x16x32_bf16 v[92:95], v[162:165], v[198:201], v[92:95]
	v_mfma_f32_16x16x32_bf16 v[88:91], v[182:185], v[194:197], v[88:91]
	v_mfma_f32_16x16x32_bf16 v[88:91], v[178:181], v[198:201], v[88:91]
	v_mfma_f32_16x16x32_bf16 v[76:79], v[166:169], v[202:205], v[76:79]
	v_mfma_f32_16x16x32_bf16 v[76:79], v[162:165], v[206:209], v[76:79]
	v_mfma_f32_16x16x32_bf16 v[72:75], v[182:185], v[202:205], v[72:75]
	v_mfma_f32_16x16x32_bf16 v[72:75], v[178:181], v[206:209], v[72:75]
	s_barrier
; #define PG8_STAGE(bufoff, gbase, voff) do { _Pragma("unroll") for (int _i = 0; _i < 2; ++_i) \
;         __builtin_amdgcn_global_load_lds((const GAS unsigned*)((const GAS char*)(gbase) + (voff)[_i]), (PG8_LAS unsigned*)(lds + (bufoff) + ldsw + _i * 8192), 16, 0, 0); } while (0)
; #define PG8_LDA(dst, b, h) do { _Pragma("unroll") for (int m = 0; m < 4; ++m) _Pragma("unroll") for (int k = 0; k < 2; ++k) dst[m][k] = *(const PG8_LAS bf16x8*)(lds + PG8_SA(b, h) + aoff + m * 2048 + k * 1024); } while (0)
; #define PG8_MMA(ai, bj, At, Bt) do { __builtin_amdgcn_s_setprio(1); _Pragma("unroll") for (int m = 0; m < 4; ++m) _Pragma("unroll") for (int n = 0; n < 2; ++n) _Pragma("unroll") for (int k = 0; k < 2; ++k) \
;         acc[ai][bj][m][n] = __builtin_amdgcn_mfma_f32_16x16x32_bf16(Bt[n][k], At[m][k], acc[ai][bj][m][n], 0, 0, 0); __builtin_amdgcn_s_setprio(0); } while (0)
; #define PG8_WAIT_V(n) asm volatile("s_waitcnt vmcnt(" #n ")" ::: "memory")
; #define PG8_WAIT_L(n) asm volatile("s_waitcnt lgkmcnt(" #n ")" ::: "memory")
; #define PG8_BAR __builtin_amdgcn_s_barrier()
; #define PG8_SCHED __builtin_amdgcn_sched_barrier(0)
; #define PG8_STAGE(bufoff, gbase, voff) do { _Pragma("unroll") for (int _i = 0; _i < 2; ++_i) \
;         __builtin_amdgcn_global_load_lds((const GAS unsigned*)((const GAS char*)(gbase) + (voff)[_i]), (PG8_LAS unsigned*)(lds + (bufoff) + ldsw + _i * 8192), 16, 0, 0); } while (0)
; #define PG8_LDA(dst, b, h) do { _Pragma("unroll") for (int m = 0; m < 4; ++m) _Pragma("unroll") for (int k = 0; k < 2; ++k) dst[m][k] = *(const PG8_LAS bf16x8*)(lds + PG8_SA(b, h) + aoff + m * 2048 + k * 1024); } while (0)
; #define PG8_LDS_S(dst, boffs) do { dst[0] = *(const PG8_LAS bf16x8*)(slds + (boffs) + soff0); dst[1] = *(const PG8_LAS bf16x8*)(slds + (boffs) + (soff0 ^ 64)); } while (0)
; #define PG8_BAR __builtin_amdgcn_s_barrier()
; template <class Epi, class Sched>
; __device__ __forceinline__ void gemm_phase_strip(PG8_LAS unsigned char* lds, PG8_LAS unsigned char* slds, PG8_LAS unsigned char* pf, const Gemm g, const Sched& S, const Epi& E, int wv) {
;     ...
;             PG8_LDA(At, 0, 1); PG8_LDS_S(As, sq); PG8_STAGE(PG8_SB(0, 0), b2, voffB); PG8_STAGE(PG8_SB(0, 1), b2 + hstepB, voffB); PG8_STAGE(PG8_SA(0, 0), a2, voffA);
;             PG8_WAIT_V(8); PG8_WAIT_L(0); PG8_BAR; PG8_MMA(1, 0, At, B0); PG8_MMA(1, 1, At, B1); PG8_MMA_S(); PG8_BAR; PG8_SCHED;
	s_add_i32 s25, s57, 0
	s_add_i32 s25, s25, 0x21000
	v_add_u32_e32 v160, s25, v248
	v_add_u32_e32 v251, s25, v249
	s_add_i32 s25, s66, s81
	v_lshl_add_u64 v[230:231], s[44:45], 0, v[216:217]
	s_mov_b32 m0, s25
	ds_read_b128 v[128:131], v250 offset:16384
	ds_read_b128 v[132:135], v250 offset:17408
	ds_read_b128 v[186:189], v250 offset:18432
	ds_read_b128 v[190:193], v250 offset:19456
	ds_read_b128 v[194:197], v250 offset:20480
	ds_read_b128 v[198:201], v250 offset:21504
	ds_read_b128 v[202:205], v250 offset:22528
	ds_read_b128 v[206:209], v250 offset:23552
	ds_read_b128 v[148:151], v160
	ds_read_b128 v[144:147], v251
	global_load_lds_dwordx4 v[230:231], off
	s_add_i32 m0, s25, 0x2000
	s_add_u32 s40, s44, 0x80000
	v_lshl_add_u64 v[232:233], s[44:45], 0, v[220:221]
	s_addc_u32 s41, s45, 0
	s_add_i32 s25, s67, s81
	global_load_lds_dwordx4 v[232:233], off
	v_lshl_add_u64 v[234:235], s[40:41], 0, v[216:217]
	s_mov_b32 m0, s25
	v_lshl_add_u64 v[236:237], s[28:29], 0, v[218:219]
	global_load_lds_dwordx4 v[234:235], off
	v_lshl_add_u64 v[234:235], s[40:41], 0, v[220:221]
	s_add_i32 m0, s25, 0x2000
	s_nop 0
	global_load_lds_dwordx4 v[234:235], off
	v_lshl_add_u64 v[234:235], s[28:29], 0, v[214:215]
	s_mov_b32 m0, s53
	s_nop 0
	global_load_lds_dwordx4 v[234:235], off
	s_mov_b32 m0, s97
	s_nop 0
	global_load_lds_dwordx4 v[236:237], off
	s_waitcnt vmcnt(8)
	s_waitcnt lgkmcnt(0)
	s_barrier
	s_waitcnt lgkmcnt(0)
	v_mfma_f32_16x16x32_bf16 v[68:71], v[156:159], v[128:131], v[68:71]
	v_mfma_f32_16x16x32_bf16 v[68:71], v[152:155], v[132:135], v[68:71]
	v_mfma_f32_16x16x32_bf16 v[64:67], v[174:177], v[128:131], v[64:67]
	v_mfma_f32_16x16x32_bf16 v[64:67], v[170:173], v[132:135], v[64:67]
	v_mfma_f32_16x16x32_bf16 v[52:55], v[156:159], v[186:189], v[52:55]
	v_mfma_f32_16x16x32_bf16 v[52:55], v[152:155], v[190:193], v[52:55]
	v_mfma_f32_16x16x32_bf16 v[48:51], v[174:177], v[186:189], v[48:51]
	v_mfma_f32_16x16x32_bf16 v[48:51], v[170:173], v[190:193], v[48:51]
	v_mfma_f32_16x16x32_bf16 v[36:39], v[156:159], v[194:197], v[36:39]
	v_mfma_f32_16x16x32_bf16 v[36:39], v[152:155], v[198:201], v[36:39]
	v_mfma_f32_16x16x32_bf16 v[32:35], v[174:177], v[194:197], v[32:35]
	v_mfma_f32_16x16x32_bf16 v[32:35], v[170:173], v[198:201], v[32:35]
	v_mfma_f32_16x16x32_bf16 v[20:23], v[156:159], v[202:205], v[20:23]
	v_mfma_f32_16x16x32_bf16 v[20:23], v[152:155], v[206:209], v[20:23]
	v_mfma_f32_16x16x32_bf16 v[16:19], v[174:177], v[202:205], v[16:19]
	v_mfma_f32_16x16x32_bf16 v[16:19], v[170:173], v[206:209], v[16:19]
	v_mfma_f32_16x16x32_bf16 v[60:63], v[166:169], v[128:131], v[60:63]
	v_mfma_f32_16x16x32_bf16 v[60:63], v[162:165], v[132:135], v[60:63]
	v_mfma_f32_16x16x32_bf16 v[56:59], v[182:185], v[128:131], v[56:59]
	v_mfma_f32_16x16x32_bf16 v[56:59], v[178:181], v[132:135], v[56:59]
	v_mfma_f32_16x16x32_bf16 v[44:47], v[166:169], v[186:189], v[44:47]
	v_mfma_f32_16x16x32_bf16 v[44:47], v[162:165], v[190:193], v[44:47]
	v_mfma_f32_16x16x32_bf16 v[40:43], v[182:185], v[186:189], v[40:43]
	v_mfma_f32_16x16x32_bf16 v[40:43], v[178:181], v[190:193], v[40:43]
	v_mfma_f32_16x16x32_bf16 v[28:31], v[166:169], v[194:197], v[28:31]
	v_mfma_f32_16x16x32_bf16 v[28:31], v[162:165], v[198:201], v[28:31]
	v_mfma_f32_16x16x32_bf16 v[24:27], v[182:185], v[194:197], v[24:27]
	v_mfma_f32_16x16x32_bf16 v[24:27], v[178:181], v[198:201], v[24:27]
	v_mfma_f32_16x16x32_bf16 v[12:15], v[166:169], v[202:205], v[12:15]
	v_mfma_f32_16x16x32_bf16 v[12:15], v[162:165], v[206:209], v[12:15]
	v_mfma_f32_16x16x32_bf16 v[8:11], v[182:185], v[202:205], v[8:11]
	v_mfma_f32_16x16x32_bf16 v[8:11], v[178:181], v[206:209], v[8:11]
	v_cndmask_b32_e64 v128, 0, 1, s[76:77]
	v_cmp_ne_u32_e64 s[40:41], 1, v128
	s_andn2_b64 vcc, exec, s[76:77]
	s_mov_b64 s[66:67], -1
	s_cbranch_vccnz .LBB0_246
	v_mfma_f32_16x16x32_bf16 v[128:131], v[174:177], v[148:151], v[4:7]
	s_mov_b64 s[66:67], 0
	v_mfma_f32_16x16x32_bf16 v[132:135], v[182:185], v[148:151], v[0:3]
	v_mfma_f32_16x16x32_bf16 v[128:131], v[170:173], v[144:147], v[128:131]
	v_mfma_f32_16x16x32_bf16 v[132:135], v[178:181], v[144:147], v[132:135]

; #define PG8_STAGE(bufoff, gbase, voff) do { _Pragma("unroll") for (int _i = 0; _i < 2; ++_i) \
;         __builtin_amdgcn_global_load_lds((const GAS unsigned*)((const GAS char*)(gbase) + (voff)[_i]), (PG8_LAS unsigned*)(lds + (bufoff) + ldsw + _i * 8192), 16, 0, 0); } while (0)
; #define PG8_LDA(dst, b, h) do { _Pragma("unroll") for (int m = 0; m < 4; ++m) _Pragma("unroll") for (int k = 0; k < 2; ++k) dst[m][k] = *(const PG8_LAS bf16x8*)(lds + PG8_SA(b, h) + aoff + m * 2048 + k * 1024); } while (0)
; #define PG8_LDB(dst, b, h) do { _Pragma("unroll") for (int n = 0; n < 2; ++n) _Pragma("unroll") for (int k = 0; k < 2; ++k) dst[n][k] = *(const PG8_LAS bf16x8*)(lds + PG8_SB(b, h) + boff + n * 2048 + k * 1024); } while (0)
; #define PG8_MMA(ai, bj, At, Bt) do { __builtin_amdgcn_s_setprio(1); _Pragma("unroll") for (int m = 0; m < 4; ++m) _Pragma("unroll") for (int n = 0; n < 2; ++n) _Pragma("unroll") for (int k = 0; k < 2; ++k) \
;         acc[ai][bj][m][n] = __builtin_amdgcn_mfma_f32_16x16x32_bf16(Bt[n][k], At[m][k], acc[ai][bj][m][n], 0, 0, 0); __builtin_amdgcn_s_setprio(0); } while (0)
; #define PG8_WAIT_V(n) asm volatile("s_waitcnt vmcnt(" #n ")" ::: "memory")
; #define PG8_WAIT_L(n) asm volatile("s_waitcnt lgkmcnt(" #n ")" ::: "memory")
; #define PG8_BAR __builtin_amdgcn_s_barrier()
; #define PG8_SCHED __builtin_amdgcn_sched_barrier(0)
; #define PG8_WAIT_V(n) asm volatile("s_waitcnt vmcnt(" #n ")" ::: "memory")
; #define PG8_BAR __builtin_amdgcn_s_barrier()
; template <class Epi, class Sched>
; __device__ __forceinline__ void gemm_phase_strip(PG8_LAS unsigned char* lds, PG8_LAS unsigned char* slds, PG8_LAS unsigned char* pf, const Gemm g, const Sched& S, const Epi& E, int wv) {
;     ...
;             PG8_LDB(B0, 1, 0); PG8_LDB(B1, 1, 1); PG8_SCHED; PG8_LDA(At, 1, 0); PG8_STAGE(PG8_SA(0, 1), a2 + (Sched::SPLIT ? ((last && has_next) ? (nxt.kh > 0 ? -(long)hstepA : (long)hstepA) : hsA) : (long)hstepA), voffA); PG8_STAGE_S(sq ^ 4096u, s2);
;             PG8_WAIT_V(9); PG8_WAIT_L(0); PG8_BAR; PG8_MMA(0, 0, At, B0); PG8_MMA(0, 1, At, B1); PG8_BAR; PG8_SCHED;
;             PG8_LDA(At, 1, 1); PG8_LDS_S(As, sq + 2048u); PG8_STAGE(PG8_SB(1, 0), b3, voffB); PG8_STAGE(PG8_SB(1, 1), b3 + hstepB, voffB); PG8_STAGE(PG8_SA(1, 0), a3, voffA);
;             PG8_WAIT_V(9); PG8_WAIT_L(0); PG8_BAR; PG8_MMA(1, 0, At, B0); PG8_MMA(1, 1, At, B1); PG8_MMA_S(); PG8_BAR; PG8_SCHED;
.LBB0_250:
	s_or_b64 exec, exec, s[28:29]
	s_waitcnt vmcnt(9)
	s_waitcnt lgkmcnt(0)
	s_barrier
	s_waitcnt lgkmcnt(0)
	v_mfma_f32_16x16x32_bf16 v[136:139], v[156:159], v[202:205], v[136:139]
	v_mfma_f32_16x16x32_bf16 v[148:151], v[152:155], v[206:209], v[136:139]
	v_mfma_f32_16x16x32_bf16 v[136:139], v[174:177], v[202:205], v[140:143]
	v_mfma_f32_16x16x32_bf16 v[116:119], v[156:159], v[194:197], v[116:119]
	v_mfma_f32_16x16x32_bf16 v[112:115], v[174:177], v[194:197], v[112:115]
	v_mfma_f32_16x16x32_bf16 v[100:103], v[156:159], v[186:189], v[100:103]
	v_mfma_f32_16x16x32_bf16 v[96:99], v[174:177], v[186:189], v[96:99]
	v_mfma_f32_16x16x32_bf16 v[84:87], v[156:159], v[0:3], v[84:87]
	v_mfma_f32_16x16x32_bf16 v[80:83], v[174:177], v[0:3], v[80:83]
	v_mfma_f32_16x16x32_bf16 v[144:147], v[170:173], v[206:209], v[136:139]
	v_mfma_f32_16x16x32_bf16 v[116:119], v[152:155], v[198:201], v[116:119]
	v_mfma_f32_16x16x32_bf16 v[112:115], v[170:173], v[198:201], v[112:115]
	v_mfma_f32_16x16x32_bf16 v[100:103], v[152:155], v[190:193], v[100:103]
	v_mfma_f32_16x16x32_bf16 v[96:99], v[170:173], v[190:193], v[96:99]
	v_mfma_f32_16x16x32_bf16 v[84:87], v[152:155], v[4:7], v[84:87]
	v_mfma_f32_16x16x32_bf16 v[80:83], v[170:173], v[4:7], v[80:83]
	v_mfma_f32_16x16x32_bf16 v[124:127], v[166:169], v[202:205], v[124:127]
	v_mfma_f32_16x16x32_bf16 v[120:123], v[182:185], v[202:205], v[120:123]
	v_mfma_f32_16x16x32_bf16 v[108:111], v[166:169], v[194:197], v[108:111]
	v_mfma_f32_16x16x32_bf16 v[104:107], v[182:185], v[194:197], v[104:107]
	v_mfma_f32_16x16x32_bf16 v[92:95], v[166:169], v[186:189], v[92:95]
	v_mfma_f32_16x16x32_bf16 v[88:91], v[182:185], v[186:189], v[88:91]
	v_mfma_f32_16x16x32_bf16 v[76:79], v[166:169], v[0:3], v[76:79]
	v_mfma_f32_16x16x32_bf16 v[0:3], v[182:185], v[0:3], v[72:75]
	v_mfma_f32_16x16x32_bf16 v[124:127], v[162:165], v[206:209], v[124:127]
	v_mfma_f32_16x16x32_bf16 v[120:123], v[178:181], v[206:209], v[120:123]
	v_mfma_f32_16x16x32_bf16 v[108:111], v[162:165], v[198:201], v[108:111]
	v_mfma_f32_16x16x32_bf16 v[104:107], v[178:181], v[198:201], v[104:107]
	v_mfma_f32_16x16x32_bf16 v[92:95], v[162:165], v[190:193], v[92:95]
	v_mfma_f32_16x16x32_bf16 v[88:91], v[178:181], v[190:193], v[88:91]
	v_mfma_f32_16x16x32_bf16 v[76:79], v[162:165], v[4:7], v[76:79]
	v_mfma_f32_16x16x32_bf16 v[72:75], v[178:181], v[4:7], v[0:3]
	s_barrier
	s_mov_b32 m0, s93
	v_lshl_add_u64 v[230:231], v[230:231], 0, s[16:17]
	s_add_u32 s2, s44, 0x80080
	ds_read_b128 v[0:3], v250 offset:49152
	ds_read_b128 v[4:7], v250 offset:50176
	ds_read_b128 v[186:189], v250 offset:51200
	ds_read_b128 v[190:193], v250 offset:52224
	ds_read_b128 v[194:197], v250 offset:53248
	ds_read_b128 v[198:201], v250 offset:54272
	ds_read_b128 v[202:205], v250 offset:55296
	ds_read_b128 v[206:209], v250 offset:56320
	ds_read_b128 v[140:143], v160 offset:2048
	ds_read_b128 v[136:139], v251 offset:2048
	global_load_lds_dwordx4 v[230:231], off
	v_lshl_add_u64 v[230:231], v[232:233], 0, s[16:17]
	s_mov_b32 m0, s89
	s_addc_u32 s3, s45, 0
	global_load_lds_dwordx4 v[230:231], off
	v_lshl_add_u64 v[230:231], s[2:3], 0, v[216:217]
	s_mov_b32 m0, s88
	s_nop 0
	global_load_lds_dwordx4 v[230:231], off
	v_lshl_add_u64 v[230:231], s[2:3], 0, v[220:221]
	s_mov_b32 m0, s27
	s_nop 0
	global_load_lds_dwordx4 v[230:231], off
	v_lshl_add_u64 v[230:231], v[234:235], 0, s[16:17]
	s_mov_b32 m0, s78
	s_nop 0
	global_load_lds_dwordx4 v[230:231], off
	v_lshl_add_u64 v[230:231], v[236:237], 0, s[16:17]
	s_mov_b32 m0, s79
	s_nop 0
	global_load_lds_dwordx4 v[230:231], off
	s_waitcnt vmcnt(9)
	s_waitcnt lgkmcnt(0)
	s_barrier
	s_waitcnt lgkmcnt(0)
	v_mfma_f32_16x16x32_bf16 v[68:71], v[156:159], v[0:3], v[68:71]
	v_mfma_f32_16x16x32_bf16 v[68:71], v[152:155], v[4:7], v[68:71]
	v_mfma_f32_16x16x32_bf16 v[64:67], v[174:177], v[0:3], v[64:67]
	v_mfma_f32_16x16x32_bf16 v[64:67], v[170:173], v[4:7], v[64:67]
	v_mfma_f32_16x16x32_bf16 v[52:55], v[156:159], v[186:189], v[52:55]
	v_mfma_f32_16x16x32_bf16 v[52:55], v[152:155], v[190:193], v[52:55]
	v_mfma_f32_16x16x32_bf16 v[48:51], v[174:177], v[186:189], v[48:51]
	v_mfma_f32_16x16x32_bf16 v[48:51], v[170:173], v[190:193], v[48:51]
	v_mfma_f32_16x16x32_bf16 v[36:39], v[156:159], v[194:197], v[36:39]
	v_mfma_f32_16x16x32_bf16 v[36:39], v[152:155], v[198:201], v[36:39]
	v_mfma_f32_16x16x32_bf16 v[32:35], v[174:177], v[194:197], v[32:35]
	v_mfma_f32_16x16x32_bf16 v[32:35], v[170:173], v[198:201], v[32:35]
	v_mfma_f32_16x16x32_bf16 v[20:23], v[156:159], v[202:205], v[20:23]
	v_mfma_f32_16x16x32_bf16 v[20:23], v[152:155], v[206:209], v[20:23]
	v_mfma_f32_16x16x32_bf16 v[16:19], v[174:177], v[202:205], v[16:19]
	v_mfma_f32_16x16x32_bf16 v[16:19], v[170:173], v[206:209], v[16:19]
	v_mfma_f32_16x16x32_bf16 v[60:63], v[166:169], v[0:3], v[60:63]
	v_mfma_f32_16x16x32_bf16 v[0:3], v[182:185], v[0:3], v[56:59]
	v_mfma_f32_16x16x32_bf16 v[56:59], v[178:181], v[4:7], v[0:3]
	v_mfma_f32_16x16x32_bf16 v[0:3], v[166:169], v[186:189], v[44:47]
	v_mfma_f32_16x16x32_bf16 v[44:47], v[162:165], v[190:193], v[0:3]
	v_mfma_f32_16x16x32_bf16 v[0:3], v[182:185], v[186:189], v[40:43]
	v_mfma_f32_16x16x32_bf16 v[40:43], v[178:181], v[190:193], v[0:3]
	v_mfma_f32_16x16x32_bf16 v[0:3], v[166:169], v[194:197], v[28:31]
	v_mfma_f32_16x16x32_bf16 v[28:31], v[162:165], v[198:201], v[0:3]
	v_mfma_f32_16x16x32_bf16 v[0:3], v[182:185], v[194:197], v[24:27]
	v_mfma_f32_16x16x32_bf16 v[24:27], v[178:181], v[198:201], v[0:3]
	v_mfma_f32_16x16x32_bf16 v[0:3], v[166:169], v[202:205], v[12:15]
	v_mfma_f32_16x16x32_bf16 v[12:15], v[162:165], v[206:209], v[0:3]
	v_mfma_f32_16x16x32_bf16 v[0:3], v[182:185], v[202:205], v[8:11]
	v_mfma_f32_16x16x32_bf16 v[60:63], v[162:165], v[4:7], v[60:63]
	v_mfma_f32_16x16x32_bf16 v[8:11], v[178:181], v[206:209], v[0:3]
	s_and_b64 vcc, exec, s[40:41]
	s_mov_b64 s[2:3], -1
	s_cbranch_vccnz .LBB0_252
	v_mfma_f32_16x16x32_bf16 v[0:3], v[174:177], v[140:143], v[128:131]
	s_mov_b64 s[2:3], 0
	v_mfma_f32_16x16x32_bf16 v[174:177], v[182:185], v[140:143], v[132:135]
	v_mfma_f32_16x16x32_bf16 v[4:7], v[170:173], v[136:139], v[0:3]
	v_mfma_f32_16x16x32_bf16 v[0:3], v[178:181], v[136:139], v[174:177]

; #define PG8_STAGE(bufoff, gbase, voff) do { _Pragma("unroll") for (int _i = 0; _i < 2; ++_i) \
;         __builtin_amdgcn_global_load_lds((const GAS unsigned*)((const GAS char*)(gbase) + (voff)[_i]), (PG8_LAS unsigned*)(lds + (bufoff) + ldsw + _i * 8192), 16, 0, 0); } while (0)
; #define PG8_LDA(dst, b, h) do { _Pragma("unroll") for (int m = 0; m < 4; ++m) _Pragma("unroll") for (int k = 0; k < 2; ++k) dst[m][k] = *(const PG8_LAS bf16x8*)(lds + PG8_SA(b, h) + aoff + m * 2048 + k * 1024); } while (0)
; #define PG8_LDB(dst, b, h) do { _Pragma("unroll") for (int n = 0; n < 2; ++n) _Pragma("unroll") for (int k = 0; k < 2; ++k) dst[n][k] = *(const PG8_LAS bf16x8*)(lds + PG8_SB(b, h) + boff + n * 2048 + k * 1024); } while (0)
; #define PG8_MMA(ai, bj, At, Bt) do { __builtin_amdgcn_s_setprio(1); _Pragma("unroll") for (int m = 0; m < 4; ++m) _Pragma("unroll") for (int n = 0; n < 2; ++n) _Pragma("unroll") for (int k = 0; k < 2; ++k) \
;         acc[ai][bj][m][n] = __builtin_amdgcn_mfma_f32_16x16x32_bf16(Bt[n][k], At[m][k], acc[ai][bj][m][n], 0, 0, 0); __builtin_amdgcn_s_setprio(0); } while (0)
; #define PG8_WAIT_V(n) asm volatile("s_waitcnt vmcnt(" #n ")" ::: "memory")
; #define PG8_WAIT_L(n) asm volatile("s_waitcnt lgkmcnt(" #n ")" ::: "memory")
; #define PG8_BAR __builtin_amdgcn_s_barrier()
; #define PG8_SCHED __builtin_amdgcn_sched_barrier(0)
; #define PG8_STAGE(bufoff, gbase, voff) do { _Pragma("unroll") for (int _i = 0; _i < 2; ++_i) \
;         __builtin_amdgcn_global_load_lds((const GAS unsigned*)((const GAS char*)(gbase) + (voff)[_i]), (PG8_LAS unsigned*)(lds + (bufoff) + ldsw + _i * 8192), 16, 0, 0); } while (0)
; #define PG8_LDA(dst, b, h) do { _Pragma("unroll") for (int m = 0; m < 4; ++m) _Pragma("unroll") for (int k = 0; k < 2; ++k) dst[m][k] = *(const PG8_LAS bf16x8*)(lds + PG8_SA(b, h) + aoff + m * 2048 + k * 1024); } while (0)
; #define PG8_BAR __builtin_amdgcn_s_barrier()
; template <class Epi, class Sched>
; __device__ __forceinline__ void gemm_phase_strip(PG8_LAS unsigned char* lds, PG8_LAS unsigned char* slds, PG8_LAS unsigned char* pf, const Gemm g, const Sched& S, const Epi& E, int wv) {
;     ...
;             PG8_LDB(B0, 0, 0); PG8_LDB(B1, 0, 1); PG8_SCHED; PG8_LDA(At, 0, 0); PG8_STAGE(PG8_SA(1, 1), a1 + PG8_HS, voffA);
;             PG8_WAIT_V(8); PG8_WAIT_L(0); PG8_BAR; PG8_MMA(0, 0, At, B0); PG8_MMA(0, 1, At, B1); PG8_BAR; PG8_SCHED;
.LBB0_539:
	s_add_u32 s2, s66, s68
	s_addc_u32 s3, s67, s69
	s_add_u32 s23, s2, 0x100
	s_addc_u32 s28, s3, 0
	s_add_u32 s40, s57, s68
	s_addc_u32 s41, s65, s69
	s_add_i32 s74, 0, 0x10000
	s_add_i32 s75, 0, 0x14000
	v_add_u32_e32 v136, s74, v234
	ds_read_b128 v[148:151], v136
	ds_read_b128 v[144:147], v136 offset:1024
	ds_read_b128 v[166:169], v136 offset:2048
	ds_read_b128 v[162:165], v136 offset:3072
	v_add_u32_e32 v136, s75, v234
	ds_read_b128 v[156:159], v136
	ds_read_b128 v[152:155], v136 offset:1024
	ds_read_b128 v[174:177], v136 offset:2048
	ds_read_b128 v[170:173], v136 offset:3072
	s_cmpk_eq_i32 s68, 0xf00
	s_cselect_b64 s[2:3], -1, 0
	s_and_b64 s[24:25], s[2:3], exec
	s_cselect_b32 s29, s59, s28
	s_cselect_b32 s28, s58, s23
	s_cselect_b32 s73, s21, s41
	s_cselect_b32 s72, s51, s40
	v_lshl_add_u64 v[222:223], v[220:221], 0, s[68:69]
	s_add_i32 m0, s1, 0xc000
	ds_read_b128 v[136:139], v237
	ds_read_b128 v[140:143], v237 offset:1024
	ds_read_b128 v[178:181], v237 offset:2048
	ds_read_b128 v[182:185], v237 offset:3072
	ds_read_b128 v[186:189], v237 offset:4096
	ds_read_b128 v[190:193], v237 offset:5120
	ds_read_b128 v[194:197], v237 offset:6144
	ds_read_b128 v[198:201], v237 offset:7168
	global_load_lds_dwordx4 v[222:223], off
	v_lshl_add_u64 v[222:223], v[218:219], 0, s[68:69]
	s_add_i32 m0, s1, 0xe000
	s_nop 0
	global_load_lds_dwordx4 v[222:223], off
	s_waitcnt vmcnt(8)
	s_waitcnt lgkmcnt(0)
	s_barrier
	s_waitcnt lgkmcnt(0)
	v_mfma_f32_16x16x32_bf16 v[132:135], v[148:151], v[136:139], v[132:135]
	v_mfma_f32_16x16x32_bf16 v[132:135], v[144:147], v[140:143], v[132:135]
	v_mfma_f32_16x16x32_bf16 v[128:131], v[166:169], v[136:139], v[128:131]
	v_mfma_f32_16x16x32_bf16 v[128:131], v[162:165], v[140:143], v[128:131]
	v_mfma_f32_16x16x32_bf16 v[116:119], v[148:151], v[178:181], v[116:119]
	v_mfma_f32_16x16x32_bf16 v[116:119], v[144:147], v[182:185], v[116:119]
	v_mfma_f32_16x16x32_bf16 v[112:115], v[166:169], v[178:181], v[112:115]
	v_mfma_f32_16x16x32_bf16 v[112:115], v[162:165], v[182:185], v[112:115]
	v_mfma_f32_16x16x32_bf16 v[100:103], v[148:151], v[186:189], v[100:103]
	v_mfma_f32_16x16x32_bf16 v[100:103], v[144:147], v[190:193], v[100:103]
	v_mfma_f32_16x16x32_bf16 v[96:99], v[166:169], v[186:189], v[96:99]
	v_mfma_f32_16x16x32_bf16 v[96:99], v[162:165], v[190:193], v[96:99]
	v_mfma_f32_16x16x32_bf16 v[84:87], v[148:151], v[194:197], v[84:87]
	v_mfma_f32_16x16x32_bf16 v[84:87], v[144:147], v[198:201], v[84:87]
	v_mfma_f32_16x16x32_bf16 v[80:83], v[166:169], v[194:197], v[80:83]
	v_mfma_f32_16x16x32_bf16 v[80:83], v[162:165], v[198:201], v[80:83]
	v_mfma_f32_16x16x32_bf16 v[124:127], v[156:159], v[136:139], v[124:127]
	v_mfma_f32_16x16x32_bf16 v[124:127], v[152:155], v[140:143], v[124:127]
	v_mfma_f32_16x16x32_bf16 v[120:123], v[174:177], v[136:139], v[120:123]
	v_mfma_f32_16x16x32_bf16 v[120:123], v[170:173], v[140:143], v[120:123]
	v_mfma_f32_16x16x32_bf16 v[108:111], v[156:159], v[178:181], v[108:111]
	v_mfma_f32_16x16x32_bf16 v[108:111], v[152:155], v[182:185], v[108:111]
	v_mfma_f32_16x16x32_bf16 v[104:107], v[174:177], v[178:181], v[104:107]
	v_mfma_f32_16x16x32_bf16 v[104:107], v[170:173], v[182:185], v[104:107]
	v_mfma_f32_16x16x32_bf16 v[92:95], v[156:159], v[186:189], v[92:95]
	v_mfma_f32_16x16x32_bf16 v[92:95], v[152:155], v[190:193], v[92:95]
	v_mfma_f32_16x16x32_bf16 v[88:91], v[174:177], v[186:189], v[88:91]
	v_mfma_f32_16x16x32_bf16 v[88:91], v[170:173], v[190:193], v[88:91]
	v_mfma_f32_16x16x32_bf16 v[76:79], v[156:159], v[194:197], v[76:79]
	v_mfma_f32_16x16x32_bf16 v[76:79], v[152:155], v[198:201], v[76:79]
	v_mfma_f32_16x16x32_bf16 v[72:75], v[174:177], v[194:197], v[72:75]
	v_mfma_f32_16x16x32_bf16 v[72:75], v[170:173], v[198:201], v[72:75]
	s_barrier
; #define PG8_STAGE(bufoff, gbase, voff) do { _Pragma("unroll") for (int _i = 0; _i < 2; ++_i) \
;         __builtin_amdgcn_global_load_lds((const GAS unsigned*)((const GAS char*)(gbase) + (voff)[_i]), (PG8_LAS unsigned*)(lds + (bufoff) + ldsw + _i * 8192), 16, 0, 0); } while (0)
; #define PG8_LDA(dst, b, h) do { _Pragma("unroll") for (int m = 0; m < 4; ++m) _Pragma("unroll") for (int k = 0; k < 2; ++k) dst[m][k] = *(const PG8_LAS bf16x8*)(lds + PG8_SA(b, h) + aoff + m * 2048 + k * 1024); } while (0)
; #define PG8_MMA(ai, bj, At, Bt) do { __builtin_amdgcn_s_setprio(1); _Pragma("unroll") for (int m = 0; m < 4; ++m) _Pragma("unroll") for (int n = 0; n < 2; ++n) _Pragma("unroll") for (int k = 0; k < 2; ++k) \
;         acc[ai][bj][m][n] = __builtin_amdgcn_mfma_f32_16x16x32_bf16(Bt[n][k], At[m][k], acc[ai][bj][m][n], 0, 0, 0); __builtin_amdgcn_s_setprio(0); } while (0)
; #define PG8_WAIT_V(n) asm volatile("s_waitcnt vmcnt(" #n ")" ::: "memory")
; #define PG8_WAIT_L(n) asm volatile("s_waitcnt lgkmcnt(" #n ")" ::: "memory")
; #define PG8_BAR __builtin_amdgcn_s_barrier()
; #define PG8_SCHED __builtin_amdgcn_sched_barrier(0)
; #define PG8_STAGE(bufoff, gbase, voff) do { _Pragma("unroll") for (int _i = 0; _i < 2; ++_i) \
;         __builtin_amdgcn_global_load_lds((const GAS unsigned*)((const GAS char*)(gbase) + (voff)[_i]), (PG8_LAS unsigned*)(lds + (bufoff) + ldsw + _i * 8192), 16, 0, 0); } while (0)
; #define PG8_LDA(dst, b, h) do { _Pragma("unroll") for (int m = 0; m < 4; ++m) _Pragma("unroll") for (int k = 0; k < 2; ++k) dst[m][k] = *(const PG8_LAS bf16x8*)(lds + PG8_SA(b, h) + aoff + m * 2048 + k * 1024); } while (0)
; #define PG8_LDS_S(dst, boffs) do { dst[0] = *(const PG8_LAS bf16x8*)(slds + (boffs) + soff0); dst[1] = *(const PG8_LAS bf16x8*)(slds + (boffs) + (soff0 ^ 64)); } while (0)
; #define PG8_BAR __builtin_amdgcn_s_barrier()
; template <class Epi, class Sched>
; __device__ __forceinline__ void gemm_phase_strip(PG8_LAS unsigned char* lds, PG8_LAS unsigned char* slds, PG8_LAS unsigned char* pf, const Gemm g, const Sched& S, const Epi& E, int wv) {
;     ...
;             PG8_LDA(At, 0, 1); PG8_LDS_S(As, sq); PG8_STAGE(PG8_SB(0, 0), b2, voffB); PG8_STAGE(PG8_SB(0, 1), b2 + hstepB, voffB); PG8_STAGE(PG8_SA(0, 0), a2, voffA);
;             PG8_WAIT_V(8); PG8_WAIT_L(0); PG8_BAR; PG8_MMA(1, 0, At, B0); PG8_MMA(1, 1, At, B1); PG8_MMA_S(); PG8_BAR; PG8_SCHED;
	s_add_i32 s23, s34, 0
	s_add_i32 s23, s23, 0x21000
	v_add_u32_e32 v160, s23, v235
	v_add_u32_e32 v242, s23, v236
	s_add_i32 s23, s74, s79
	v_lshl_add_u64 v[222:223], s[72:73], 0, v[204:205]
	s_mov_b32 m0, s23
	ds_read_b128 v[136:139], v237 offset:16384
	ds_read_b128 v[140:143], v237 offset:17408
	ds_read_b128 v[186:189], v237 offset:18432
	ds_read_b128 v[190:193], v237 offset:19456
	ds_read_b128 v[194:197], v237 offset:20480
	ds_read_b128 v[198:201], v237 offset:21504
	ds_read_b128 v[244:247], v237 offset:22528
	ds_read_b128 v[248:251], v237 offset:23552
	ds_read_b128 v[182:185], v160
	ds_read_b128 v[178:181], v242
	global_load_lds_dwordx4 v[222:223], off
	s_add_i32 m0, s23, 0x2000
	s_add_u32 s24, s72, 0x80000
	v_lshl_add_u64 v[224:225], s[72:73], 0, v[208:209]
	s_addc_u32 s25, s73, 0
	s_add_i32 s23, s75, s79
	global_load_lds_dwordx4 v[224:225], off
	v_lshl_add_u64 v[226:227], s[24:25], 0, v[204:205]
	s_mov_b32 m0, s23
	v_lshl_add_u64 v[228:229], s[28:29], 0, v[206:207]
	global_load_lds_dwordx4 v[226:227], off
	v_lshl_add_u64 v[226:227], s[24:25], 0, v[208:209]
	s_add_i32 m0, s23, 0x2000
	s_nop 0
	global_load_lds_dwordx4 v[226:227], off
	v_lshl_add_u64 v[226:227], s[28:29], 0, v[202:203]
	s_mov_b32 m0, s1
	s_nop 0
	global_load_lds_dwordx4 v[226:227], off
	s_mov_b32 m0, s80
	s_nop 0
	global_load_lds_dwordx4 v[228:229], off
	s_waitcnt vmcnt(8)
	s_waitcnt lgkmcnt(0)
	s_barrier
	s_waitcnt lgkmcnt(0)
	v_mfma_f32_16x16x32_bf16 v[68:71], v[148:151], v[136:139], v[68:71]
	v_mfma_f32_16x16x32_bf16 v[68:71], v[144:147], v[140:143], v[68:71]
	v_mfma_f32_16x16x32_bf16 v[64:67], v[166:169], v[136:139], v[64:67]
	v_mfma_f32_16x16x32_bf16 v[64:67], v[162:165], v[140:143], v[64:67]
	v_mfma_f32_16x16x32_bf16 v[52:55], v[148:151], v[186:189], v[52:55]
	v_mfma_f32_16x16x32_bf16 v[52:55], v[144:147], v[190:193], v[52:55]
	v_mfma_f32_16x16x32_bf16 v[48:51], v[166:169], v[186:189], v[48:51]
	v_mfma_f32_16x16x32_bf16 v[48:51], v[162:165], v[190:193], v[48:51]
	v_mfma_f32_16x16x32_bf16 v[36:39], v[148:151], v[194:197], v[36:39]
	v_mfma_f32_16x16x32_bf16 v[36:39], v[144:147], v[198:201], v[36:39]
	v_mfma_f32_16x16x32_bf16 v[32:35], v[166:169], v[194:197], v[32:35]
	v_mfma_f32_16x16x32_bf16 v[32:35], v[162:165], v[198:201], v[32:35]
	v_mfma_f32_16x16x32_bf16 v[20:23], v[148:151], v[244:247], v[20:23]
	v_mfma_f32_16x16x32_bf16 v[20:23], v[144:147], v[248:251], v[20:23]
	v_mfma_f32_16x16x32_bf16 v[16:19], v[166:169], v[244:247], v[16:19]
	v_mfma_f32_16x16x32_bf16 v[16:19], v[162:165], v[248:251], v[16:19]
	v_mfma_f32_16x16x32_bf16 v[60:63], v[156:159], v[136:139], v[60:63]
	v_mfma_f32_16x16x32_bf16 v[60:63], v[152:155], v[140:143], v[60:63]
	v_mfma_f32_16x16x32_bf16 v[56:59], v[174:177], v[136:139], v[56:59]
	v_mfma_f32_16x16x32_bf16 v[56:59], v[170:173], v[140:143], v[56:59]
	v_mfma_f32_16x16x32_bf16 v[44:47], v[156:159], v[186:189], v[44:47]
	v_mfma_f32_16x16x32_bf16 v[44:47], v[152:155], v[190:193], v[44:47]
	v_mfma_f32_16x16x32_bf16 v[40:43], v[174:177], v[186:189], v[40:43]
	v_mfma_f32_16x16x32_bf16 v[40:43], v[170:173], v[190:193], v[40:43]
	v_mfma_f32_16x16x32_bf16 v[28:31], v[156:159], v[194:197], v[28:31]
	v_mfma_f32_16x16x32_bf16 v[28:31], v[152:155], v[198:201], v[28:31]
	v_mfma_f32_16x16x32_bf16 v[24:27], v[174:177], v[194:197], v[24:27]
	v_mfma_f32_16x16x32_bf16 v[24:27], v[170:173], v[198:201], v[24:27]
	v_mfma_f32_16x16x32_bf16 v[12:15], v[156:159], v[244:247], v[12:15]
	v_mfma_f32_16x16x32_bf16 v[12:15], v[152:155], v[248:251], v[12:15]
	v_mfma_f32_16x16x32_bf16 v[8:11], v[174:177], v[244:247], v[8:11]
	v_mfma_f32_16x16x32_bf16 v[8:11], v[170:173], v[248:251], v[8:11]
	v_cndmask_b32_e64 v136, 0, 1, s[42:43]
	v_cmp_ne_u32_e64 s[40:41], 1, v136
	s_andn2_b64 vcc, exec, s[42:43]
	s_mov_b64 s[74:75], -1
	s_cbranch_vccnz .LBB0_541
	v_mfma_f32_16x16x32_bf16 v[136:139], v[166:169], v[182:185], v[4:7]
	s_mov_b64 s[74:75], 0
	v_mfma_f32_16x16x32_bf16 v[140:143], v[174:177], v[182:185], v[0:3]
	v_mfma_f32_16x16x32_bf16 v[136:139], v[162:165], v[178:181], v[136:139]
	v_mfma_f32_16x16x32_bf16 v[140:143], v[170:173], v[178:181], v[140:143]

; #define PG8_STAGE(bufoff, gbase, voff) do { _Pragma("unroll") for (int _i = 0; _i < 2; ++_i) \
;         __builtin_amdgcn_global_load_lds((const GAS unsigned*)((const GAS char*)(gbase) + (voff)[_i]), (PG8_LAS unsigned*)(lds + (bufoff) + ldsw + _i * 8192), 16, 0, 0); } while (0)
; #define PG8_LDA(dst, b, h) do { _Pragma("unroll") for (int m = 0; m < 4; ++m) _Pragma("unroll") for (int k = 0; k < 2; ++k) dst[m][k] = *(const PG8_LAS bf16x8*)(lds + PG8_SA(b, h) + aoff + m * 2048 + k * 1024); } while (0)
; #define PG8_LDB(dst, b, h) do { _Pragma("unroll") for (int n = 0; n < 2; ++n) _Pragma("unroll") for (int k = 0; k < 2; ++k) dst[n][k] = *(const PG8_LAS bf16x8*)(lds + PG8_SB(b, h) + boff + n * 2048 + k * 1024); } while (0)
; #define PG8_MMA(ai, bj, At, Bt) do { __builtin_amdgcn_s_setprio(1); _Pragma("unroll") for (int m = 0; m < 4; ++m) _Pragma("unroll") for (int n = 0; n < 2; ++n) _Pragma("unroll") for (int k = 0; k < 2; ++k) \
;         acc[ai][bj][m][n] = __builtin_amdgcn_mfma_f32_16x16x32_bf16(Bt[n][k], At[m][k], acc[ai][bj][m][n], 0, 0, 0); __builtin_amdgcn_s_setprio(0); } while (0)
; #define PG8_WAIT_V(n) asm volatile("s_waitcnt vmcnt(" #n ")" ::: "memory")
; #define PG8_WAIT_L(n) asm volatile("s_waitcnt lgkmcnt(" #n ")" ::: "memory")
; #define PG8_BAR __builtin_amdgcn_s_barrier()
; #define PG8_SCHED __builtin_amdgcn_sched_barrier(0)
; #define PG8_WAIT_V(n) asm volatile("s_waitcnt vmcnt(" #n ")" ::: "memory")
; #define PG8_BAR __builtin_amdgcn_s_barrier()
; template <class Epi, class Sched>
; __device__ __forceinline__ void gemm_phase_strip(PG8_LAS unsigned char* lds, PG8_LAS unsigned char* slds, PG8_LAS unsigned char* pf, const Gemm g, const Sched& S, const Epi& E, int wv) {
;     ...
;             PG8_LDB(B0, 1, 0); PG8_LDB(B1, 1, 1); PG8_SCHED; PG8_LDA(At, 1, 0); PG8_STAGE(PG8_SA(0, 1), a2 + (Sched::SPLIT ? ((last && has_next) ? (nxt.kh > 0 ? -(long)hstepA : (long)hstepA) : hsA) : (long)hstepA), voffA); PG8_STAGE_S(sq ^ 4096u, s2);
;             PG8_WAIT_V(9); PG8_WAIT_L(0); PG8_BAR; PG8_MMA(0, 0, At, B0); PG8_MMA(0, 1, At, B1); PG8_BAR; PG8_SCHED;
;             PG8_LDA(At, 1, 1); PG8_LDS_S(As, sq + 2048u); PG8_STAGE(PG8_SB(1, 0), b3, voffB); PG8_STAGE(PG8_SB(1, 1), b3 + hstepB, voffB); PG8_STAGE(PG8_SA(1, 0), a3, voffA);
;             PG8_WAIT_V(9); PG8_WAIT_L(0); PG8_BAR; PG8_MMA(1, 0, At, B0); PG8_MMA(1, 1, At, B1); PG8_MMA_S(); PG8_BAR; PG8_SCHED;
.LBB0_545:
	s_or_b64 exec, exec, s[28:29]
	s_waitcnt vmcnt(9)
	s_waitcnt lgkmcnt(0)
	s_barrier
	s_waitcnt lgkmcnt(0)
	v_mfma_f32_16x16x32_bf16 v[132:135], v[148:151], v[194:197], v[132:135]
	v_mfma_f32_16x16x32_bf16 v[132:135], v[144:147], v[198:201], v[132:135]
	v_mfma_f32_16x16x32_bf16 v[128:131], v[166:169], v[194:197], v[128:131]
	v_mfma_f32_16x16x32_bf16 v[128:131], v[162:165], v[198:201], v[128:131]
	v_mfma_f32_16x16x32_bf16 v[116:119], v[148:151], v[186:189], v[116:119]
	v_mfma_f32_16x16x32_bf16 v[116:119], v[144:147], v[190:193], v[116:119]
	v_mfma_f32_16x16x32_bf16 v[112:115], v[166:169], v[186:189], v[112:115]
	v_mfma_f32_16x16x32_bf16 v[112:115], v[162:165], v[190:193], v[112:115]
	v_mfma_f32_16x16x32_bf16 v[100:103], v[148:151], v[178:181], v[100:103]
	v_mfma_f32_16x16x32_bf16 v[100:103], v[144:147], v[182:185], v[100:103]
	v_mfma_f32_16x16x32_bf16 v[96:99], v[166:169], v[178:181], v[96:99]
	v_mfma_f32_16x16x32_bf16 v[96:99], v[162:165], v[182:185], v[96:99]
	v_mfma_f32_16x16x32_bf16 v[84:87], v[148:151], v[0:3], v[84:87]
	v_mfma_f32_16x16x32_bf16 v[84:87], v[144:147], v[4:7], v[84:87]
	v_mfma_f32_16x16x32_bf16 v[80:83], v[166:169], v[0:3], v[80:83]
	v_mfma_f32_16x16x32_bf16 v[80:83], v[162:165], v[4:7], v[80:83]
	v_mfma_f32_16x16x32_bf16 v[124:127], v[156:159], v[194:197], v[124:127]
	v_mfma_f32_16x16x32_bf16 v[120:123], v[174:177], v[194:197], v[120:123]
	v_mfma_f32_16x16x32_bf16 v[108:111], v[156:159], v[186:189], v[108:111]
	v_mfma_f32_16x16x32_bf16 v[104:107], v[174:177], v[186:189], v[104:107]
	v_mfma_f32_16x16x32_bf16 v[92:95], v[156:159], v[178:181], v[92:95]
	v_mfma_f32_16x16x32_bf16 v[88:91], v[174:177], v[178:181], v[88:91]
	v_mfma_f32_16x16x32_bf16 v[76:79], v[156:159], v[0:3], v[76:79]
	v_mfma_f32_16x16x32_bf16 v[0:3], v[174:177], v[0:3], v[72:75]
	v_mfma_f32_16x16x32_bf16 v[124:127], v[152:155], v[198:201], v[124:127]
	v_mfma_f32_16x16x32_bf16 v[120:123], v[170:173], v[198:201], v[120:123]
	v_mfma_f32_16x16x32_bf16 v[108:111], v[152:155], v[190:193], v[108:111]
	v_mfma_f32_16x16x32_bf16 v[104:107], v[170:173], v[190:193], v[104:107]
	v_mfma_f32_16x16x32_bf16 v[92:95], v[152:155], v[182:185], v[92:95]
	v_mfma_f32_16x16x32_bf16 v[88:91], v[170:173], v[182:185], v[88:91]
	v_mfma_f32_16x16x32_bf16 v[76:79], v[152:155], v[4:7], v[76:79]
	v_mfma_f32_16x16x32_bf16 v[72:75], v[170:173], v[4:7], v[0:3]
	s_barrier
	s_mov_b32 m0, s85
	v_lshl_add_u64 v[222:223], v[222:223], 0, s[16:17]
	s_add_u32 s2, s72, 0x80080
	ds_read_b128 v[0:3], v237 offset:49152
	ds_read_b128 v[4:7], v237 offset:50176
	ds_read_b128 v[186:189], v237 offset:51200
	ds_read_b128 v[190:193], v237 offset:52224
	ds_read_b128 v[194:197], v237 offset:53248
	ds_read_b128 v[198:201], v237 offset:54272
	ds_read_b128 v[244:247], v237 offset:55296
	ds_read_b128 v[248:251], v237 offset:56320
	ds_read_b128 v[182:185], v160 offset:2048
	ds_read_b128 v[178:181], v242 offset:2048
	global_load_lds_dwordx4 v[222:223], off
	v_lshl_add_u64 v[222:223], v[224:225], 0, s[16:17]
	s_mov_b32 m0, s86
	s_addc_u32 s3, s73, 0
	global_load_lds_dwordx4 v[222:223], off
	v_lshl_add_u64 v[222:223], s[2:3], 0, v[204:205]
	s_mov_b32 m0, s89
	s_nop 0
	global_load_lds_dwordx4 v[222:223], off
	v_lshl_add_u64 v[222:223], s[2:3], 0, v[208:209]
	s_mov_b32 m0, s90
	s_nop 0
	global_load_lds_dwordx4 v[222:223], off
	v_lshl_add_u64 v[222:223], v[226:227], 0, s[16:17]
	s_mov_b32 m0, s87
	s_nop 0
	global_load_lds_dwordx4 v[222:223], off
	v_lshl_add_u64 v[222:223], v[228:229], 0, s[16:17]
	s_mov_b32 m0, s88
	s_nop 0
	global_load_lds_dwordx4 v[222:223], off
	s_waitcnt vmcnt(9)
	s_waitcnt lgkmcnt(0)
	s_barrier
	s_waitcnt lgkmcnt(0)
	v_mfma_f32_16x16x32_bf16 v[68:71], v[148:151], v[0:3], v[68:71]
	v_mfma_f32_16x16x32_bf16 v[68:71], v[144:147], v[4:7], v[68:71]
	v_mfma_f32_16x16x32_bf16 v[64:67], v[166:169], v[0:3], v[64:67]
	v_mfma_f32_16x16x32_bf16 v[64:67], v[162:165], v[4:7], v[64:67]
	v_mfma_f32_16x16x32_bf16 v[52:55], v[148:151], v[186:189], v[52:55]
	v_mfma_f32_16x16x32_bf16 v[52:55], v[144:147], v[190:193], v[52:55]
	v_mfma_f32_16x16x32_bf16 v[48:51], v[166:169], v[186:189], v[48:51]
	v_mfma_f32_16x16x32_bf16 v[48:51], v[162:165], v[190:193], v[48:51]
	v_mfma_f32_16x16x32_bf16 v[36:39], v[148:151], v[194:197], v[36:39]
	v_mfma_f32_16x16x32_bf16 v[36:39], v[144:147], v[198:201], v[36:39]
	v_mfma_f32_16x16x32_bf16 v[32:35], v[166:169], v[194:197], v[32:35]
	v_mfma_f32_16x16x32_bf16 v[32:35], v[162:165], v[198:201], v[32:35]
	v_mfma_f32_16x16x32_bf16 v[20:23], v[148:151], v[244:247], v[20:23]
	v_mfma_f32_16x16x32_bf16 v[20:23], v[144:147], v[248:251], v[20:23]
	v_mfma_f32_16x16x32_bf16 v[16:19], v[166:169], v[244:247], v[16:19]
	v_mfma_f32_16x16x32_bf16 v[16:19], v[162:165], v[248:251], v[16:19]
	v_mfma_f32_16x16x32_bf16 v[60:63], v[156:159], v[0:3], v[60:63]
	v_mfma_f32_16x16x32_bf16 v[0:3], v[174:177], v[0:3], v[56:59]
	v_mfma_f32_16x16x32_bf16 v[56:59], v[170:173], v[4:7], v[0:3]
	v_mfma_f32_16x16x32_bf16 v[0:3], v[156:159], v[186:189], v[44:47]
	v_mfma_f32_16x16x32_bf16 v[44:47], v[152:155], v[190:193], v[0:3]
	v_mfma_f32_16x16x32_bf16 v[0:3], v[174:177], v[186:189], v[40:43]
	v_mfma_f32_16x16x32_bf16 v[40:43], v[170:173], v[190:193], v[0:3]
	v_mfma_f32_16x16x32_bf16 v[0:3], v[156:159], v[194:197], v[28:31]
	v_mfma_f32_16x16x32_bf16 v[28:31], v[152:155], v[198:201], v[0:3]
	v_mfma_f32_16x16x32_bf16 v[0:3], v[174:177], v[194:197], v[24:27]
	v_mfma_f32_16x16x32_bf16 v[24:27], v[170:173], v[198:201], v[0:3]
	v_mfma_f32_16x16x32_bf16 v[0:3], v[156:159], v[244:247], v[12:15]
	v_mfma_f32_16x16x32_bf16 v[12:15], v[152:155], v[248:251], v[0:3]
	v_mfma_f32_16x16x32_bf16 v[0:3], v[174:177], v[244:247], v[8:11]
	v_mfma_f32_16x16x32_bf16 v[60:63], v[152:155], v[4:7], v[60:63]
	v_mfma_f32_16x16x32_bf16 v[8:11], v[170:173], v[248:251], v[0:3]
	s_and_b64 vcc, exec, s[40:41]
	s_mov_b64 s[2:3], -1
	s_cbranch_vccnz .LBB0_547
	v_mfma_f32_16x16x32_bf16 v[0:3], v[166:169], v[182:185], v[136:139]
	s_mov_b64 s[2:3], 0
	v_mfma_f32_16x16x32_bf16 v[166:169], v[174:177], v[182:185], v[140:143]
	v_mfma_f32_16x16x32_bf16 v[4:7], v[162:165], v[178:181], v[0:3]
	v_mfma_f32_16x16x32_bf16 v[0:3], v[170:173], v[178:181], v[166:169]

; #define PG8_STAGE(bufoff, gbase, voff) do { _Pragma("unroll") for (int _i = 0; _i < 2; ++_i) \
;         __builtin_amdgcn_global_load_lds((const GAS unsigned*)((const GAS char*)(gbase) + (voff)[_i]), (PG8_LAS unsigned*)(lds + (bufoff) + ldsw + _i * 8192), 16, 0, 0); } while (0)
; #define PG8_LDA(dst, b, h) do { _Pragma("unroll") for (int m = 0; m < 4; ++m) _Pragma("unroll") for (int k = 0; k < 2; ++k) dst[m][k] = *(const PG8_LAS bf16x8*)(lds + PG8_SA(b, h) + aoff + m * 2048 + k * 1024); } while (0)
; #define PG8_LDB(dst, b, h) do { _Pragma("unroll") for (int n = 0; n < 2; ++n) _Pragma("unroll") for (int k = 0; k < 2; ++k) dst[n][k] = *(const PG8_LAS bf16x8*)(lds + PG8_SB(b, h) + boff + n * 2048 + k * 1024); } while (0)
; #define PG8_MMA(ai, bj, At, Bt) do { __builtin_amdgcn_s_setprio(1); _Pragma("unroll") for (int m = 0; m < 4; ++m) _Pragma("unroll") for (int n = 0; n < 2; ++n) _Pragma("unroll") for (int k = 0; k < 2; ++k) \
;         acc[ai][bj][m][n] = __builtin_amdgcn_mfma_f32_16x16x32_bf16(Bt[n][k], At[m][k], acc[ai][bj][m][n], 0, 0, 0); __builtin_amdgcn_s_setprio(0); } while (0)
; #define PG8_WAIT_V(n) asm volatile("s_waitcnt vmcnt(" #n ")" ::: "memory")
; #define PG8_WAIT_L(n) asm volatile("s_waitcnt lgkmcnt(" #n ")" ::: "memory")
; #define PG8_BAR __builtin_amdgcn_s_barrier()
; #define PG8_SCHED __builtin_amdgcn_sched_barrier(0)
; #define PG8_STAGE(bufoff, gbase, voff) do { _Pragma("unroll") for (int _i = 0; _i < 2; ++_i) \
;         __builtin_amdgcn_global_load_lds((const GAS unsigned*)((const GAS char*)(gbase) + (voff)[_i]), (PG8_LAS unsigned*)(lds + (bufoff) + ldsw + _i * 8192), 16, 0, 0); } while (0)
; #define PG8_LDA(dst, b, h) do { _Pragma("unroll") for (int m = 0; m < 4; ++m) _Pragma("unroll") for (int k = 0; k < 2; ++k) dst[m][k] = *(const PG8_LAS bf16x8*)(lds + PG8_SA(b, h) + aoff + m * 2048 + k * 1024); } while (0)
; #define PG8_BAR __builtin_amdgcn_s_barrier()
; template <class Epi, class Sched>
; __device__ __forceinline__ void gemm_phase_strip(PG8_LAS unsigned char* lds, PG8_LAS unsigned char* slds, PG8_LAS unsigned char* pf, const Gemm g, const Sched& S, const Epi& E, int wv) {
;     ...
;             PG8_LDB(B0, 0, 0); PG8_LDB(B1, 0, 1); PG8_SCHED; PG8_LDA(At, 0, 0); PG8_STAGE(PG8_SA(1, 1), a1 + PG8_HS, voffA);
;             PG8_WAIT_V(8); PG8_WAIT_L(0); PG8_BAR; PG8_MMA(0, 0, At, B0); PG8_MMA(0, 1, At, B1); PG8_BAR; PG8_SCHED;
.LBB0_1109:
	s_add_u32 s24, s12, s14
	s_addc_u32 s25, s13, s15
	s_add_u32 s28, s24, 0x100
	s_addc_u32 s29, s25, 0
	s_add_u32 s38, s21, s14
	s_addc_u32 s39, s22, s15
	s_add_i32 s41, 0, 0x10000
	s_add_i32 s43, 0, 0x14000
	v_add_u32_e32 v132, s41, v233
	ds_read_b128 v[148:151], v132
	ds_read_b128 v[144:147], v132 offset:1024
	ds_read_b128 v[166:169], v132 offset:2048
	ds_read_b128 v[162:165], v132 offset:3072
	v_add_u32_e32 v132, s43, v233
	ds_read_b128 v[156:159], v132
	ds_read_b128 v[152:155], v132 offset:1024
	ds_read_b128 v[174:177], v132 offset:2048
	ds_read_b128 v[170:173], v132 offset:3072
	s_cmpk_eq_i32 s14, 0x300
	s_cselect_b64 s[58:59], -1, 0
	s_and_b64 s[24:25], s[58:59], exec
	s_cselect_b32 s29, s51, s29
	s_cselect_b32 s28, s50, s28
	s_cselect_b32 s57, s1, s39
	s_cselect_b32 s56, s5, s38
	v_lshl_add_u64 v[222:223], v[220:221], 0, s[14:15]
	s_add_i32 m0, s19, 0xc000
	ds_read_b128 v[132:135], v236
	ds_read_b128 v[140:143], v236 offset:1024
	ds_read_b128 v[178:181], v236 offset:2048
	ds_read_b128 v[182:185], v236 offset:3072
	ds_read_b128 v[186:189], v236 offset:4096
	ds_read_b128 v[190:193], v236 offset:5120
	ds_read_b128 v[194:197], v236 offset:6144
	ds_read_b128 v[198:201], v236 offset:7168
	global_load_lds_dwordx4 v[222:223], off
	v_lshl_add_u64 v[222:223], v[218:219], 0, s[14:15]
	s_add_i32 m0, s19, 0xe000
	s_nop 0
	global_load_lds_dwordx4 v[222:223], off
	s_waitcnt vmcnt(8)
	s_waitcnt lgkmcnt(0)
	s_barrier
	s_waitcnt lgkmcnt(0)
	v_mfma_f32_16x16x32_bf16 v[136:139], v[148:151], v[132:135], v[136:139]
	v_mfma_f32_16x16x32_bf16 v[136:139], v[144:147], v[140:143], v[136:139]
	v_mfma_f32_16x16x32_bf16 v[128:131], v[166:169], v[132:135], v[128:131]
	v_mfma_f32_16x16x32_bf16 v[128:131], v[162:165], v[140:143], v[128:131]
	v_mfma_f32_16x16x32_bf16 v[124:127], v[148:151], v[178:181], v[124:127]
	v_mfma_f32_16x16x32_bf16 v[124:127], v[144:147], v[182:185], v[124:127]
	v_mfma_f32_16x16x32_bf16 v[120:123], v[166:169], v[178:181], v[120:123]
	v_mfma_f32_16x16x32_bf16 v[120:123], v[162:165], v[182:185], v[120:123]
	v_mfma_f32_16x16x32_bf16 v[116:119], v[148:151], v[186:189], v[116:119]
	v_mfma_f32_16x16x32_bf16 v[116:119], v[144:147], v[190:193], v[116:119]
	v_mfma_f32_16x16x32_bf16 v[112:115], v[166:169], v[186:189], v[112:115]
	v_mfma_f32_16x16x32_bf16 v[112:115], v[162:165], v[190:193], v[112:115]
	v_mfma_f32_16x16x32_bf16 v[108:111], v[148:151], v[194:197], v[108:111]
	v_mfma_f32_16x16x32_bf16 v[108:111], v[144:147], v[198:201], v[108:111]
	v_mfma_f32_16x16x32_bf16 v[104:107], v[166:169], v[194:197], v[104:107]
	v_mfma_f32_16x16x32_bf16 v[104:107], v[162:165], v[198:201], v[104:107]
	v_mfma_f32_16x16x32_bf16 v[68:71], v[156:159], v[132:135], v[68:71]
	v_mfma_f32_16x16x32_bf16 v[68:71], v[152:155], v[140:143], v[68:71]
	v_mfma_f32_16x16x32_bf16 v[64:67], v[174:177], v[132:135], v[64:67]
	v_mfma_f32_16x16x32_bf16 v[64:67], v[170:173], v[140:143], v[64:67]
	v_mfma_f32_16x16x32_bf16 v[60:63], v[156:159], v[178:181], v[60:63]
	v_mfma_f32_16x16x32_bf16 v[60:63], v[152:155], v[182:185], v[60:63]
	v_mfma_f32_16x16x32_bf16 v[56:59], v[174:177], v[178:181], v[56:59]
	v_mfma_f32_16x16x32_bf16 v[56:59], v[170:173], v[182:185], v[56:59]
	v_mfma_f32_16x16x32_bf16 v[52:55], v[156:159], v[186:189], v[52:55]
	v_mfma_f32_16x16x32_bf16 v[52:55], v[152:155], v[190:193], v[52:55]
	v_mfma_f32_16x16x32_bf16 v[48:51], v[174:177], v[186:189], v[48:51]
	v_mfma_f32_16x16x32_bf16 v[48:51], v[170:173], v[190:193], v[48:51]
	v_mfma_f32_16x16x32_bf16 v[44:47], v[156:159], v[194:197], v[44:47]
	v_mfma_f32_16x16x32_bf16 v[44:47], v[152:155], v[198:201], v[44:47]
	v_mfma_f32_16x16x32_bf16 v[40:43], v[174:177], v[194:197], v[40:43]
	v_mfma_f32_16x16x32_bf16 v[40:43], v[170:173], v[198:201], v[40:43]
	s_barrier
; #define PG8_STAGE(bufoff, gbase, voff) do { _Pragma("unroll") for (int _i = 0; _i < 2; ++_i) \
;         __builtin_amdgcn_global_load_lds((const GAS unsigned*)((const GAS char*)(gbase) + (voff)[_i]), (PG8_LAS unsigned*)(lds + (bufoff) + ldsw + _i * 8192), 16, 0, 0); } while (0)
; #define PG8_LDA(dst, b, h) do { _Pragma("unroll") for (int m = 0; m < 4; ++m) _Pragma("unroll") for (int k = 0; k < 2; ++k) dst[m][k] = *(const PG8_LAS bf16x8*)(lds + PG8_SA(b, h) + aoff + m * 2048 + k * 1024); } while (0)
; #define PG8_MMA(ai, bj, At, Bt) do { __builtin_amdgcn_s_setprio(1); _Pragma("unroll") for (int m = 0; m < 4; ++m) _Pragma("unroll") for (int n = 0; n < 2; ++n) _Pragma("unroll") for (int k = 0; k < 2; ++k) \
;         acc[ai][bj][m][n] = __builtin_amdgcn_mfma_f32_16x16x32_bf16(Bt[n][k], At[m][k], acc[ai][bj][m][n], 0, 0, 0); __builtin_amdgcn_s_setprio(0); } while (0)
; #define PG8_WAIT_V(n) asm volatile("s_waitcnt vmcnt(" #n ")" ::: "memory")
; #define PG8_WAIT_L(n) asm volatile("s_waitcnt lgkmcnt(" #n ")" ::: "memory")
; #define PG8_BAR __builtin_amdgcn_s_barrier()
; #define PG8_SCHED __builtin_amdgcn_sched_barrier(0)
; #define PG8_STAGE(bufoff, gbase, voff) do { _Pragma("unroll") for (int _i = 0; _i < 2; ++_i) \
;         __builtin_amdgcn_global_load_lds((const GAS unsigned*)((const GAS char*)(gbase) + (voff)[_i]), (PG8_LAS unsigned*)(lds + (bufoff) + ldsw + _i * 8192), 16, 0, 0); } while (0)
; #define PG8_LDA(dst, b, h) do { _Pragma("unroll") for (int m = 0; m < 4; ++m) _Pragma("unroll") for (int k = 0; k < 2; ++k) dst[m][k] = *(const PG8_LAS bf16x8*)(lds + PG8_SA(b, h) + aoff + m * 2048 + k * 1024); } while (0)
; #define PG8_LDS_S(dst, boffs) do { dst[0] = *(const PG8_LAS bf16x8*)(slds + (boffs) + soff0); dst[1] = *(const PG8_LAS bf16x8*)(slds + (boffs) + (soff0 ^ 64)); } while (0)
; #define PG8_BAR __builtin_amdgcn_s_barrier()
; template <class Epi, class Sched>
; __device__ __forceinline__ void gemm_phase_strip(PG8_LAS unsigned char* lds, PG8_LAS unsigned char* slds, PG8_LAS unsigned char* pf, const Gemm g, const Sched& S, const Epi& E, int wv) {
;     ...
;             PG8_LDA(At, 0, 1); PG8_LDS_S(As, sq); PG8_STAGE(PG8_SB(0, 0), b2, voffB); PG8_STAGE(PG8_SB(0, 1), b2 + hstepB, voffB); PG8_STAGE(PG8_SA(0, 0), a2, voffA);
;             PG8_WAIT_V(8); PG8_WAIT_L(0); PG8_BAR; PG8_MMA(1, 0, At, B0); PG8_MMA(1, 1, At, B1); PG8_MMA_S(); PG8_BAR; PG8_SCHED;
	s_add_i32 s24, s97, 0
	s_add_i32 s24, s24, 0x21000
	v_add_u32_e32 v160, s24, v234
	v_add_u32_e32 v237, s24, v235
	s_add_i32 s24, s41, s81
	v_lshl_add_u64 v[222:223], s[56:57], 0, v[204:205]
	s_mov_b32 m0, s24
	ds_read_b128 v[132:135], v236 offset:16384
	ds_read_b128 v[140:143], v236 offset:17408
	ds_read_b128 v[186:189], v236 offset:18432
	ds_read_b128 v[190:193], v236 offset:19456
	ds_read_b128 v[194:197], v236 offset:20480
	ds_read_b128 v[198:201], v236 offset:21504
	ds_read_b128 v[242:245], v236 offset:22528
	ds_read_b128 v[246:249], v236 offset:23552
	ds_read_b128 v[182:185], v160
	ds_read_b128 v[178:181], v237
	global_load_lds_dwordx4 v[222:223], off
	s_add_i32 m0, s24, 0x2000
	s_add_u32 s24, s56, 0x20000
	v_lshl_add_u64 v[224:225], s[56:57], 0, v[208:209]
	s_addc_u32 s25, s57, 0
	s_add_i32 s38, s43, s81
	global_load_lds_dwordx4 v[224:225], off
	v_lshl_add_u64 v[226:227], s[24:25], 0, v[204:205]
	s_mov_b32 m0, s38
	v_lshl_add_u64 v[228:229], s[28:29], 0, v[206:207]
	global_load_lds_dwordx4 v[226:227], off
	v_lshl_add_u64 v[226:227], s[24:25], 0, v[208:209]
	s_add_i32 m0, s38, 0x2000
	s_nop 0
	global_load_lds_dwordx4 v[226:227], off
	v_lshl_add_u64 v[226:227], s[28:29], 0, v[202:203]
	s_mov_b32 m0, s19
	s_nop 0
	global_load_lds_dwordx4 v[226:227], off
	s_mov_b32 m0, s27
	s_nop 0
	global_load_lds_dwordx4 v[228:229], off
	s_waitcnt vmcnt(8)
	s_waitcnt lgkmcnt(0)
	s_barrier
	s_waitcnt lgkmcnt(0)
	v_mfma_f32_16x16x32_bf16 v[100:103], v[148:151], v[132:135], v[100:103]
	v_mfma_f32_16x16x32_bf16 v[100:103], v[144:147], v[140:143], v[100:103]
	v_mfma_f32_16x16x32_bf16 v[96:99], v[166:169], v[132:135], v[96:99]
	v_mfma_f32_16x16x32_bf16 v[96:99], v[162:165], v[140:143], v[96:99]
	v_mfma_f32_16x16x32_bf16 v[92:95], v[148:151], v[186:189], v[92:95]
	v_mfma_f32_16x16x32_bf16 v[92:95], v[144:147], v[190:193], v[92:95]
	v_mfma_f32_16x16x32_bf16 v[88:91], v[166:169], v[186:189], v[88:91]
	v_mfma_f32_16x16x32_bf16 v[88:91], v[162:165], v[190:193], v[88:91]
	v_mfma_f32_16x16x32_bf16 v[84:87], v[148:151], v[194:197], v[84:87]
	v_mfma_f32_16x16x32_bf16 v[84:87], v[144:147], v[198:201], v[84:87]
	v_mfma_f32_16x16x32_bf16 v[80:83], v[166:169], v[194:197], v[80:83]
	v_mfma_f32_16x16x32_bf16 v[80:83], v[162:165], v[198:201], v[80:83]
	v_mfma_f32_16x16x32_bf16 v[76:79], v[148:151], v[242:245], v[76:79]
	v_mfma_f32_16x16x32_bf16 v[76:79], v[144:147], v[246:249], v[76:79]
	v_mfma_f32_16x16x32_bf16 v[72:75], v[166:169], v[242:245], v[72:75]
	v_mfma_f32_16x16x32_bf16 v[72:75], v[162:165], v[246:249], v[72:75]
	v_mfma_f32_16x16x32_bf16 v[36:39], v[156:159], v[132:135], v[36:39]
	v_mfma_f32_16x16x32_bf16 v[36:39], v[152:155], v[140:143], v[36:39]
	v_mfma_f32_16x16x32_bf16 v[32:35], v[174:177], v[132:135], v[32:35]
	v_mfma_f32_16x16x32_bf16 v[32:35], v[170:173], v[140:143], v[32:35]
	v_mfma_f32_16x16x32_bf16 v[28:31], v[156:159], v[186:189], v[28:31]
	v_mfma_f32_16x16x32_bf16 v[28:31], v[152:155], v[190:193], v[28:31]
	v_mfma_f32_16x16x32_bf16 v[24:27], v[174:177], v[186:189], v[24:27]
	v_mfma_f32_16x16x32_bf16 v[24:27], v[170:173], v[190:193], v[24:27]
	v_mfma_f32_16x16x32_bf16 v[20:23], v[156:159], v[194:197], v[20:23]
	v_mfma_f32_16x16x32_bf16 v[20:23], v[152:155], v[198:201], v[20:23]
	v_mfma_f32_16x16x32_bf16 v[16:19], v[174:177], v[194:197], v[16:19]
	v_mfma_f32_16x16x32_bf16 v[16:19], v[170:173], v[198:201], v[16:19]
	v_mfma_f32_16x16x32_bf16 v[12:15], v[156:159], v[242:245], v[12:15]
	v_mfma_f32_16x16x32_bf16 v[12:15], v[152:155], v[246:249], v[12:15]
	v_mfma_f32_16x16x32_bf16 v[8:11], v[174:177], v[242:245], v[8:11]
	v_mfma_f32_16x16x32_bf16 v[8:11], v[170:173], v[246:249], v[8:11]
	v_cndmask_b32_e64 v132, 0, 1, s[8:9]
	v_cmp_ne_u32_e64 s[38:39], 1, v132
	s_andn2_b64 vcc, exec, s[8:9]
	s_mov_b64 s[60:61], -1
	s_cbranch_vccnz .LBB0_1111
	v_mfma_f32_16x16x32_bf16 v[132:135], v[166:169], v[182:185], v[4:7]
	s_mov_b64 s[60:61], 0
	v_mfma_f32_16x16x32_bf16 v[140:143], v[174:177], v[182:185], v[0:3]
	v_mfma_f32_16x16x32_bf16 v[132:135], v[162:165], v[178:181], v[132:135]
	v_mfma_f32_16x16x32_bf16 v[140:143], v[170:173], v[178:181], v[140:143]

; #define PG8_STAGE(bufoff, gbase, voff) do { _Pragma("unroll") for (int _i = 0; _i < 2; ++_i) \
;         __builtin_amdgcn_global_load_lds((const GAS unsigned*)((const GAS char*)(gbase) + (voff)[_i]), (PG8_LAS unsigned*)(lds + (bufoff) + ldsw + _i * 8192), 16, 0, 0); } while (0)
; #define PG8_LDA(dst, b, h) do { _Pragma("unroll") for (int m = 0; m < 4; ++m) _Pragma("unroll") for (int k = 0; k < 2; ++k) dst[m][k] = *(const PG8_LAS bf16x8*)(lds + PG8_SA(b, h) + aoff + m * 2048 + k * 1024); } while (0)
; #define PG8_LDB(dst, b, h) do { _Pragma("unroll") for (int n = 0; n < 2; ++n) _Pragma("unroll") for (int k = 0; k < 2; ++k) dst[n][k] = *(const PG8_LAS bf16x8*)(lds + PG8_SB(b, h) + boff + n * 2048 + k * 1024); } while (0)
; #define PG8_MMA(ai, bj, At, Bt) do { __builtin_amdgcn_s_setprio(1); _Pragma("unroll") for (int m = 0; m < 4; ++m) _Pragma("unroll") for (int n = 0; n < 2; ++n) _Pragma("unroll") for (int k = 0; k < 2; ++k) \
;         acc[ai][bj][m][n] = __builtin_amdgcn_mfma_f32_16x16x32_bf16(Bt[n][k], At[m][k], acc[ai][bj][m][n], 0, 0, 0); __builtin_amdgcn_s_setprio(0); } while (0)
; #define PG8_WAIT_V(n) asm volatile("s_waitcnt vmcnt(" #n ")" ::: "memory")
; #define PG8_WAIT_L(n) asm volatile("s_waitcnt lgkmcnt(" #n ")" ::: "memory")
; #define PG8_BAR __builtin_amdgcn_s_barrier()
; #define PG8_SCHED __builtin_amdgcn_sched_barrier(0)
; #define PG8_WAIT_V(n) asm volatile("s_waitcnt vmcnt(" #n ")" ::: "memory")
; #define PG8_BAR __builtin_amdgcn_s_barrier()
; template <class Epi, class Sched>
; __device__ __forceinline__ void gemm_phase_strip(PG8_LAS unsigned char* lds, PG8_LAS unsigned char* slds, PG8_LAS unsigned char* pf, const Gemm g, const Sched& S, const Epi& E, int wv) {
;     ...
;             PG8_LDB(B0, 1, 0); PG8_LDB(B1, 1, 1); PG8_SCHED; PG8_LDA(At, 1, 0); PG8_STAGE(PG8_SA(0, 1), a2 + (Sched::SPLIT ? ((last && has_next) ? (nxt.kh > 0 ? -(long)hstepA : (long)hstepA) : hsA) : (long)hstepA), voffA); PG8_STAGE_S(sq ^ 4096u, s2);
;             PG8_WAIT_V(9); PG8_WAIT_L(0); PG8_BAR; PG8_MMA(0, 0, At, B0); PG8_MMA(0, 1, At, B1); PG8_BAR; PG8_SCHED;
;             PG8_LDA(At, 1, 1); PG8_LDS_S(As, sq + 2048u); PG8_STAGE(PG8_SB(1, 0), b3, voffB); PG8_STAGE(PG8_SB(1, 1), b3 + hstepB, voffB); PG8_STAGE(PG8_SA(1, 0), a3, voffA);
;             PG8_WAIT_V(9); PG8_WAIT_L(0); PG8_BAR; PG8_MMA(1, 0, At, B0); PG8_MMA(1, 1, At, B1); PG8_MMA_S(); PG8_BAR; PG8_SCHED;
.LBB0_1115:
	s_or_b64 exec, exec, s[28:29]
	s_waitcnt vmcnt(9)
	s_waitcnt lgkmcnt(0)
	s_barrier
	s_waitcnt lgkmcnt(0)
	v_mfma_f32_16x16x32_bf16 v[136:139], v[148:151], v[194:197], v[136:139]
	v_mfma_f32_16x16x32_bf16 v[136:139], v[144:147], v[198:201], v[136:139]
	v_mfma_f32_16x16x32_bf16 v[128:131], v[166:169], v[194:197], v[128:131]
	v_mfma_f32_16x16x32_bf16 v[128:131], v[162:165], v[198:201], v[128:131]
	v_mfma_f32_16x16x32_bf16 v[124:127], v[148:151], v[186:189], v[124:127]
	v_mfma_f32_16x16x32_bf16 v[124:127], v[144:147], v[190:193], v[124:127]
	v_mfma_f32_16x16x32_bf16 v[120:123], v[166:169], v[186:189], v[120:123]
	v_mfma_f32_16x16x32_bf16 v[120:123], v[162:165], v[190:193], v[120:123]
	v_mfma_f32_16x16x32_bf16 v[116:119], v[148:151], v[178:181], v[116:119]
	v_mfma_f32_16x16x32_bf16 v[116:119], v[144:147], v[182:185], v[116:119]
	v_mfma_f32_16x16x32_bf16 v[112:115], v[166:169], v[178:181], v[112:115]
	v_mfma_f32_16x16x32_bf16 v[112:115], v[162:165], v[182:185], v[112:115]
	v_mfma_f32_16x16x32_bf16 v[108:111], v[148:151], v[0:3], v[108:111]
	v_mfma_f32_16x16x32_bf16 v[108:111], v[144:147], v[4:7], v[108:111]
	v_mfma_f32_16x16x32_bf16 v[104:107], v[166:169], v[0:3], v[104:107]
	v_mfma_f32_16x16x32_bf16 v[104:107], v[162:165], v[4:7], v[104:107]
	v_mfma_f32_16x16x32_bf16 v[68:71], v[156:159], v[194:197], v[68:71]
	v_mfma_f32_16x16x32_bf16 v[64:67], v[174:177], v[194:197], v[64:67]
	v_mfma_f32_16x16x32_bf16 v[60:63], v[156:159], v[186:189], v[60:63]
	v_mfma_f32_16x16x32_bf16 v[56:59], v[174:177], v[186:189], v[56:59]
	v_mfma_f32_16x16x32_bf16 v[52:55], v[156:159], v[178:181], v[52:55]
	v_mfma_f32_16x16x32_bf16 v[48:51], v[174:177], v[178:181], v[48:51]
	v_mfma_f32_16x16x32_bf16 v[44:47], v[156:159], v[0:3], v[44:47]
	v_mfma_f32_16x16x32_bf16 v[0:3], v[174:177], v[0:3], v[40:43]
	v_mfma_f32_16x16x32_bf16 v[68:71], v[152:155], v[198:201], v[68:71]
	v_mfma_f32_16x16x32_bf16 v[64:67], v[170:173], v[198:201], v[64:67]
	v_mfma_f32_16x16x32_bf16 v[60:63], v[152:155], v[190:193], v[60:63]
	v_mfma_f32_16x16x32_bf16 v[56:59], v[170:173], v[190:193], v[56:59]
	v_mfma_f32_16x16x32_bf16 v[52:55], v[152:155], v[182:185], v[52:55]
	v_mfma_f32_16x16x32_bf16 v[48:51], v[170:173], v[182:185], v[48:51]
	v_mfma_f32_16x16x32_bf16 v[44:47], v[152:155], v[4:7], v[44:47]
	v_mfma_f32_16x16x32_bf16 v[40:43], v[170:173], v[4:7], v[0:3]
	s_barrier
	s_mov_b32 m0, s83
	v_lshl_add_u64 v[222:223], v[222:223], 0, s[16:17]
	s_add_u32 s24, s56, 0x20080
	ds_read_b128 v[0:3], v236 offset:49152
	ds_read_b128 v[4:7], v236 offset:50176
	ds_read_b128 v[186:189], v236 offset:51200
	ds_read_b128 v[190:193], v236 offset:52224
	ds_read_b128 v[194:197], v236 offset:53248
	ds_read_b128 v[198:201], v236 offset:54272
	ds_read_b128 v[242:245], v236 offset:55296
	ds_read_b128 v[246:249], v236 offset:56320
	ds_read_b128 v[182:185], v160 offset:2048
	ds_read_b128 v[178:181], v237 offset:2048
	global_load_lds_dwordx4 v[222:223], off
	v_lshl_add_u64 v[222:223], v[224:225], 0, s[16:17]
	s_mov_b32 m0, s84
	s_addc_u32 s25, s57, 0
	global_load_lds_dwordx4 v[222:223], off
	v_lshl_add_u64 v[222:223], s[24:25], 0, v[204:205]
	s_mov_b32 m0, s87
	s_nop 0
	global_load_lds_dwordx4 v[222:223], off
	v_lshl_add_u64 v[222:223], s[24:25], 0, v[208:209]
	s_mov_b32 m0, s88
	s_nop 0
	global_load_lds_dwordx4 v[222:223], off
	v_lshl_add_u64 v[222:223], v[226:227], 0, s[16:17]
	s_mov_b32 m0, s85
	s_nop 0
	global_load_lds_dwordx4 v[222:223], off
	v_lshl_add_u64 v[222:223], v[228:229], 0, s[16:17]
	s_mov_b32 m0, s86
	s_nop 0
	global_load_lds_dwordx4 v[222:223], off
	s_waitcnt vmcnt(9)
	s_waitcnt lgkmcnt(0)
	s_barrier
	s_waitcnt lgkmcnt(0)
	v_mfma_f32_16x16x32_bf16 v[100:103], v[148:151], v[0:3], v[100:103]
	v_mfma_f32_16x16x32_bf16 v[100:103], v[144:147], v[4:7], v[100:103]
	v_mfma_f32_16x16x32_bf16 v[96:99], v[166:169], v[0:3], v[96:99]
	v_mfma_f32_16x16x32_bf16 v[96:99], v[162:165], v[4:7], v[96:99]
	v_mfma_f32_16x16x32_bf16 v[92:95], v[148:151], v[186:189], v[92:95]
	v_mfma_f32_16x16x32_bf16 v[92:95], v[144:147], v[190:193], v[92:95]
	v_mfma_f32_16x16x32_bf16 v[88:91], v[166:169], v[186:189], v[88:91]
	v_mfma_f32_16x16x32_bf16 v[88:91], v[162:165], v[190:193], v[88:91]
	v_mfma_f32_16x16x32_bf16 v[84:87], v[148:151], v[194:197], v[84:87]
	v_mfma_f32_16x16x32_bf16 v[84:87], v[144:147], v[198:201], v[84:87]
	v_mfma_f32_16x16x32_bf16 v[80:83], v[166:169], v[194:197], v[80:83]
	v_mfma_f32_16x16x32_bf16 v[80:83], v[162:165], v[198:201], v[80:83]
	v_mfma_f32_16x16x32_bf16 v[76:79], v[148:151], v[242:245], v[76:79]
	v_mfma_f32_16x16x32_bf16 v[76:79], v[144:147], v[246:249], v[76:79]
	v_mfma_f32_16x16x32_bf16 v[72:75], v[166:169], v[242:245], v[72:75]
	v_mfma_f32_16x16x32_bf16 v[72:75], v[162:165], v[246:249], v[72:75]
	v_mfma_f32_16x16x32_bf16 v[36:39], v[156:159], v[0:3], v[36:39]
	v_mfma_f32_16x16x32_bf16 v[0:3], v[174:177], v[0:3], v[32:35]
	v_mfma_f32_16x16x32_bf16 v[32:35], v[170:173], v[4:7], v[0:3]
	v_mfma_f32_16x16x32_bf16 v[0:3], v[156:159], v[186:189], v[28:31]
	v_mfma_f32_16x16x32_bf16 v[28:31], v[152:155], v[190:193], v[0:3]
	v_mfma_f32_16x16x32_bf16 v[0:3], v[174:177], v[186:189], v[24:27]
	v_mfma_f32_16x16x32_bf16 v[24:27], v[170:173], v[190:193], v[0:3]
	v_mfma_f32_16x16x32_bf16 v[0:3], v[156:159], v[194:197], v[20:23]
	v_mfma_f32_16x16x32_bf16 v[20:23], v[152:155], v[198:201], v[0:3]
	v_mfma_f32_16x16x32_bf16 v[0:3], v[174:177], v[194:197], v[16:19]
	v_mfma_f32_16x16x32_bf16 v[16:19], v[170:173], v[198:201], v[0:3]
	v_mfma_f32_16x16x32_bf16 v[0:3], v[156:159], v[242:245], v[12:15]
	v_mfma_f32_16x16x32_bf16 v[12:15], v[152:155], v[246:249], v[0:3]
	v_mfma_f32_16x16x32_bf16 v[0:3], v[174:177], v[242:245], v[8:11]
	v_mfma_f32_16x16x32_bf16 v[36:39], v[152:155], v[4:7], v[36:39]
	v_mfma_f32_16x16x32_bf16 v[8:11], v[170:173], v[246:249], v[0:3]
	s_and_b64 vcc, exec, s[38:39]
	s_mov_b64 s[28:29], -1
	s_cbranch_vccnz .LBB0_1117
	v_mfma_f32_16x16x32_bf16 v[0:3], v[166:169], v[182:185], v[132:135]
	s_mov_b64 s[28:29], 0
	v_mfma_f32_16x16x32_bf16 v[166:169], v[174:177], v[182:185], v[140:143]
	v_mfma_f32_16x16x32_bf16 v[4:7], v[162:165], v[178:181], v[0:3]
	v_mfma_f32_16x16x32_bf16 v[0:3], v[170:173], v[178:181], v[166:169]

; #define PG8_STAGE(bufoff, gbase, voff) do { _Pragma("unroll") for (int _i = 0; _i < 2; ++_i) \
;         __builtin_amdgcn_global_load_lds((const GAS unsigned*)((const GAS char*)(gbase) + (voff)[_i]), (PG8_LAS unsigned*)(lds + (bufoff) + ldsw + _i * 8192), 16, 0, 0); } while (0)
; #define PG8_LDA(dst, b, h) do { _Pragma("unroll") for (int m = 0; m < 4; ++m) _Pragma("unroll") for (int k = 0; k < 2; ++k) dst[m][k] = *(const PG8_LAS bf16x8*)(lds + PG8_SA(b, h) + aoff + m * 2048 + k * 1024); } while (0)
; #define PG8_LDB(dst, b, h) do { _Pragma("unroll") for (int n = 0; n < 2; ++n) _Pragma("unroll") for (int k = 0; k < 2; ++k) dst[n][k] = *(const PG8_LAS bf16x8*)(lds + PG8_SB(b, h) + boff + n * 2048 + k * 1024); } while (0)
; #define PG8_MMA(ai, bj, At, Bt) do { __builtin_amdgcn_s_setprio(1); _Pragma("unroll") for (int m = 0; m < 4; ++m) _Pragma("unroll") for (int n = 0; n < 2; ++n) _Pragma("unroll") for (int k = 0; k < 2; ++k) \
;         acc[ai][bj][m][n] = __builtin_amdgcn_mfma_f32_16x16x32_bf16(Bt[n][k], At[m][k], acc[ai][bj][m][n], 0, 0, 0); __builtin_amdgcn_s_setprio(0); } while (0)
; #define PG8_WAIT_V(n) asm volatile("s_waitcnt vmcnt(" #n ")" ::: "memory")
; #define PG8_WAIT_L(n) asm volatile("s_waitcnt lgkmcnt(" #n ")" ::: "memory")
; #define PG8_BAR __builtin_amdgcn_s_barrier()
; #define PG8_SCHED __builtin_amdgcn_sched_barrier(0)
; #define PG8_LDA(dst, b, h) do { _Pragma("unroll") for (int m = 0; m < 4; ++m) _Pragma("unroll") for (int k = 0; k < 2; ++k) dst[m][k] = *(const PG8_LAS bf16x8*)(lds + PG8_SA(b, h) + aoff + m * 2048 + k * 1024); } while (0)
; template <class Epi, class Sched, bool ALIGN_EPI = false, bool SP2 = false>
; __device__ __forceinline__ void gemm_phase(PG8_LAS unsigned char* lds, PG8_LAS unsigned char* pf, const Gemm g, const Sched& S, const Epi& E, int wv) {
;     ...
;             PG8_LDB(B0, 0, 0); PG8_LDB(B1, 0, 1); PG8_SCHED; PG8_LDA(At, 0, 0); PG8_STAGE(PG8_SA(1, 1), a1 + (Sched::SPLIT ? hsA : (long)hstepA), voffA);
;             PG8_WAIT_V(8); PG8_WAIT_L(0); PG8_BAR; PG8_MMA(0, 0, At, B0); PG8_MMA(0, 1, At, B1); PG8_BAR; PG8_SCHED;
;             PG8_LDA(At, 0, 1); PG8_STAGE(PG8_SB(0, 0), b2, voffB); PG8_STAGE(PG8_SB(0, 1), b2 + hstepB, voffB); PG8_STAGE(PG8_SA(0, 0), a2, voffA);
;             PG8_WAIT_V(8); PG8_WAIT_L(0); PG8_BAR; PG8_MMA(1, 0, At, B0); PG8_MMA(1, 1, At, B1); PG8_BAR; PG8_SCHED;
.LBB0_1186:
	s_add_u32 s22, s14, 0xfff80080
	s_addc_u32 s23, s15, -1
	s_add_i32 s24, 0, 0x10000
	s_cmp_eq_u32 s21, 4
	s_cselect_b32 s29, s39, s23
	s_cselect_b32 s28, s38, s22
	s_cselect_b32 s37, s5, s20
	s_cselect_b32 s36, s11, s13
	s_add_i32 s25, 0, 0x14000
	v_add_u32_e32 v140, s24, v204
	v_add_u32_e32 v156, s25, v204
	ds_read_b128 v[120:123], v140
	ds_read_b128 v[124:127], v140 offset:1024
	ds_read_b128 v[136:139], v140 offset:2048
	ds_read_b128 v[140:143], v140 offset:3072
	ds_read_b128 v[144:147], v156
	ds_read_b128 v[148:151], v156 offset:1024
	ds_read_b128 v[152:155], v156 offset:2048
	ds_read_b128 v[156:159], v156 offset:3072
	v_lshl_add_u64 v[214:215], s[14:15], 0, v[172:173]
	s_add_i32 m0, s18, 0xc000
	ds_read_b128 v[174:177], v205
	ds_read_b128 v[178:181], v205 offset:1024
	ds_read_b128 v[182:185], v205 offset:2048
	ds_read_b128 v[186:189], v205 offset:3072
	ds_read_b128 v[190:193], v205 offset:4096
	ds_read_b128 v[194:197], v205 offset:5120
	ds_read_b128 v[198:201], v205 offset:6144
	ds_read_b128 v[206:209], v205 offset:7168
	global_load_lds_dwordx4 v[214:215], off
	v_lshl_add_u64 v[214:215], s[14:15], 0, v[170:171]
	s_add_i32 m0, s18, 0xe000
	s_nop 0
	global_load_lds_dwordx4 v[214:215], off
	s_waitcnt vmcnt(8)
	s_waitcnt lgkmcnt(0)
	s_barrier
	s_waitcnt lgkmcnt(0)
	v_mfma_f32_16x16x32_bf16 v[132:135], v[120:123], v[174:177], v[132:135]
	v_mfma_f32_16x16x32_bf16 v[132:135], v[124:127], v[178:181], v[132:135]
	v_mfma_f32_16x16x32_bf16 v[128:131], v[136:139], v[174:177], v[128:131]
	v_mfma_f32_16x16x32_bf16 v[128:131], v[140:143], v[178:181], v[128:131]
	v_mfma_f32_16x16x32_bf16 v[116:119], v[120:123], v[182:185], v[116:119]
	v_mfma_f32_16x16x32_bf16 v[116:119], v[124:127], v[186:189], v[116:119]
	v_mfma_f32_16x16x32_bf16 v[112:115], v[136:139], v[182:185], v[112:115]
	v_mfma_f32_16x16x32_bf16 v[112:115], v[140:143], v[186:189], v[112:115]
	v_mfma_f32_16x16x32_bf16 v[108:111], v[120:123], v[190:193], v[108:111]
	v_mfma_f32_16x16x32_bf16 v[108:111], v[124:127], v[194:197], v[108:111]
	v_mfma_f32_16x16x32_bf16 v[104:107], v[136:139], v[190:193], v[104:107]
	v_mfma_f32_16x16x32_bf16 v[104:107], v[140:143], v[194:197], v[104:107]
	v_mfma_f32_16x16x32_bf16 v[100:103], v[120:123], v[198:201], v[100:103]
	v_mfma_f32_16x16x32_bf16 v[100:103], v[124:127], v[206:209], v[100:103]
	v_mfma_f32_16x16x32_bf16 v[96:99], v[136:139], v[198:201], v[96:99]
	v_mfma_f32_16x16x32_bf16 v[96:99], v[140:143], v[206:209], v[96:99]
	v_mfma_f32_16x16x32_bf16 v[60:63], v[144:147], v[174:177], v[60:63]
	v_mfma_f32_16x16x32_bf16 v[60:63], v[148:151], v[178:181], v[60:63]
	v_mfma_f32_16x16x32_bf16 v[56:59], v[152:155], v[174:177], v[56:59]
	v_mfma_f32_16x16x32_bf16 v[56:59], v[156:159], v[178:181], v[56:59]
	v_mfma_f32_16x16x32_bf16 v[52:55], v[144:147], v[182:185], v[52:55]
	v_mfma_f32_16x16x32_bf16 v[52:55], v[148:151], v[186:189], v[52:55]
	v_mfma_f32_16x16x32_bf16 v[48:51], v[152:155], v[182:185], v[48:51]
	v_mfma_f32_16x16x32_bf16 v[48:51], v[156:159], v[186:189], v[48:51]
	v_mfma_f32_16x16x32_bf16 v[44:47], v[144:147], v[190:193], v[44:47]
	v_mfma_f32_16x16x32_bf16 v[44:47], v[148:151], v[194:197], v[44:47]
	v_mfma_f32_16x16x32_bf16 v[40:43], v[152:155], v[190:193], v[40:43]
	v_mfma_f32_16x16x32_bf16 v[40:43], v[156:159], v[194:197], v[40:43]
	v_mfma_f32_16x16x32_bf16 v[36:39], v[144:147], v[198:201], v[36:39]
	v_mfma_f32_16x16x32_bf16 v[36:39], v[148:151], v[206:209], v[36:39]
	v_mfma_f32_16x16x32_bf16 v[32:35], v[152:155], v[198:201], v[32:35]
	v_mfma_f32_16x16x32_bf16 v[32:35], v[156:159], v[206:209], v[32:35]
	s_barrier
	s_add_i32 s22, s24, s81
	v_lshl_add_u64 v[214:215], s[36:37], 0, v[164:165]
	s_mov_b32 m0, s22
	ds_read_b128 v[174:177], v205 offset:16384
	ds_read_b128 v[178:181], v205 offset:17408
	ds_read_b128 v[182:185], v205 offset:18432
	ds_read_b128 v[186:189], v205 offset:19456
	ds_read_b128 v[190:193], v205 offset:20480
	ds_read_b128 v[194:197], v205 offset:21504
	ds_read_b128 v[198:201], v205 offset:22528
	ds_read_b128 v[206:209], v205 offset:23552
	global_load_lds_dwordx4 v[214:215], off
	s_add_i32 m0, s22, 0x2000
	s_add_u32 s22, s36, 0x20000
	v_lshl_add_u64 v[216:217], s[36:37], 0, v[168:169]
	s_addc_u32 s23, s37, 0
	s_add_i32 s24, s25, s81
	global_load_lds_dwordx4 v[216:217], off
	v_lshl_add_u64 v[218:219], s[22:23], 0, v[164:165]
	s_mov_b32 m0, s24
	v_lshl_add_u64 v[220:221], s[28:29], 0, v[166:167]
	global_load_lds_dwordx4 v[218:219], off
	v_lshl_add_u64 v[218:219], s[22:23], 0, v[168:169]
	s_add_i32 m0, s24, 0x2000
	s_nop 0
	global_load_lds_dwordx4 v[218:219], off
	v_lshl_add_u64 v[218:219], s[28:29], 0, v[162:163]
	s_mov_b32 m0, s18
	s_nop 0
	global_load_lds_dwordx4 v[218:219], off
	s_mov_b32 m0, s19
	s_nop 0
	global_load_lds_dwordx4 v[220:221], off
	s_waitcnt vmcnt(8)
	s_waitcnt lgkmcnt(0)
	s_barrier
; #define PG8_STAGE(bufoff, gbase, voff) do { _Pragma("unroll") for (int _i = 0; _i < 2; ++_i) \
;         __builtin_amdgcn_global_load_lds((const GAS unsigned*)((const GAS char*)(gbase) + (voff)[_i]), (PG8_LAS unsigned*)(lds + (bufoff) + ldsw + _i * 8192), 16, 0, 0); } while (0)
; #define PG8_LDA(dst, b, h) do { _Pragma("unroll") for (int m = 0; m < 4; ++m) _Pragma("unroll") for (int k = 0; k < 2; ++k) dst[m][k] = *(const PG8_LAS bf16x8*)(lds + PG8_SA(b, h) + aoff + m * 2048 + k * 1024); } while (0)
; #define PG8_LDB(dst, b, h) do { _Pragma("unroll") for (int n = 0; n < 2; ++n) _Pragma("unroll") for (int k = 0; k < 2; ++k) dst[n][k] = *(const PG8_LAS bf16x8*)(lds + PG8_SB(b, h) + boff + n * 2048 + k * 1024); } while (0)
; #define PG8_MMA(ai, bj, At, Bt) do { __builtin_amdgcn_s_setprio(1); _Pragma("unroll") for (int m = 0; m < 4; ++m) _Pragma("unroll") for (int n = 0; n < 2; ++n) _Pragma("unroll") for (int k = 0; k < 2; ++k) \
;         acc[ai][bj][m][n] = __builtin_amdgcn_mfma_f32_16x16x32_bf16(Bt[n][k], At[m][k], acc[ai][bj][m][n], 0, 0, 0); __builtin_amdgcn_s_setprio(0); } while (0)
; #define PG8_WAIT_V(n) asm volatile("s_waitcnt vmcnt(" #n ")" ::: "memory")
; #define PG8_WAIT_L(n) asm volatile("s_waitcnt lgkmcnt(" #n ")" ::: "memory")
; #define PG8_BAR __builtin_amdgcn_s_barrier()
; #define PG8_SCHED __builtin_amdgcn_sched_barrier(0)
; #define PG8_STAGE(bufoff, gbase, voff) do { _Pragma("unroll") for (int _i = 0; _i < 2; ++_i) \
;         __builtin_amdgcn_global_load_lds((const GAS unsigned*)((const GAS char*)(gbase) + (voff)[_i]), (PG8_LAS unsigned*)(lds + (bufoff) + ldsw + _i * 8192), 16, 0, 0); } while (0)
; #define PG8_BAR __builtin_amdgcn_s_barrier()
; template <class Epi, class Sched, bool ALIGN_EPI = false, bool SP2 = false>
; __device__ __forceinline__ void gemm_phase(PG8_LAS unsigned char* lds, PG8_LAS unsigned char* pf, const Gemm g, const Sched& S, const Epi& E, int wv) {
;     ...
;             PG8_WAIT_V(8); PG8_WAIT_L(0); PG8_BAR; PG8_MMA(1, 0, At, B0); PG8_MMA(1, 1, At, B1); PG8_BAR; PG8_SCHED;
;             PG8_LDB(B0, 1, 0); PG8_LDB(B1, 1, 1); PG8_SCHED; PG8_LDA(At, 1, 0); PG8_STAGE(PG8_SA(0, 1), a2 + (Sched::SPLIT ? ((last && has_next) ? (nxt.kh > 0 ? -(long)hstepA : (long)hstepA) : hsA) : (long)hstepA), voffA);
;             PG8_WAIT_V(8); PG8_WAIT_L(0); PG8_BAR; PG8_MMA(0, 0, At, B0); PG8_MMA(0, 1, At, B1); PG8_BAR; PG8_SCHED;
	s_waitcnt lgkmcnt(0)
	v_mfma_f32_16x16x32_bf16 v[92:95], v[120:123], v[174:177], v[92:95]
	v_mfma_f32_16x16x32_bf16 v[92:95], v[124:127], v[178:181], v[92:95]
	v_mfma_f32_16x16x32_bf16 v[88:91], v[136:139], v[174:177], v[88:91]
	v_mfma_f32_16x16x32_bf16 v[88:91], v[140:143], v[178:181], v[88:91]
	v_mfma_f32_16x16x32_bf16 v[84:87], v[120:123], v[182:185], v[84:87]
	v_mfma_f32_16x16x32_bf16 v[84:87], v[124:127], v[186:189], v[84:87]
	v_mfma_f32_16x16x32_bf16 v[80:83], v[136:139], v[182:185], v[80:83]
	v_mfma_f32_16x16x32_bf16 v[80:83], v[140:143], v[186:189], v[80:83]
	v_mfma_f32_16x16x32_bf16 v[76:79], v[120:123], v[190:193], v[76:79]
	v_mfma_f32_16x16x32_bf16 v[76:79], v[124:127], v[194:197], v[76:79]
	v_mfma_f32_16x16x32_bf16 v[72:75], v[136:139], v[190:193], v[72:75]
	v_mfma_f32_16x16x32_bf16 v[72:75], v[140:143], v[194:197], v[72:75]
	v_mfma_f32_16x16x32_bf16 v[68:71], v[120:123], v[198:201], v[68:71]
	v_mfma_f32_16x16x32_bf16 v[68:71], v[124:127], v[206:209], v[68:71]
	v_mfma_f32_16x16x32_bf16 v[64:67], v[136:139], v[198:201], v[64:67]
	v_mfma_f32_16x16x32_bf16 v[64:67], v[140:143], v[206:209], v[64:67]
	v_mfma_f32_16x16x32_bf16 v[28:31], v[144:147], v[174:177], v[28:31]
	v_mfma_f32_16x16x32_bf16 v[28:31], v[148:151], v[178:181], v[28:31]
	v_mfma_f32_16x16x32_bf16 v[24:27], v[152:155], v[174:177], v[24:27]
	v_mfma_f32_16x16x32_bf16 v[24:27], v[156:159], v[178:181], v[24:27]
	v_mfma_f32_16x16x32_bf16 v[20:23], v[144:147], v[182:185], v[20:23]
	v_mfma_f32_16x16x32_bf16 v[20:23], v[148:151], v[186:189], v[20:23]
	v_mfma_f32_16x16x32_bf16 v[16:19], v[152:155], v[182:185], v[16:19]
	v_mfma_f32_16x16x32_bf16 v[16:19], v[156:159], v[186:189], v[16:19]
	v_mfma_f32_16x16x32_bf16 v[12:15], v[144:147], v[190:193], v[12:15]
	v_mfma_f32_16x16x32_bf16 v[12:15], v[148:151], v[194:197], v[12:15]
	v_mfma_f32_16x16x32_bf16 v[8:11], v[152:155], v[190:193], v[8:11]
	v_mfma_f32_16x16x32_bf16 v[8:11], v[156:159], v[194:197], v[8:11]
	v_mfma_f32_16x16x32_bf16 v[4:7], v[144:147], v[198:201], v[4:7]
	v_mfma_f32_16x16x32_bf16 v[4:7], v[148:151], v[206:209], v[4:7]
	v_mfma_f32_16x16x32_bf16 v[0:3], v[152:155], v[198:201], v[0:3]
	v_mfma_f32_16x16x32_bf16 v[0:3], v[156:159], v[206:209], v[0:3]
	s_barrier
	s_add_i32 s24, 0, 0x18000
	s_add_i32 s25, 0, 0x1c000
	v_add_u32_e32 v140, s24, v204
	v_add_u32_e32 v156, s25, v204
	ds_read_b128 v[120:123], v140
	ds_read_b128 v[124:127], v140 offset:1024
	ds_read_b128 v[136:139], v140 offset:2048
	ds_read_b128 v[140:143], v140 offset:3072
	ds_read_b128 v[144:147], v156
	ds_read_b128 v[148:151], v156 offset:1024
	ds_read_b128 v[152:155], v156 offset:2048
	ds_read_b128 v[156:159], v156 offset:3072
	s_add_u32 s22, s28, 0x80000
	s_addc_u32 s23, s29, 0
	s_mov_b32 m0, s27
	v_lshl_add_u64 v[222:223], s[22:23], 0, v[162:163]
	ds_read_b128 v[174:177], v205 offset:32768
	ds_read_b128 v[178:181], v205 offset:33792
	ds_read_b128 v[182:185], v205 offset:34816
	ds_read_b128 v[186:189], v205 offset:35840
	ds_read_b128 v[190:193], v205 offset:36864
	ds_read_b128 v[194:197], v205 offset:37888
	ds_read_b128 v[198:201], v205 offset:38912
	ds_read_b128 v[206:209], v205 offset:39936
	global_load_lds_dwordx4 v[222:223], off
	v_lshl_add_u64 v[222:223], s[22:23], 0, v[166:167]
	s_mov_b32 m0, s52
	s_nop 0
	global_load_lds_dwordx4 v[222:223], off
	s_waitcnt vmcnt(8)
	s_waitcnt lgkmcnt(0)
	s_barrier
	s_waitcnt lgkmcnt(0)
	v_mfma_f32_16x16x32_bf16 v[132:135], v[120:123], v[174:177], v[132:135]
	v_mfma_f32_16x16x32_bf16 v[132:135], v[124:127], v[178:181], v[132:135]
	v_mfma_f32_16x16x32_bf16 v[128:131], v[136:139], v[174:177], v[128:131]
	v_mfma_f32_16x16x32_bf16 v[128:131], v[140:143], v[178:181], v[128:131]
	v_mfma_f32_16x16x32_bf16 v[116:119], v[120:123], v[182:185], v[116:119]
	v_mfma_f32_16x16x32_bf16 v[116:119], v[124:127], v[186:189], v[116:119]
	v_mfma_f32_16x16x32_bf16 v[112:115], v[136:139], v[182:185], v[112:115]
	v_mfma_f32_16x16x32_bf16 v[112:115], v[140:143], v[186:189], v[112:115]
	v_mfma_f32_16x16x32_bf16 v[108:111], v[120:123], v[190:193], v[108:111]
	v_mfma_f32_16x16x32_bf16 v[108:111], v[124:127], v[194:197], v[108:111]
	v_mfma_f32_16x16x32_bf16 v[104:107], v[136:139], v[190:193], v[104:107]
	v_mfma_f32_16x16x32_bf16 v[104:107], v[140:143], v[194:197], v[104:107]
	v_mfma_f32_16x16x32_bf16 v[100:103], v[120:123], v[198:201], v[100:103]
	v_mfma_f32_16x16x32_bf16 v[100:103], v[124:127], v[206:209], v[100:103]
	v_mfma_f32_16x16x32_bf16 v[96:99], v[136:139], v[198:201], v[96:99]
	v_mfma_f32_16x16x32_bf16 v[96:99], v[140:143], v[206:209], v[96:99]
	v_mfma_f32_16x16x32_bf16 v[60:63], v[144:147], v[174:177], v[60:63]
	v_mfma_f32_16x16x32_bf16 v[60:63], v[148:151], v[178:181], v[60:63]
	v_mfma_f32_16x16x32_bf16 v[56:59], v[152:155], v[174:177], v[56:59]
	v_mfma_f32_16x16x32_bf16 v[56:59], v[156:159], v[178:181], v[56:59]
	v_mfma_f32_16x16x32_bf16 v[52:55], v[144:147], v[182:185], v[52:55]
	v_mfma_f32_16x16x32_bf16 v[52:55], v[148:151], v[186:189], v[52:55]
	v_mfma_f32_16x16x32_bf16 v[48:51], v[152:155], v[182:185], v[48:51]
	v_mfma_f32_16x16x32_bf16 v[48:51], v[156:159], v[186:189], v[48:51]
	v_mfma_f32_16x16x32_bf16 v[44:47], v[144:147], v[190:193], v[44:47]
	v_mfma_f32_16x16x32_bf16 v[44:47], v[148:151], v[194:197], v[44:47]
	v_mfma_f32_16x16x32_bf16 v[40:43], v[152:155], v[190:193], v[40:43]
	v_mfma_f32_16x16x32_bf16 v[40:43], v[156:159], v[194:197], v[40:43]
	v_mfma_f32_16x16x32_bf16 v[36:39], v[144:147], v[198:201], v[36:39]
	v_mfma_f32_16x16x32_bf16 v[36:39], v[148:151], v[206:209], v[36:39]
	v_mfma_f32_16x16x32_bf16 v[32:35], v[152:155], v[198:201], v[32:35]
	v_mfma_f32_16x16x32_bf16 v[32:35], v[156:159], v[206:209], v[32:35]
	s_barrier
; #define GAS __attribute__((address_space(1)))
; #define PG8_STAGE(bufoff, gbase, voff) do { _Pragma("unroll") for (int _i = 0; _i < 2; ++_i) \
;         __builtin_amdgcn_global_load_lds((const GAS unsigned*)((const GAS char*)(gbase) + (voff)[_i]), (PG8_LAS unsigned*)(lds + (bufoff) + ldsw + _i * 8192), 16, 0, 0); } while (0)
; #define PG8_LDA(dst, b, h) do { _Pragma("unroll") for (int m = 0; m < 4; ++m) _Pragma("unroll") for (int k = 0; k < 2; ++k) dst[m][k] = *(const PG8_LAS bf16x8*)(lds + PG8_SA(b, h) + aoff + m * 2048 + k * 1024); } while (0)
; #define PG8_MMA(ai, bj, At, Bt) do { __builtin_amdgcn_s_setprio(1); _Pragma("unroll") for (int m = 0; m < 4; ++m) _Pragma("unroll") for (int n = 0; n < 2; ++n) _Pragma("unroll") for (int k = 0; k < 2; ++k) \
;         acc[ai][bj][m][n] = __builtin_amdgcn_mfma_f32_16x16x32_bf16(Bt[n][k], At[m][k], acc[ai][bj][m][n], 0, 0, 0); __builtin_amdgcn_s_setprio(0); } while (0)
; #define PG8_WAIT_V(n) asm volatile("s_waitcnt vmcnt(" #n ")" ::: "memory")
; #define PG8_WAIT_L(n) asm volatile("s_waitcnt lgkmcnt(" #n ")" ::: "memory")
; #define PG8_BAR __builtin_amdgcn_s_barrier()
; #define PG8_SCHED __builtin_amdgcn_sched_barrier(0)
; #define PG8_STAGE(bufoff, gbase, voff) do { _Pragma("unroll") for (int _i = 0; _i < 2; ++_i) \
;         __builtin_amdgcn_global_load_lds((const GAS unsigned*)((const GAS char*)(gbase) + (voff)[_i]), (PG8_LAS unsigned*)(lds + (bufoff) + ldsw + _i * 8192), 16, 0, 0); } while (0)
; #define PG8_WAIT_V(n) asm volatile("s_waitcnt vmcnt(" #n ")" ::: "memory")
; #define PG8_BAR __builtin_amdgcn_s_barrier()
; template <class Epi, class Sched, bool ALIGN_EPI = false, bool SP2 = false>
; __device__ __forceinline__ void gemm_phase(PG8_LAS unsigned char* lds, PG8_LAS unsigned char* pf, const Gemm g, const Sched& S, const Epi& E, int wv) {
;     ...
;         for (int t = 0; t < ntu; t += 2) {
;             const bool last = (t == ntu - 2);
;             const GAS char* a1 = cA + (size_t)(t + 1) * kstep;
;             const GAS char* a2 = last ? nA : cA + (size_t)(t + 2) * kstep; const GAS char* b2 = last ? nB : cB + (size_t)(t + 2) * kstep;
;     ...
;             PG8_LDA(At, 1, 1); PG8_STAGE(PG8_SB(1, 0), b3, voffB); PG8_STAGE(PG8_SB(1, 1), b3 + hstepB, voffB); PG8_STAGE(PG8_SA(1, 0), a3, voffA);
;             PG8_WAIT_V(8); PG8_WAIT_L(0); PG8_BAR; PG8_MMA(1, 0, At, B0); PG8_MMA(1, 1, At, B1); PG8_BAR; PG8_SCHED;
	s_add_i32 s22, s24, s81
	v_lshl_add_u64 v[214:215], v[214:215], 0, s[16:17]
	s_mov_b32 m0, s22
	ds_read_b128 v[174:177], v205 offset:49152
	ds_read_b128 v[178:181], v205 offset:50176
	ds_read_b128 v[182:185], v205 offset:51200
	ds_read_b128 v[186:189], v205 offset:52224
	ds_read_b128 v[190:193], v205 offset:53248
	ds_read_b128 v[194:197], v205 offset:54272
	ds_read_b128 v[198:201], v205 offset:55296
	ds_read_b128 v[206:209], v205 offset:56320
	global_load_lds_dwordx4 v[214:215], off
	s_add_i32 m0, s22, 0x2000
	s_add_u32 s22, s36, 0x20080
	v_lshl_add_u64 v[214:215], v[216:217], 0, s[16:17]
	s_addc_u32 s23, s37, 0
	s_add_i32 s24, s25, s81
	global_load_lds_dwordx4 v[214:215], off
	v_lshl_add_u64 v[214:215], s[22:23], 0, v[164:165]
	s_mov_b32 m0, s24
	s_nop 0
	global_load_lds_dwordx4 v[214:215], off
	v_lshl_add_u64 v[214:215], s[22:23], 0, v[168:169]
	s_add_i32 m0, s24, 0x2000
	s_nop 0
	global_load_lds_dwordx4 v[214:215], off
	v_lshl_add_u64 v[214:215], v[218:219], 0, s[16:17]
	s_mov_b32 m0, s55
	s_nop 0
	global_load_lds_dwordx4 v[214:215], off
	v_lshl_add_u64 v[214:215], v[220:221], 0, s[16:17]
	s_mov_b32 m0, s56
	s_nop 0
	global_load_lds_dwordx4 v[214:215], off
	s_waitcnt vmcnt(8)
	s_waitcnt lgkmcnt(0)
	s_barrier
	s_waitcnt lgkmcnt(0)
	v_mfma_f32_16x16x32_bf16 v[92:95], v[120:123], v[174:177], v[92:95]
	v_mfma_f32_16x16x32_bf16 v[92:95], v[124:127], v[178:181], v[92:95]
	v_mfma_f32_16x16x32_bf16 v[88:91], v[136:139], v[174:177], v[88:91]
	v_mfma_f32_16x16x32_bf16 v[88:91], v[140:143], v[178:181], v[88:91]
	v_mfma_f32_16x16x32_bf16 v[84:87], v[120:123], v[182:185], v[84:87]
	v_mfma_f32_16x16x32_bf16 v[84:87], v[124:127], v[186:189], v[84:87]
	v_mfma_f32_16x16x32_bf16 v[80:83], v[136:139], v[182:185], v[80:83]
	v_mfma_f32_16x16x32_bf16 v[80:83], v[140:143], v[186:189], v[80:83]
	v_mfma_f32_16x16x32_bf16 v[76:79], v[120:123], v[190:193], v[76:79]
	v_mfma_f32_16x16x32_bf16 v[76:79], v[124:127], v[194:197], v[76:79]
	v_mfma_f32_16x16x32_bf16 v[72:75], v[136:139], v[190:193], v[72:75]
	v_mfma_f32_16x16x32_bf16 v[72:75], v[140:143], v[194:197], v[72:75]
	v_mfma_f32_16x16x32_bf16 v[68:71], v[120:123], v[198:201], v[68:71]
	v_mfma_f32_16x16x32_bf16 v[68:71], v[124:127], v[206:209], v[68:71]
	v_mfma_f32_16x16x32_bf16 v[64:67], v[136:139], v[198:201], v[64:67]
	v_mfma_f32_16x16x32_bf16 v[64:67], v[140:143], v[206:209], v[64:67]
	v_mfma_f32_16x16x32_bf16 v[28:31], v[144:147], v[174:177], v[28:31]
	v_mfma_f32_16x16x32_bf16 v[28:31], v[148:151], v[178:181], v[28:31]
	v_mfma_f32_16x16x32_bf16 v[24:27], v[152:155], v[174:177], v[24:27]
	v_mfma_f32_16x16x32_bf16 v[24:27], v[156:159], v[178:181], v[24:27]
	v_mfma_f32_16x16x32_bf16 v[20:23], v[144:147], v[182:185], v[20:23]
	v_mfma_f32_16x16x32_bf16 v[20:23], v[148:151], v[186:189], v[20:23]
	v_mfma_f32_16x16x32_bf16 v[16:19], v[152:155], v[182:185], v[16:19]
	v_mfma_f32_16x16x32_bf16 v[16:19], v[156:159], v[186:189], v[16:19]
	v_mfma_f32_16x16x32_bf16 v[12:15], v[144:147], v[190:193], v[12:15]
	v_mfma_f32_16x16x32_bf16 v[12:15], v[148:151], v[194:197], v[12:15]
	v_mfma_f32_16x16x32_bf16 v[8:11], v[152:155], v[190:193], v[8:11]
	v_mfma_f32_16x16x32_bf16 v[8:11], v[156:159], v[194:197], v[8:11]
	v_mfma_f32_16x16x32_bf16 v[4:7], v[144:147], v[198:201], v[4:7]
	v_mfma_f32_16x16x32_bf16 v[4:7], v[148:151], v[206:209], v[4:7]
	v_mfma_f32_16x16x32_bf16 v[0:3], v[152:155], v[198:201], v[0:3]
	v_mfma_f32_16x16x32_bf16 v[0:3], v[156:159], v[206:209], v[0:3]
	s_barrier
	s_add_i32 s21, s21, 2
	s_add_u32 s13, s13, 0x100
	s_addc_u32 s20, s20, 0
	s_add_u32 s14, s14, 0x100
	s_addc_u32 s15, s15, 0
	s_cmp_gt_u32 s21, 5
	s_cbranch_scc0 .LBB0_1186
	s_and_b64 vcc, exec, s[6:7]
	s_cbranch_vccz .LBB0_1189
	s_barrier

; #define PG8_STAGE(bufoff, gbase, voff) do { _Pragma("unroll") for (int _i = 0; _i < 2; ++_i) \
;         __builtin_amdgcn_global_load_lds((const GAS unsigned*)((const GAS char*)(gbase) + (voff)[_i]), (PG8_LAS unsigned*)(lds + (bufoff) + ldsw + _i * 8192), 16, 0, 0); } while (0)
; #define PG8_LDA(dst, b, h) do { _Pragma("unroll") for (int m = 0; m < 4; ++m) _Pragma("unroll") for (int k = 0; k < 2; ++k) dst[m][k] = *(const PG8_LAS bf16x8*)(lds + PG8_SA(b, h) + aoff + m * 2048 + k * 1024); } while (0)
; #define PG8_LDB(dst, b, h) do { _Pragma("unroll") for (int n = 0; n < 2; ++n) _Pragma("unroll") for (int k = 0; k < 2; ++k) dst[n][k] = *(const PG8_LAS bf16x8*)(lds + PG8_SB(b, h) + boff + n * 2048 + k * 1024); } while (0)
; #define PG8_MMA(ai, bj, At, Bt) do { __builtin_amdgcn_s_setprio(1); _Pragma("unroll") for (int m = 0; m < 4; ++m) _Pragma("unroll") for (int n = 0; n < 2; ++n) _Pragma("unroll") for (int k = 0; k < 2; ++k) \
;         acc[ai][bj][m][n] = __builtin_amdgcn_mfma_f32_16x16x32_bf16(Bt[n][k], At[m][k], acc[ai][bj][m][n], 0, 0, 0); __builtin_amdgcn_s_setprio(0); } while (0)
; #define PG8_WAIT_V(n) asm volatile("s_waitcnt vmcnt(" #n ")" ::: "memory")
; #define PG8_WAIT_L(n) asm volatile("s_waitcnt lgkmcnt(" #n ")" ::: "memory")
; #define PG8_BAR __builtin_amdgcn_s_barrier()
; #define PG8_SCHED __builtin_amdgcn_sched_barrier(0)
; #define PG8_STAGE(bufoff, gbase, voff) do { _Pragma("unroll") for (int _i = 0; _i < 2; ++_i) \
;         __builtin_amdgcn_global_load_lds((const GAS unsigned*)((const GAS char*)(gbase) + (voff)[_i]), (PG8_LAS unsigned*)(lds + (bufoff) + ldsw + _i * 8192), 16, 0, 0); } while (0)
; #define PG8_LDA(dst, b, h) do { _Pragma("unroll") for (int m = 0; m < 4; ++m) _Pragma("unroll") for (int k = 0; k < 2; ++k) dst[m][k] = *(const PG8_LAS bf16x8*)(lds + PG8_SA(b, h) + aoff + m * 2048 + k * 1024); } while (0)
; #define PG8_BAR __builtin_amdgcn_s_barrier()
; template <class Epi, class Sched>
; __device__ __forceinline__ void gemm_phase_strip(PG8_LAS unsigned char* lds, PG8_LAS unsigned char* slds, PG8_LAS unsigned char* pf, const Gemm g, const Sched& S, const Epi& E, int wv) {
;     ...
;             PG8_LDB(B0, 0, 0); PG8_LDB(B1, 0, 1); PG8_SCHED; PG8_LDA(At, 0, 0); PG8_STAGE(PG8_SA(1, 1), a1 + PG8_HS, voffA);
;             PG8_WAIT_V(8); PG8_WAIT_L(0); PG8_BAR; PG8_MMA(0, 0, At, B0); PG8_MMA(0, 1, At, B1); PG8_BAR; PG8_SCHED;
.LBB0_1305:
	s_add_u32 s23, s14, s52
	s_addc_u32 s24, s15, s53
	s_add_u32 s23, s23, 0x100
	s_addc_u32 s28, s24, 0
	s_add_u32 s31, s20, s52
	s_addc_u32 s38, s21, s53
	s_add_i32 s39, 0, 0x10000
	s_add_i32 s41, 0, 0x14000
	v_add_u32_e32 v128, s39, v233
	ds_read_b128 v[148:151], v128
	ds_read_b128 v[144:147], v128 offset:1024
	ds_read_b128 v[166:169], v128 offset:2048
	ds_read_b128 v[162:165], v128 offset:3072
	v_add_u32_e32 v128, s41, v233
	ds_read_b128 v[156:159], v128
	ds_read_b128 v[152:155], v128 offset:1024
	ds_read_b128 v[174:177], v128 offset:2048
	ds_read_b128 v[170:173], v128 offset:3072
	s_cmpk_eq_i32 s52, 0xf00
	s_cselect_b64 s[56:57], -1, 0
	s_and_b64 s[24:25], s[56:57], exec
	s_cselect_b32 s29, s43, s28
	s_cselect_b32 s28, s42, s23
	s_cselect_b32 s55, s1, s38
	s_cselect_b32 s54, s5, s31
	v_lshl_add_u64 v[222:223], v[220:221], 0, s[52:53]
	s_add_i32 m0, s64, 0xc000
	ds_read_b128 v[128:131], v236
	ds_read_b128 v[136:139], v236 offset:1024
	ds_read_b128 v[178:181], v236 offset:2048
	ds_read_b128 v[182:185], v236 offset:3072
	ds_read_b128 v[186:189], v236 offset:4096
	ds_read_b128 v[190:193], v236 offset:5120
	ds_read_b128 v[194:197], v236 offset:6144
	ds_read_b128 v[198:201], v236 offset:7168
	global_load_lds_dwordx4 v[222:223], off
	v_lshl_add_u64 v[222:223], v[218:219], 0, s[52:53]
	s_add_i32 m0, s64, 0xe000
	s_nop 0
	global_load_lds_dwordx4 v[222:223], off
	s_waitcnt vmcnt(8)
	s_waitcnt lgkmcnt(0)
	s_barrier
	s_waitcnt lgkmcnt(0)
	v_mfma_f32_16x16x32_bf16 v[140:143], v[148:151], v[128:131], v[140:143]
	v_mfma_f32_16x16x32_bf16 v[140:143], v[144:147], v[136:139], v[140:143]
	v_mfma_f32_16x16x32_bf16 v[132:135], v[166:169], v[128:131], v[132:135]
	v_mfma_f32_16x16x32_bf16 v[132:135], v[162:165], v[136:139], v[132:135]
	v_mfma_f32_16x16x32_bf16 v[124:127], v[148:151], v[178:181], v[124:127]
	v_mfma_f32_16x16x32_bf16 v[124:127], v[144:147], v[182:185], v[124:127]
	v_mfma_f32_16x16x32_bf16 v[120:123], v[166:169], v[178:181], v[120:123]
	v_mfma_f32_16x16x32_bf16 v[120:123], v[162:165], v[182:185], v[120:123]
	v_mfma_f32_16x16x32_bf16 v[116:119], v[148:151], v[186:189], v[116:119]
	v_mfma_f32_16x16x32_bf16 v[116:119], v[144:147], v[190:193], v[116:119]
	v_mfma_f32_16x16x32_bf16 v[112:115], v[166:169], v[186:189], v[112:115]
	v_mfma_f32_16x16x32_bf16 v[112:115], v[162:165], v[190:193], v[112:115]
	v_mfma_f32_16x16x32_bf16 v[108:111], v[148:151], v[194:197], v[108:111]
	v_mfma_f32_16x16x32_bf16 v[108:111], v[144:147], v[198:201], v[108:111]
	v_mfma_f32_16x16x32_bf16 v[104:107], v[166:169], v[194:197], v[104:107]
	v_mfma_f32_16x16x32_bf16 v[104:107], v[162:165], v[198:201], v[104:107]
	v_mfma_f32_16x16x32_bf16 v[68:71], v[156:159], v[128:131], v[68:71]
	v_mfma_f32_16x16x32_bf16 v[68:71], v[152:155], v[136:139], v[68:71]
	v_mfma_f32_16x16x32_bf16 v[64:67], v[174:177], v[128:131], v[64:67]
	v_mfma_f32_16x16x32_bf16 v[64:67], v[170:173], v[136:139], v[64:67]
	v_mfma_f32_16x16x32_bf16 v[60:63], v[156:159], v[178:181], v[60:63]
	v_mfma_f32_16x16x32_bf16 v[60:63], v[152:155], v[182:185], v[60:63]
	v_mfma_f32_16x16x32_bf16 v[56:59], v[174:177], v[178:181], v[56:59]
	v_mfma_f32_16x16x32_bf16 v[56:59], v[170:173], v[182:185], v[56:59]
	v_mfma_f32_16x16x32_bf16 v[52:55], v[156:159], v[186:189], v[52:55]
	v_mfma_f32_16x16x32_bf16 v[52:55], v[152:155], v[190:193], v[52:55]
	v_mfma_f32_16x16x32_bf16 v[48:51], v[174:177], v[186:189], v[48:51]
	v_mfma_f32_16x16x32_bf16 v[48:51], v[170:173], v[190:193], v[48:51]
	v_mfma_f32_16x16x32_bf16 v[44:47], v[156:159], v[194:197], v[44:47]
	v_mfma_f32_16x16x32_bf16 v[44:47], v[152:155], v[198:201], v[44:47]
	v_mfma_f32_16x16x32_bf16 v[40:43], v[174:177], v[194:197], v[40:43]
	v_mfma_f32_16x16x32_bf16 v[40:43], v[170:173], v[198:201], v[40:43]
	s_barrier
; #define PG8_STAGE(bufoff, gbase, voff) do { _Pragma("unroll") for (int _i = 0; _i < 2; ++_i) \
;         __builtin_amdgcn_global_load_lds((const GAS unsigned*)((const GAS char*)(gbase) + (voff)[_i]), (PG8_LAS unsigned*)(lds + (bufoff) + ldsw + _i * 8192), 16, 0, 0); } while (0)
; #define PG8_LDA(dst, b, h) do { _Pragma("unroll") for (int m = 0; m < 4; ++m) _Pragma("unroll") for (int k = 0; k < 2; ++k) dst[m][k] = *(const PG8_LAS bf16x8*)(lds + PG8_SA(b, h) + aoff + m * 2048 + k * 1024); } while (0)
; #define PG8_MMA(ai, bj, At, Bt) do { __builtin_amdgcn_s_setprio(1); _Pragma("unroll") for (int m = 0; m < 4; ++m) _Pragma("unroll") for (int n = 0; n < 2; ++n) _Pragma("unroll") for (int k = 0; k < 2; ++k) \
;         acc[ai][bj][m][n] = __builtin_amdgcn_mfma_f32_16x16x32_bf16(Bt[n][k], At[m][k], acc[ai][bj][m][n], 0, 0, 0); __builtin_amdgcn_s_setprio(0); } while (0)
; #define PG8_WAIT_V(n) asm volatile("s_waitcnt vmcnt(" #n ")" ::: "memory")
; #define PG8_WAIT_L(n) asm volatile("s_waitcnt lgkmcnt(" #n ")" ::: "memory")
; #define PG8_BAR __builtin_amdgcn_s_barrier()
; #define PG8_SCHED __builtin_amdgcn_sched_barrier(0)
; #define PG8_STAGE(bufoff, gbase, voff) do { _Pragma("unroll") for (int _i = 0; _i < 2; ++_i) \
;         __builtin_amdgcn_global_load_lds((const GAS unsigned*)((const GAS char*)(gbase) + (voff)[_i]), (PG8_LAS unsigned*)(lds + (bufoff) + ldsw + _i * 8192), 16, 0, 0); } while (0)
; #define PG8_LDA(dst, b, h) do { _Pragma("unroll") for (int m = 0; m < 4; ++m) _Pragma("unroll") for (int k = 0; k < 2; ++k) dst[m][k] = *(const PG8_LAS bf16x8*)(lds + PG8_SA(b, h) + aoff + m * 2048 + k * 1024); } while (0)
; #define PG8_LDS_S(dst, boffs) do { dst[0] = *(const PG8_LAS bf16x8*)(slds + (boffs) + soff0); dst[1] = *(const PG8_LAS bf16x8*)(slds + (boffs) + (soff0 ^ 64)); } while (0)
; #define PG8_BAR __builtin_amdgcn_s_barrier()
; template <class Epi, class Sched>
; __device__ __forceinline__ void gemm_phase_strip(PG8_LAS unsigned char* lds, PG8_LAS unsigned char* slds, PG8_LAS unsigned char* pf, const Gemm g, const Sched& S, const Epi& E, int wv) {
;     ...
;             PG8_LDA(At, 0, 1); PG8_LDS_S(As, sq); PG8_STAGE(PG8_SB(0, 0), b2, voffB); PG8_STAGE(PG8_SB(0, 1), b2 + hstepB, voffB); PG8_STAGE(PG8_SA(0, 0), a2, voffA);
;             PG8_WAIT_V(8); PG8_WAIT_L(0); PG8_BAR; PG8_MMA(1, 0, At, B0); PG8_MMA(1, 1, At, B1); PG8_MMA_S(); PG8_BAR; PG8_SCHED;
	s_add_i32 s23, s91, 0
	s_add_i32 s23, s23, 0x21000
	v_add_u32_e32 v160, s23, v234
	v_add_u32_e32 v237, s23, v235
	s_add_i32 s23, s39, s62
	v_lshl_add_u64 v[222:223], s[54:55], 0, v[204:205]
	s_mov_b32 m0, s23
	ds_read_b128 v[128:131], v236 offset:16384
	ds_read_b128 v[136:139], v236 offset:17408
	ds_read_b128 v[186:189], v236 offset:18432
	ds_read_b128 v[190:193], v236 offset:19456
	ds_read_b128 v[194:197], v236 offset:20480
	ds_read_b128 v[198:201], v236 offset:21504
	ds_read_b128 v[242:245], v236 offset:22528
	ds_read_b128 v[246:249], v236 offset:23552
	ds_read_b128 v[182:185], v160
	ds_read_b128 v[178:181], v237
	global_load_lds_dwordx4 v[222:223], off
	s_add_i32 m0, s23, 0x2000
	s_add_u32 s24, s54, 0x80000
	v_lshl_add_u64 v[224:225], s[54:55], 0, v[208:209]
	s_addc_u32 s25, s55, 0
	s_add_i32 s23, s41, s62
	global_load_lds_dwordx4 v[224:225], off
	v_lshl_add_u64 v[226:227], s[24:25], 0, v[204:205]
	s_mov_b32 m0, s23
	v_lshl_add_u64 v[228:229], s[28:29], 0, v[206:207]
	global_load_lds_dwordx4 v[226:227], off
	v_lshl_add_u64 v[226:227], s[24:25], 0, v[208:209]
	s_add_i32 m0, s23, 0x2000
	s_nop 0
	global_load_lds_dwordx4 v[226:227], off
	v_lshl_add_u64 v[226:227], s[28:29], 0, v[202:203]
	s_mov_b32 m0, s64
	s_nop 0
	global_load_lds_dwordx4 v[226:227], off
	s_mov_b32 m0, s65
	s_nop 0
	global_load_lds_dwordx4 v[228:229], off
	s_waitcnt vmcnt(8)
	s_waitcnt lgkmcnt(0)
	s_barrier
	s_waitcnt lgkmcnt(0)
	v_mfma_f32_16x16x32_bf16 v[100:103], v[148:151], v[128:131], v[100:103]
	v_mfma_f32_16x16x32_bf16 v[100:103], v[144:147], v[136:139], v[100:103]
	v_mfma_f32_16x16x32_bf16 v[96:99], v[166:169], v[128:131], v[96:99]
	v_mfma_f32_16x16x32_bf16 v[96:99], v[162:165], v[136:139], v[96:99]
	v_mfma_f32_16x16x32_bf16 v[92:95], v[148:151], v[186:189], v[92:95]
	v_mfma_f32_16x16x32_bf16 v[92:95], v[144:147], v[190:193], v[92:95]
	v_mfma_f32_16x16x32_bf16 v[88:91], v[166:169], v[186:189], v[88:91]
	v_mfma_f32_16x16x32_bf16 v[88:91], v[162:165], v[190:193], v[88:91]
	v_mfma_f32_16x16x32_bf16 v[84:87], v[148:151], v[194:197], v[84:87]
	v_mfma_f32_16x16x32_bf16 v[84:87], v[144:147], v[198:201], v[84:87]
	v_mfma_f32_16x16x32_bf16 v[80:83], v[166:169], v[194:197], v[80:83]
	v_mfma_f32_16x16x32_bf16 v[80:83], v[162:165], v[198:201], v[80:83]
	v_mfma_f32_16x16x32_bf16 v[76:79], v[148:151], v[242:245], v[76:79]
	v_mfma_f32_16x16x32_bf16 v[76:79], v[144:147], v[246:249], v[76:79]
	v_mfma_f32_16x16x32_bf16 v[72:75], v[166:169], v[242:245], v[72:75]
	v_mfma_f32_16x16x32_bf16 v[72:75], v[162:165], v[246:249], v[72:75]
	v_mfma_f32_16x16x32_bf16 v[36:39], v[156:159], v[128:131], v[36:39]
	v_mfma_f32_16x16x32_bf16 v[36:39], v[152:155], v[136:139], v[36:39]
	v_mfma_f32_16x16x32_bf16 v[32:35], v[174:177], v[128:131], v[32:35]
	v_mfma_f32_16x16x32_bf16 v[32:35], v[170:173], v[136:139], v[32:35]
	v_mfma_f32_16x16x32_bf16 v[28:31], v[156:159], v[186:189], v[28:31]
	v_mfma_f32_16x16x32_bf16 v[28:31], v[152:155], v[190:193], v[28:31]
	v_mfma_f32_16x16x32_bf16 v[24:27], v[174:177], v[186:189], v[24:27]
	v_mfma_f32_16x16x32_bf16 v[24:27], v[170:173], v[190:193], v[24:27]
	v_mfma_f32_16x16x32_bf16 v[20:23], v[156:159], v[194:197], v[20:23]
	v_mfma_f32_16x16x32_bf16 v[20:23], v[152:155], v[198:201], v[20:23]
	v_mfma_f32_16x16x32_bf16 v[16:19], v[174:177], v[194:197], v[16:19]
	v_mfma_f32_16x16x32_bf16 v[16:19], v[170:173], v[198:201], v[16:19]
	v_mfma_f32_16x16x32_bf16 v[12:15], v[156:159], v[242:245], v[12:15]
	v_mfma_f32_16x16x32_bf16 v[12:15], v[152:155], v[246:249], v[12:15]
	v_mfma_f32_16x16x32_bf16 v[8:11], v[174:177], v[242:245], v[8:11]
	v_mfma_f32_16x16x32_bf16 v[8:11], v[170:173], v[246:249], v[8:11]
	v_cndmask_b32_e64 v128, 0, 1, s[8:9]
	v_cmp_ne_u32_e64 s[38:39], 1, v128
	s_andn2_b64 vcc, exec, s[8:9]
	s_mov_b64 s[58:59], -1
	s_cbranch_vccnz .LBB0_1307
	v_mfma_f32_16x16x32_bf16 v[128:131], v[166:169], v[182:185], v[4:7]
	s_mov_b64 s[58:59], 0
	v_mfma_f32_16x16x32_bf16 v[136:139], v[174:177], v[182:185], v[0:3]
	v_mfma_f32_16x16x32_bf16 v[128:131], v[162:165], v[178:181], v[128:131]
	v_mfma_f32_16x16x32_bf16 v[136:139], v[170:173], v[178:181], v[136:139]

; #define PG8_STAGE(bufoff, gbase, voff) do { _Pragma("unroll") for (int _i = 0; _i < 2; ++_i) \
;         __builtin_amdgcn_global_load_lds((const GAS unsigned*)((const GAS char*)(gbase) + (voff)[_i]), (PG8_LAS unsigned*)(lds + (bufoff) + ldsw + _i * 8192), 16, 0, 0); } while (0)
; #define PG8_LDA(dst, b, h) do { _Pragma("unroll") for (int m = 0; m < 4; ++m) _Pragma("unroll") for (int k = 0; k < 2; ++k) dst[m][k] = *(const PG8_LAS bf16x8*)(lds + PG8_SA(b, h) + aoff + m * 2048 + k * 1024); } while (0)
; #define PG8_LDB(dst, b, h) do { _Pragma("unroll") for (int n = 0; n < 2; ++n) _Pragma("unroll") for (int k = 0; k < 2; ++k) dst[n][k] = *(const PG8_LAS bf16x8*)(lds + PG8_SB(b, h) + boff + n * 2048 + k * 1024); } while (0)
; #define PG8_MMA(ai, bj, At, Bt) do { __builtin_amdgcn_s_setprio(1); _Pragma("unroll") for (int m = 0; m < 4; ++m) _Pragma("unroll") for (int n = 0; n < 2; ++n) _Pragma("unroll") for (int k = 0; k < 2; ++k) \
;         acc[ai][bj][m][n] = __builtin_amdgcn_mfma_f32_16x16x32_bf16(Bt[n][k], At[m][k], acc[ai][bj][m][n], 0, 0, 0); __builtin_amdgcn_s_setprio(0); } while (0)
; #define PG8_WAIT_V(n) asm volatile("s_waitcnt vmcnt(" #n ")" ::: "memory")
; #define PG8_WAIT_L(n) asm volatile("s_waitcnt lgkmcnt(" #n ")" ::: "memory")
; #define PG8_BAR __builtin_amdgcn_s_barrier()
; #define PG8_SCHED __builtin_amdgcn_sched_barrier(0)
; #define PG8_WAIT_V(n) asm volatile("s_waitcnt vmcnt(" #n ")" ::: "memory")
; #define PG8_BAR __builtin_amdgcn_s_barrier()
; template <class Epi, class Sched>
; __device__ __forceinline__ void gemm_phase_strip(PG8_LAS unsigned char* lds, PG8_LAS unsigned char* slds, PG8_LAS unsigned char* pf, const Gemm g, const Sched& S, const Epi& E, int wv) {
;     ...
;             PG8_LDB(B0, 1, 0); PG8_LDB(B1, 1, 1); PG8_SCHED; PG8_LDA(At, 1, 0); PG8_STAGE(PG8_SA(0, 1), a2 + (Sched::SPLIT ? ((last && has_next) ? (nxt.kh > 0 ? -(long)hstepA : (long)hstepA) : hsA) : (long)hstepA), voffA); PG8_STAGE_S(sq ^ 4096u, s2);
;             PG8_WAIT_V(9); PG8_WAIT_L(0); PG8_BAR; PG8_MMA(0, 0, At, B0); PG8_MMA(0, 1, At, B1); PG8_BAR; PG8_SCHED;
;             PG8_LDA(At, 1, 1); PG8_LDS_S(As, sq + 2048u); PG8_STAGE(PG8_SB(1, 0), b3, voffB); PG8_STAGE(PG8_SB(1, 1), b3 + hstepB, voffB); PG8_STAGE(PG8_SA(1, 0), a3, voffA);
;             PG8_WAIT_V(9); PG8_WAIT_L(0); PG8_BAR; PG8_MMA(1, 0, At, B0); PG8_MMA(1, 1, At, B1); PG8_MMA_S(); PG8_BAR; PG8_SCHED;
.LBB0_1311:
	s_or_b64 exec, exec, s[28:29]
	s_waitcnt vmcnt(9)
	s_waitcnt lgkmcnt(0)
	s_barrier
	s_waitcnt lgkmcnt(0)
	v_mfma_f32_16x16x32_bf16 v[140:143], v[148:151], v[194:197], v[140:143]
	v_mfma_f32_16x16x32_bf16 v[140:143], v[144:147], v[198:201], v[140:143]
	v_mfma_f32_16x16x32_bf16 v[132:135], v[166:169], v[194:197], v[132:135]
	v_mfma_f32_16x16x32_bf16 v[132:135], v[162:165], v[198:201], v[132:135]
	v_mfma_f32_16x16x32_bf16 v[124:127], v[148:151], v[186:189], v[124:127]
	v_mfma_f32_16x16x32_bf16 v[124:127], v[144:147], v[190:193], v[124:127]
	v_mfma_f32_16x16x32_bf16 v[120:123], v[166:169], v[186:189], v[120:123]
	v_mfma_f32_16x16x32_bf16 v[120:123], v[162:165], v[190:193], v[120:123]
	v_mfma_f32_16x16x32_bf16 v[116:119], v[148:151], v[178:181], v[116:119]
	v_mfma_f32_16x16x32_bf16 v[116:119], v[144:147], v[182:185], v[116:119]
	v_mfma_f32_16x16x32_bf16 v[112:115], v[166:169], v[178:181], v[112:115]
	v_mfma_f32_16x16x32_bf16 v[112:115], v[162:165], v[182:185], v[112:115]
	v_mfma_f32_16x16x32_bf16 v[108:111], v[148:151], v[0:3], v[108:111]
	v_mfma_f32_16x16x32_bf16 v[108:111], v[144:147], v[4:7], v[108:111]
	v_mfma_f32_16x16x32_bf16 v[104:107], v[166:169], v[0:3], v[104:107]
	v_mfma_f32_16x16x32_bf16 v[104:107], v[162:165], v[4:7], v[104:107]
	v_mfma_f32_16x16x32_bf16 v[68:71], v[156:159], v[194:197], v[68:71]
	v_mfma_f32_16x16x32_bf16 v[64:67], v[174:177], v[194:197], v[64:67]
	v_mfma_f32_16x16x32_bf16 v[60:63], v[156:159], v[186:189], v[60:63]
	v_mfma_f32_16x16x32_bf16 v[56:59], v[174:177], v[186:189], v[56:59]
	v_mfma_f32_16x16x32_bf16 v[52:55], v[156:159], v[178:181], v[52:55]
	v_mfma_f32_16x16x32_bf16 v[48:51], v[174:177], v[178:181], v[48:51]
	v_mfma_f32_16x16x32_bf16 v[44:47], v[156:159], v[0:3], v[44:47]
	v_mfma_f32_16x16x32_bf16 v[0:3], v[174:177], v[0:3], v[40:43]
	v_mfma_f32_16x16x32_bf16 v[68:71], v[152:155], v[198:201], v[68:71]
	v_mfma_f32_16x16x32_bf16 v[64:67], v[170:173], v[198:201], v[64:67]
	v_mfma_f32_16x16x32_bf16 v[60:63], v[152:155], v[190:193], v[60:63]
	v_mfma_f32_16x16x32_bf16 v[56:59], v[170:173], v[190:193], v[56:59]
	v_mfma_f32_16x16x32_bf16 v[52:55], v[152:155], v[182:185], v[52:55]
	v_mfma_f32_16x16x32_bf16 v[48:51], v[170:173], v[182:185], v[48:51]
	v_mfma_f32_16x16x32_bf16 v[44:47], v[152:155], v[4:7], v[44:47]
	v_mfma_f32_16x16x32_bf16 v[40:43], v[170:173], v[4:7], v[0:3]
	s_barrier
	s_mov_b32 m0, s76
	v_lshl_add_u64 v[222:223], v[222:223], 0, s[16:17]
	s_add_u32 s24, s54, 0x80080
	ds_read_b128 v[0:3], v236 offset:49152
	ds_read_b128 v[4:7], v236 offset:50176
	ds_read_b128 v[186:189], v236 offset:51200
	ds_read_b128 v[190:193], v236 offset:52224
	ds_read_b128 v[194:197], v236 offset:53248
	ds_read_b128 v[198:201], v236 offset:54272
	ds_read_b128 v[242:245], v236 offset:55296
	ds_read_b128 v[246:249], v236 offset:56320
	ds_read_b128 v[182:185], v160 offset:2048
	ds_read_b128 v[178:181], v237 offset:2048
	global_load_lds_dwordx4 v[222:223], off
	v_lshl_add_u64 v[222:223], v[224:225], 0, s[16:17]
	s_mov_b32 m0, s77
	s_addc_u32 s25, s55, 0
	global_load_lds_dwordx4 v[222:223], off
	v_lshl_add_u64 v[222:223], s[24:25], 0, v[204:205]
	s_mov_b32 m0, s80
	s_nop 0
	global_load_lds_dwordx4 v[222:223], off
	v_lshl_add_u64 v[222:223], s[24:25], 0, v[208:209]
	s_mov_b32 m0, s81
	s_nop 0
	global_load_lds_dwordx4 v[222:223], off
	v_lshl_add_u64 v[222:223], v[226:227], 0, s[16:17]
	s_mov_b32 m0, s78
	s_nop 0
	global_load_lds_dwordx4 v[222:223], off
	v_lshl_add_u64 v[222:223], v[228:229], 0, s[16:17]
	s_mov_b32 m0, s79
	s_nop 0
	global_load_lds_dwordx4 v[222:223], off
	s_waitcnt vmcnt(9)
	s_waitcnt lgkmcnt(0)
	s_barrier
	s_waitcnt lgkmcnt(0)
	v_mfma_f32_16x16x32_bf16 v[100:103], v[148:151], v[0:3], v[100:103]
	v_mfma_f32_16x16x32_bf16 v[100:103], v[144:147], v[4:7], v[100:103]
	v_mfma_f32_16x16x32_bf16 v[96:99], v[166:169], v[0:3], v[96:99]
	v_mfma_f32_16x16x32_bf16 v[96:99], v[162:165], v[4:7], v[96:99]
	v_mfma_f32_16x16x32_bf16 v[92:95], v[148:151], v[186:189], v[92:95]
	v_mfma_f32_16x16x32_bf16 v[92:95], v[144:147], v[190:193], v[92:95]
	v_mfma_f32_16x16x32_bf16 v[88:91], v[166:169], v[186:189], v[88:91]
	v_mfma_f32_16x16x32_bf16 v[88:91], v[162:165], v[190:193], v[88:91]
	v_mfma_f32_16x16x32_bf16 v[84:87], v[148:151], v[194:197], v[84:87]
	v_mfma_f32_16x16x32_bf16 v[84:87], v[144:147], v[198:201], v[84:87]
	v_mfma_f32_16x16x32_bf16 v[80:83], v[166:169], v[194:197], v[80:83]
	v_mfma_f32_16x16x32_bf16 v[80:83], v[162:165], v[198:201], v[80:83]
	v_mfma_f32_16x16x32_bf16 v[76:79], v[148:151], v[242:245], v[76:79]
	v_mfma_f32_16x16x32_bf16 v[76:79], v[144:147], v[246:249], v[76:79]
	v_mfma_f32_16x16x32_bf16 v[72:75], v[166:169], v[242:245], v[72:75]
	v_mfma_f32_16x16x32_bf16 v[72:75], v[162:165], v[246:249], v[72:75]
	v_mfma_f32_16x16x32_bf16 v[36:39], v[156:159], v[0:3], v[36:39]
	v_mfma_f32_16x16x32_bf16 v[0:3], v[174:177], v[0:3], v[32:35]
	v_mfma_f32_16x16x32_bf16 v[32:35], v[170:173], v[4:7], v[0:3]
	v_mfma_f32_16x16x32_bf16 v[0:3], v[156:159], v[186:189], v[28:31]
	v_mfma_f32_16x16x32_bf16 v[28:31], v[152:155], v[190:193], v[0:3]
	v_mfma_f32_16x16x32_bf16 v[0:3], v[174:177], v[186:189], v[24:27]
	v_mfma_f32_16x16x32_bf16 v[24:27], v[170:173], v[190:193], v[0:3]
	v_mfma_f32_16x16x32_bf16 v[0:3], v[156:159], v[194:197], v[20:23]
	v_mfma_f32_16x16x32_bf16 v[20:23], v[152:155], v[198:201], v[0:3]
	v_mfma_f32_16x16x32_bf16 v[0:3], v[174:177], v[194:197], v[16:19]
	v_mfma_f32_16x16x32_bf16 v[16:19], v[170:173], v[198:201], v[0:3]
	v_mfma_f32_16x16x32_bf16 v[0:3], v[156:159], v[242:245], v[12:15]
	v_mfma_f32_16x16x32_bf16 v[12:15], v[152:155], v[246:249], v[0:3]
	v_mfma_f32_16x16x32_bf16 v[0:3], v[174:177], v[242:245], v[8:11]
	v_mfma_f32_16x16x32_bf16 v[36:39], v[152:155], v[4:7], v[36:39]
	v_mfma_f32_16x16x32_bf16 v[8:11], v[170:173], v[246:249], v[0:3]
	s_and_b64 vcc, exec, s[38:39]
	s_mov_b64 s[28:29], -1
	s_cbranch_vccnz .LBB0_1313
	v_mfma_f32_16x16x32_bf16 v[0:3], v[166:169], v[182:185], v[128:131]
	s_mov_b64 s[28:29], 0
	v_mfma_f32_16x16x32_bf16 v[166:169], v[174:177], v[182:185], v[136:139]
	v_mfma_f32_16x16x32_bf16 v[4:7], v[162:165], v[178:181], v[0:3]
	v_mfma_f32_16x16x32_bf16 v[0:3], v[170:173], v[178:181], v[166:169]

; #define PG8_STAGE(bufoff, gbase, voff) do { _Pragma("unroll") for (int _i = 0; _i < 2; ++_i) \
;         __builtin_amdgcn_global_load_lds((const GAS unsigned*)((const GAS char*)(gbase) + (voff)[_i]), (PG8_LAS unsigned*)(lds + (bufoff) + ldsw + _i * 8192), 16, 0, 0); } while (0)
; #define PG8_LDA(dst, b, h) do { _Pragma("unroll") for (int m = 0; m < 4; ++m) _Pragma("unroll") for (int k = 0; k < 2; ++k) dst[m][k] = *(const PG8_LAS bf16x8*)(lds + PG8_SA(b, h) + aoff + m * 2048 + k * 1024); } while (0)
; #define PG8_LDB(dst, b, h) do { _Pragma("unroll") for (int n = 0; n < 2; ++n) _Pragma("unroll") for (int k = 0; k < 2; ++k) dst[n][k] = *(const PG8_LAS bf16x8*)(lds + PG8_SB(b, h) + boff + n * 2048 + k * 1024); } while (0)
; #define PG8_MMA(ai, bj, At, Bt) do { __builtin_amdgcn_s_setprio(1); _Pragma("unroll") for (int m = 0; m < 4; ++m) _Pragma("unroll") for (int n = 0; n < 2; ++n) _Pragma("unroll") for (int k = 0; k < 2; ++k) \
;         acc[ai][bj][m][n] = __builtin_amdgcn_mfma_f32_16x16x32_bf16(Bt[n][k], At[m][k], acc[ai][bj][m][n], 0, 0, 0); __builtin_amdgcn_s_setprio(0); } while (0)
; #define PG8_WAIT_V(n) asm volatile("s_waitcnt vmcnt(" #n ")" ::: "memory")
; #define PG8_WAIT_L(n) asm volatile("s_waitcnt lgkmcnt(" #n ")" ::: "memory")
; #define PG8_BAR __builtin_amdgcn_s_barrier()
; #define PG8_SCHED __builtin_amdgcn_sched_barrier(0)
; #define PG8_LDA(dst, b, h) do { _Pragma("unroll") for (int m = 0; m < 4; ++m) _Pragma("unroll") for (int k = 0; k < 2; ++k) dst[m][k] = *(const PG8_LAS bf16x8*)(lds + PG8_SA(b, h) + aoff + m * 2048 + k * 1024); } while (0)
; template <class Epi, class Sched, bool ALIGN_EPI = false, bool SP2 = false>
; __device__ __forceinline__ void gemm_phase(PG8_LAS unsigned char* lds, PG8_LAS unsigned char* pf, const Gemm g, const Sched& S, const Epi& E, int wv) {
;     ...
;             PG8_LDB(B0, 0, 0); PG8_LDB(B1, 0, 1); PG8_SCHED; PG8_LDA(At, 0, 0); PG8_STAGE(PG8_SA(1, 1), a1 + (Sched::SPLIT ? hsA : (long)hstepA), voffA);
;             PG8_WAIT_V(8); PG8_WAIT_L(0); PG8_BAR; PG8_MMA(0, 0, At, B0); PG8_MMA(0, 1, At, B1); PG8_BAR; PG8_SCHED;
;             PG8_LDA(At, 0, 1); PG8_STAGE(PG8_SB(0, 0), b2, voffB); PG8_STAGE(PG8_SB(0, 1), b2 + hstepB, voffB); PG8_STAGE(PG8_SA(0, 0), a2, voffA);
;             PG8_WAIT_V(8); PG8_WAIT_L(0); PG8_BAR; PG8_MMA(1, 0, At, B0); PG8_MMA(1, 1, At, B1); PG8_BAR; PG8_SCHED;
.LBB0_1414:
	s_add_u32 s25, s36, 0xfff80080
	s_addc_u32 s28, s37, -1
	s_add_i32 s42, 0, 0x10000
	s_cmp_eq_u32 s24, 28
	s_cselect_b32 s29, s13, s28
	s_cselect_b32 s28, s12, s25
	s_cselect_b32 s41, s9, s23
	s_cselect_b32 s40, s11, s22
	s_add_i32 s25, 0, 0x14000
	v_add_u32_e32 v132, s42, v159
	v_add_u32_e32 v160, s25, v159
	ds_read_b128 v[120:123], v132
	ds_read_b128 v[124:127], v132 offset:1024
	ds_read_b128 v[128:131], v132 offset:2048
	ds_read_b128 v[132:135], v132 offset:3072
	ds_read_b128 v[164:167], v160
	ds_read_b128 v[168:171], v160 offset:1024
	ds_read_b128 v[172:175], v160 offset:2048
	ds_read_b128 v[176:179], v160 offset:3072
	v_lshl_add_u64 v[208:209], s[36:37], 0, v[154:155]
	s_add_i32 m0, s1, 0xc000
	ds_read_b128 v[180:183], v162
	ds_read_b128 v[184:187], v162 offset:1024
	ds_read_b128 v[188:191], v162 offset:2048
	ds_read_b128 v[192:195], v162 offset:3072
	ds_read_b128 v[196:199], v162 offset:4096
	ds_read_b128 v[200:203], v162 offset:5120
	ds_read_b128 v[204:207], v162 offset:6144
	ds_read_b128 v[214:217], v162 offset:7168
	global_load_lds_dwordx4 v[208:209], off
	v_lshl_add_u64 v[208:209], s[36:37], 0, v[152:153]
	s_add_i32 m0, s1, 0xe000
	s_nop 0
	global_load_lds_dwordx4 v[208:209], off
	s_waitcnt vmcnt(8)
	s_waitcnt lgkmcnt(0)
	s_barrier
	s_waitcnt lgkmcnt(0)
	v_mfma_f32_16x16x32_bf16 v[140:143], v[120:123], v[180:183], v[140:143]
	v_mfma_f32_16x16x32_bf16 v[140:143], v[124:127], v[184:187], v[140:143]
	v_mfma_f32_16x16x32_bf16 v[136:139], v[128:131], v[180:183], v[136:139]
	v_mfma_f32_16x16x32_bf16 v[136:139], v[132:135], v[184:187], v[136:139]
	v_mfma_f32_16x16x32_bf16 v[108:111], v[120:123], v[188:191], v[108:111]
	v_mfma_f32_16x16x32_bf16 v[108:111], v[124:127], v[192:195], v[108:111]
	v_mfma_f32_16x16x32_bf16 v[104:107], v[128:131], v[188:191], v[104:107]
	v_mfma_f32_16x16x32_bf16 v[104:107], v[132:135], v[192:195], v[104:107]
	v_mfma_f32_16x16x32_bf16 v[92:95], v[120:123], v[196:199], v[92:95]
	v_mfma_f32_16x16x32_bf16 v[92:95], v[124:127], v[200:203], v[92:95]
	v_mfma_f32_16x16x32_bf16 v[88:91], v[128:131], v[196:199], v[88:91]
	v_mfma_f32_16x16x32_bf16 v[88:91], v[132:135], v[200:203], v[88:91]
	v_mfma_f32_16x16x32_bf16 v[76:79], v[120:123], v[204:207], v[76:79]
	v_mfma_f32_16x16x32_bf16 v[76:79], v[124:127], v[214:217], v[76:79]
	v_mfma_f32_16x16x32_bf16 v[72:75], v[128:131], v[204:207], v[72:75]
	v_mfma_f32_16x16x32_bf16 v[72:75], v[132:135], v[214:217], v[72:75]
	v_mfma_f32_16x16x32_bf16 v[116:119], v[164:167], v[180:183], v[116:119]
	v_mfma_f32_16x16x32_bf16 v[116:119], v[168:171], v[184:187], v[116:119]
	v_mfma_f32_16x16x32_bf16 v[112:115], v[172:175], v[180:183], v[112:115]
	v_mfma_f32_16x16x32_bf16 v[112:115], v[176:179], v[184:187], v[112:115]
	v_mfma_f32_16x16x32_bf16 v[100:103], v[164:167], v[188:191], v[100:103]
	v_mfma_f32_16x16x32_bf16 v[100:103], v[168:171], v[192:195], v[100:103]
	v_mfma_f32_16x16x32_bf16 v[96:99], v[172:175], v[188:191], v[96:99]
	v_mfma_f32_16x16x32_bf16 v[96:99], v[176:179], v[192:195], v[96:99]
	v_mfma_f32_16x16x32_bf16 v[84:87], v[164:167], v[196:199], v[84:87]
	v_mfma_f32_16x16x32_bf16 v[84:87], v[168:171], v[200:203], v[84:87]
	v_mfma_f32_16x16x32_bf16 v[80:83], v[172:175], v[196:199], v[80:83]
	v_mfma_f32_16x16x32_bf16 v[80:83], v[176:179], v[200:203], v[80:83]
	v_mfma_f32_16x16x32_bf16 v[68:71], v[164:167], v[204:207], v[68:71]
	v_mfma_f32_16x16x32_bf16 v[68:71], v[168:171], v[214:217], v[68:71]
	v_mfma_f32_16x16x32_bf16 v[64:67], v[172:175], v[204:207], v[64:67]
	v_mfma_f32_16x16x32_bf16 v[64:67], v[176:179], v[214:217], v[64:67]
	s_barrier
	s_add_i32 s42, s42, s27
	v_lshl_add_u64 v[208:209], s[40:41], 0, v[146:147]
	s_mov_b32 m0, s42
	ds_read_b128 v[180:183], v162 offset:16384
	ds_read_b128 v[184:187], v162 offset:17408
	ds_read_b128 v[188:191], v162 offset:18432
	ds_read_b128 v[192:195], v162 offset:19456
	ds_read_b128 v[196:199], v162 offset:20480
	ds_read_b128 v[200:203], v162 offset:21504
	ds_read_b128 v[204:207], v162 offset:22528
	ds_read_b128 v[214:217], v162 offset:23552
	global_load_lds_dwordx4 v[208:209], off
	s_add_i32 m0, s42, 0x2000
	s_add_u32 s42, s40, 0x80000
	v_lshl_add_u64 v[218:219], s[40:41], 0, v[150:151]
	s_addc_u32 s43, s41, 0
	s_add_i32 s25, s25, s27
	global_load_lds_dwordx4 v[218:219], off
	v_lshl_add_u64 v[220:221], s[42:43], 0, v[146:147]
	s_mov_b32 m0, s25
	v_lshl_add_u64 v[222:223], s[28:29], 0, v[148:149]
	global_load_lds_dwordx4 v[220:221], off
	v_lshl_add_u64 v[220:221], s[42:43], 0, v[150:151]
	s_add_i32 m0, s25, 0x2000
	s_nop 0
	global_load_lds_dwordx4 v[220:221], off
	v_lshl_add_u64 v[220:221], s[28:29], 0, v[144:145]
	s_mov_b32 m0, s1
	s_nop 0
	global_load_lds_dwordx4 v[220:221], off
	s_mov_b32 m0, s39
	s_nop 0
	global_load_lds_dwordx4 v[222:223], off
	s_waitcnt vmcnt(8)
	s_waitcnt lgkmcnt(0)
	s_barrier
; #define PG8_STAGE(bufoff, gbase, voff) do { _Pragma("unroll") for (int _i = 0; _i < 2; ++_i) \
;         __builtin_amdgcn_global_load_lds((const GAS unsigned*)((const GAS char*)(gbase) + (voff)[_i]), (PG8_LAS unsigned*)(lds + (bufoff) + ldsw + _i * 8192), 16, 0, 0); } while (0)
; #define PG8_LDA(dst, b, h) do { _Pragma("unroll") for (int m = 0; m < 4; ++m) _Pragma("unroll") for (int k = 0; k < 2; ++k) dst[m][k] = *(const PG8_LAS bf16x8*)(lds + PG8_SA(b, h) + aoff + m * 2048 + k * 1024); } while (0)
; #define PG8_LDB(dst, b, h) do { _Pragma("unroll") for (int n = 0; n < 2; ++n) _Pragma("unroll") for (int k = 0; k < 2; ++k) dst[n][k] = *(const PG8_LAS bf16x8*)(lds + PG8_SB(b, h) + boff + n * 2048 + k * 1024); } while (0)
; #define PG8_MMA(ai, bj, At, Bt) do { __builtin_amdgcn_s_setprio(1); _Pragma("unroll") for (int m = 0; m < 4; ++m) _Pragma("unroll") for (int n = 0; n < 2; ++n) _Pragma("unroll") for (int k = 0; k < 2; ++k) \
;         acc[ai][bj][m][n] = __builtin_amdgcn_mfma_f32_16x16x32_bf16(Bt[n][k], At[m][k], acc[ai][bj][m][n], 0, 0, 0); __builtin_amdgcn_s_setprio(0); } while (0)
; #define PG8_WAIT_V(n) asm volatile("s_waitcnt vmcnt(" #n ")" ::: "memory")
; #define PG8_WAIT_L(n) asm volatile("s_waitcnt lgkmcnt(" #n ")" ::: "memory")
; #define PG8_BAR __builtin_amdgcn_s_barrier()
; #define PG8_SCHED __builtin_amdgcn_sched_barrier(0)
; #define PG8_WAIT_V(n) asm volatile("s_waitcnt vmcnt(" #n ")" ::: "memory")
; #define PG8_WAIT_L(n) asm volatile("s_waitcnt lgkmcnt(" #n ")" ::: "memory")
; template <class Epi, class Sched, bool ALIGN_EPI = false, bool SP2 = false>
; __device__ __forceinline__ void gemm_phase(PG8_LAS unsigned char* lds, PG8_LAS unsigned char* pf, const Gemm g, const Sched& S, const Epi& E, int wv) {
;     ...
;             PG8_LDA(At, 0, 1); PG8_STAGE(PG8_SB(0, 0), b2, voffB); PG8_STAGE(PG8_SB(0, 1), b2 + hstepB, voffB); PG8_STAGE(PG8_SA(0, 0), a2, voffA);
;             PG8_WAIT_V(8); PG8_WAIT_L(0); PG8_BAR; PG8_MMA(1, 0, At, B0); PG8_MMA(1, 1, At, B1); PG8_BAR; PG8_SCHED;
;             PG8_LDB(B0, 1, 0); PG8_LDB(B1, 1, 1); PG8_SCHED; PG8_LDA(At, 1, 0); PG8_STAGE(PG8_SA(0, 1), a2 + (Sched::SPLIT ? ((last && has_next) ? (nxt.kh > 0 ? -(long)hstepA : (long)hstepA) : hsA) : (long)hstepA), voffA);
;             PG8_WAIT_V(8); PG8_WAIT_L(0); PG8_BAR; PG8_MMA(0, 0, At, B0); PG8_MMA(0, 1, At, B1); PG8_BAR; PG8_SCHED;
	s_waitcnt lgkmcnt(0)
	v_mfma_f32_16x16x32_bf16 v[60:63], v[120:123], v[180:183], v[60:63]
	v_mfma_f32_16x16x32_bf16 v[60:63], v[124:127], v[184:187], v[60:63]
	v_mfma_f32_16x16x32_bf16 v[56:59], v[128:131], v[180:183], v[56:59]
	v_mfma_f32_16x16x32_bf16 v[56:59], v[132:135], v[184:187], v[56:59]
	v_mfma_f32_16x16x32_bf16 v[44:47], v[120:123], v[188:191], v[44:47]
	v_mfma_f32_16x16x32_bf16 v[44:47], v[124:127], v[192:195], v[44:47]
	v_mfma_f32_16x16x32_bf16 v[40:43], v[128:131], v[188:191], v[40:43]
	v_mfma_f32_16x16x32_bf16 v[40:43], v[132:135], v[192:195], v[40:43]
	v_mfma_f32_16x16x32_bf16 v[28:31], v[120:123], v[196:199], v[28:31]
	v_mfma_f32_16x16x32_bf16 v[28:31], v[124:127], v[200:203], v[28:31]
	v_mfma_f32_16x16x32_bf16 v[24:27], v[128:131], v[196:199], v[24:27]
	v_mfma_f32_16x16x32_bf16 v[24:27], v[132:135], v[200:203], v[24:27]
	v_mfma_f32_16x16x32_bf16 v[12:15], v[120:123], v[204:207], v[12:15]
	v_mfma_f32_16x16x32_bf16 v[12:15], v[124:127], v[214:217], v[12:15]
	v_mfma_f32_16x16x32_bf16 v[8:11], v[128:131], v[204:207], v[8:11]
	v_mfma_f32_16x16x32_bf16 v[8:11], v[132:135], v[214:217], v[8:11]
	v_mfma_f32_16x16x32_bf16 v[52:55], v[164:167], v[180:183], v[52:55]
	v_mfma_f32_16x16x32_bf16 v[52:55], v[168:171], v[184:187], v[52:55]
	v_mfma_f32_16x16x32_bf16 v[48:51], v[172:175], v[180:183], v[48:51]
	v_mfma_f32_16x16x32_bf16 v[48:51], v[176:179], v[184:187], v[48:51]
	v_mfma_f32_16x16x32_bf16 v[36:39], v[164:167], v[188:191], v[36:39]
	v_mfma_f32_16x16x32_bf16 v[36:39], v[168:171], v[192:195], v[36:39]
	v_mfma_f32_16x16x32_bf16 v[32:35], v[172:175], v[188:191], v[32:35]
	v_mfma_f32_16x16x32_bf16 v[32:35], v[176:179], v[192:195], v[32:35]
	v_mfma_f32_16x16x32_bf16 v[20:23], v[164:167], v[196:199], v[20:23]
	v_mfma_f32_16x16x32_bf16 v[20:23], v[168:171], v[200:203], v[20:23]
	v_mfma_f32_16x16x32_bf16 v[16:19], v[172:175], v[196:199], v[16:19]
	v_mfma_f32_16x16x32_bf16 v[16:19], v[176:179], v[200:203], v[16:19]
	v_mfma_f32_16x16x32_bf16 v[4:7], v[164:167], v[204:207], v[4:7]
	v_mfma_f32_16x16x32_bf16 v[4:7], v[168:171], v[214:217], v[4:7]
	v_mfma_f32_16x16x32_bf16 v[0:3], v[172:175], v[204:207], v[0:3]
	v_mfma_f32_16x16x32_bf16 v[0:3], v[176:179], v[214:217], v[0:3]
	s_barrier
	s_add_i32 s25, 0, 0x18000
	s_add_i32 s42, 0, 0x1c000
	v_add_u32_e32 v132, s25, v159
	v_add_u32_e32 v160, s42, v159
	ds_read_b128 v[120:123], v132
	ds_read_b128 v[124:127], v132 offset:1024
	ds_read_b128 v[128:131], v132 offset:2048
	ds_read_b128 v[132:135], v132 offset:3072
	ds_read_b128 v[164:167], v160
	ds_read_b128 v[168:171], v160 offset:1024
	ds_read_b128 v[172:175], v160 offset:2048
	ds_read_b128 v[176:179], v160 offset:3072
	s_add_u32 s28, s28, 0x80000
	s_addc_u32 s29, s29, 0
	s_mov_b32 m0, s44
	v_lshl_add_u64 v[224:225], s[28:29], 0, v[144:145]
	ds_read_b128 v[180:183], v162 offset:32768
	ds_read_b128 v[184:187], v162 offset:33792
	ds_read_b128 v[188:191], v162 offset:34816
	ds_read_b128 v[192:195], v162 offset:35840
	ds_read_b128 v[196:199], v162 offset:36864
	ds_read_b128 v[200:203], v162 offset:37888
	ds_read_b128 v[204:207], v162 offset:38912
	ds_read_b128 v[214:217], v162 offset:39936
	global_load_lds_dwordx4 v[224:225], off
	v_lshl_add_u64 v[224:225], s[28:29], 0, v[148:149]
	s_mov_b32 m0, s45
	s_nop 0
	global_load_lds_dwordx4 v[224:225], off
	s_waitcnt vmcnt(8)
	s_waitcnt lgkmcnt(0)
	s_barrier
	s_waitcnt lgkmcnt(0)
	v_mfma_f32_16x16x32_bf16 v[140:143], v[120:123], v[180:183], v[140:143]
	v_mfma_f32_16x16x32_bf16 v[140:143], v[124:127], v[184:187], v[140:143]
	v_mfma_f32_16x16x32_bf16 v[136:139], v[128:131], v[180:183], v[136:139]
	v_mfma_f32_16x16x32_bf16 v[136:139], v[132:135], v[184:187], v[136:139]
	v_mfma_f32_16x16x32_bf16 v[108:111], v[120:123], v[188:191], v[108:111]
	v_mfma_f32_16x16x32_bf16 v[108:111], v[124:127], v[192:195], v[108:111]
	v_mfma_f32_16x16x32_bf16 v[104:107], v[128:131], v[188:191], v[104:107]
	v_mfma_f32_16x16x32_bf16 v[104:107], v[132:135], v[192:195], v[104:107]
	v_mfma_f32_16x16x32_bf16 v[92:95], v[120:123], v[196:199], v[92:95]
	v_mfma_f32_16x16x32_bf16 v[92:95], v[124:127], v[200:203], v[92:95]
	v_mfma_f32_16x16x32_bf16 v[88:91], v[128:131], v[196:199], v[88:91]
	v_mfma_f32_16x16x32_bf16 v[88:91], v[132:135], v[200:203], v[88:91]
	v_mfma_f32_16x16x32_bf16 v[76:79], v[120:123], v[204:207], v[76:79]
	v_mfma_f32_16x16x32_bf16 v[76:79], v[124:127], v[214:217], v[76:79]
	v_mfma_f32_16x16x32_bf16 v[72:75], v[128:131], v[204:207], v[72:75]
	v_mfma_f32_16x16x32_bf16 v[72:75], v[132:135], v[214:217], v[72:75]
	v_mfma_f32_16x16x32_bf16 v[116:119], v[164:167], v[180:183], v[116:119]
	v_mfma_f32_16x16x32_bf16 v[116:119], v[168:171], v[184:187], v[116:119]
	v_mfma_f32_16x16x32_bf16 v[112:115], v[172:175], v[180:183], v[112:115]
	v_mfma_f32_16x16x32_bf16 v[112:115], v[176:179], v[184:187], v[112:115]
	v_mfma_f32_16x16x32_bf16 v[100:103], v[164:167], v[188:191], v[100:103]
	v_mfma_f32_16x16x32_bf16 v[100:103], v[168:171], v[192:195], v[100:103]
	v_mfma_f32_16x16x32_bf16 v[96:99], v[172:175], v[188:191], v[96:99]
	v_mfma_f32_16x16x32_bf16 v[96:99], v[176:179], v[192:195], v[96:99]
	v_mfma_f32_16x16x32_bf16 v[84:87], v[164:167], v[196:199], v[84:87]
	v_mfma_f32_16x16x32_bf16 v[84:87], v[168:171], v[200:203], v[84:87]
	v_mfma_f32_16x16x32_bf16 v[80:83], v[172:175], v[196:199], v[80:83]
	v_mfma_f32_16x16x32_bf16 v[80:83], v[176:179], v[200:203], v[80:83]
	v_mfma_f32_16x16x32_bf16 v[68:71], v[164:167], v[204:207], v[68:71]
	v_mfma_f32_16x16x32_bf16 v[68:71], v[168:171], v[214:217], v[68:71]
	v_mfma_f32_16x16x32_bf16 v[64:67], v[172:175], v[204:207], v[64:67]
	v_mfma_f32_16x16x32_bf16 v[64:67], v[176:179], v[214:217], v[64:67]
	s_barrier
; #define PG8_STAGE(bufoff, gbase, voff) do { _Pragma("unroll") for (int _i = 0; _i < 2; ++_i) \
;         __builtin_amdgcn_global_load_lds((const GAS unsigned*)((const GAS char*)(gbase) + (voff)[_i]), (PG8_LAS unsigned*)(lds + (bufoff) + ldsw + _i * 8192), 16, 0, 0); } while (0)
; #define PG8_LDA(dst, b, h) do { _Pragma("unroll") for (int m = 0; m < 4; ++m) _Pragma("unroll") for (int k = 0; k < 2; ++k) dst[m][k] = *(const PG8_LAS bf16x8*)(lds + PG8_SA(b, h) + aoff + m * 2048 + k * 1024); } while (0)
; #define PG8_LDB(dst, b, h) do { _Pragma("unroll") for (int n = 0; n < 2; ++n) _Pragma("unroll") for (int k = 0; k < 2; ++k) dst[n][k] = *(const PG8_LAS bf16x8*)(lds + PG8_SB(b, h) + boff + n * 2048 + k * 1024); } while (0)
; #define PG8_MMA(ai, bj, At, Bt) do { __builtin_amdgcn_s_setprio(1); _Pragma("unroll") for (int m = 0; m < 4; ++m) _Pragma("unroll") for (int n = 0; n < 2; ++n) _Pragma("unroll") for (int k = 0; k < 2; ++k) \
;         acc[ai][bj][m][n] = __builtin_amdgcn_mfma_f32_16x16x32_bf16(Bt[n][k], At[m][k], acc[ai][bj][m][n], 0, 0, 0); __builtin_amdgcn_s_setprio(0); } while (0)
; #define PG8_WAIT_V(n) asm volatile("s_waitcnt vmcnt(" #n ")" ::: "memory")
; #define PG8_WAIT_L(n) asm volatile("s_waitcnt lgkmcnt(" #n ")" ::: "memory")
; #define PG8_BAR __builtin_amdgcn_s_barrier()
; #define PG8_SCHED __builtin_amdgcn_sched_barrier(0)
; #define PG8_WAIT_V(n) asm volatile("s_waitcnt vmcnt(" #n ")" ::: "memory")
; #define PG8_WAIT_L(n) asm volatile("s_waitcnt lgkmcnt(" #n ")" ::: "memory")
; template <class Epi, class Sched, bool ALIGN_EPI = false, bool SP2 = false>
; __device__ __forceinline__ void gemm_phase(PG8_LAS unsigned char* lds, PG8_LAS unsigned char* pf, const Gemm g, const Sched& S, const Epi& E, int wv) {
;     ...
;             PG8_LDB(B0, 1, 0); PG8_LDB(B1, 1, 1); PG8_SCHED; PG8_LDA(At, 1, 0); PG8_STAGE(PG8_SA(0, 1), a2 + (Sched::SPLIT ? ((last && has_next) ? (nxt.kh > 0 ? -(long)hstepA : (long)hstepA) : hsA) : (long)hstepA), voffA);
;             PG8_WAIT_V(8); PG8_WAIT_L(0); PG8_BAR; PG8_MMA(0, 0, At, B0); PG8_MMA(0, 1, At, B1); PG8_BAR; PG8_SCHED;
;             PG8_LDA(At, 1, 1); PG8_STAGE(PG8_SB(1, 0), b3, voffB); PG8_STAGE(PG8_SB(1, 1), b3 + hstepB, voffB); PG8_STAGE(PG8_SA(1, 0), a3, voffA);
;             PG8_WAIT_V(8); PG8_WAIT_L(0); PG8_BAR; PG8_MMA(1, 0, At, B0); PG8_MMA(1, 1, At, B1); PG8_BAR; PG8_SCHED;
	s_add_i32 s25, s25, s27
	v_lshl_add_u64 v[208:209], v[208:209], 0, s[16:17]
	s_mov_b32 m0, s25
	ds_read_b128 v[180:183], v162 offset:49152
	ds_read_b128 v[184:187], v162 offset:50176
	ds_read_b128 v[188:191], v162 offset:51200
	ds_read_b128 v[192:195], v162 offset:52224
	ds_read_b128 v[196:199], v162 offset:53248
	ds_read_b128 v[200:203], v162 offset:54272
	ds_read_b128 v[204:207], v162 offset:55296
	ds_read_b128 v[214:217], v162 offset:56320
	global_load_lds_dwordx4 v[208:209], off
	s_add_i32 m0, s25, 0x2000
	s_add_u32 s28, s40, 0x80080
	v_lshl_add_u64 v[208:209], v[218:219], 0, s[16:17]
	s_addc_u32 s29, s41, 0
	s_add_i32 s25, s42, s27
	global_load_lds_dwordx4 v[208:209], off
	v_lshl_add_u64 v[208:209], s[28:29], 0, v[146:147]
	s_mov_b32 m0, s25
	s_nop 0
	global_load_lds_dwordx4 v[208:209], off
	v_lshl_add_u64 v[208:209], s[28:29], 0, v[150:151]
	s_add_i32 m0, s25, 0x2000
	s_nop 0
	global_load_lds_dwordx4 v[208:209], off
	v_lshl_add_u64 v[208:209], v[220:221], 0, s[16:17]
	s_mov_b32 m0, s20
	s_nop 0
	global_load_lds_dwordx4 v[208:209], off
	v_lshl_add_u64 v[208:209], v[222:223], 0, s[16:17]
	s_mov_b32 m0, s21
	s_nop 0
	global_load_lds_dwordx4 v[208:209], off
	s_waitcnt vmcnt(8)
	s_waitcnt lgkmcnt(0)
	s_barrier
	s_waitcnt lgkmcnt(0)
	v_mfma_f32_16x16x32_bf16 v[60:63], v[120:123], v[180:183], v[60:63]
	v_mfma_f32_16x16x32_bf16 v[60:63], v[124:127], v[184:187], v[60:63]
	v_mfma_f32_16x16x32_bf16 v[56:59], v[128:131], v[180:183], v[56:59]
	v_mfma_f32_16x16x32_bf16 v[56:59], v[132:135], v[184:187], v[56:59]
	v_mfma_f32_16x16x32_bf16 v[44:47], v[120:123], v[188:191], v[44:47]
	v_mfma_f32_16x16x32_bf16 v[44:47], v[124:127], v[192:195], v[44:47]
	v_mfma_f32_16x16x32_bf16 v[40:43], v[128:131], v[188:191], v[40:43]
	v_mfma_f32_16x16x32_bf16 v[40:43], v[132:135], v[192:195], v[40:43]
	v_mfma_f32_16x16x32_bf16 v[28:31], v[120:123], v[196:199], v[28:31]
	v_mfma_f32_16x16x32_bf16 v[28:31], v[124:127], v[200:203], v[28:31]
	v_mfma_f32_16x16x32_bf16 v[24:27], v[128:131], v[196:199], v[24:27]
	v_mfma_f32_16x16x32_bf16 v[24:27], v[132:135], v[200:203], v[24:27]
	v_mfma_f32_16x16x32_bf16 v[12:15], v[120:123], v[204:207], v[12:15]
	v_mfma_f32_16x16x32_bf16 v[12:15], v[124:127], v[214:217], v[12:15]
	v_mfma_f32_16x16x32_bf16 v[8:11], v[128:131], v[204:207], v[8:11]
	v_mfma_f32_16x16x32_bf16 v[8:11], v[132:135], v[214:217], v[8:11]
	v_mfma_f32_16x16x32_bf16 v[52:55], v[164:167], v[180:183], v[52:55]
	v_mfma_f32_16x16x32_bf16 v[52:55], v[168:171], v[184:187], v[52:55]
	v_mfma_f32_16x16x32_bf16 v[48:51], v[172:175], v[180:183], v[48:51]
	v_mfma_f32_16x16x32_bf16 v[48:51], v[176:179], v[184:187], v[48:51]
	v_mfma_f32_16x16x32_bf16 v[36:39], v[164:167], v[188:191], v[36:39]
	v_mfma_f32_16x16x32_bf16 v[36:39], v[168:171], v[192:195], v[36:39]
	v_mfma_f32_16x16x32_bf16 v[32:35], v[172:175], v[188:191], v[32:35]
	v_mfma_f32_16x16x32_bf16 v[32:35], v[176:179], v[192:195], v[32:35]
	v_mfma_f32_16x16x32_bf16 v[20:23], v[164:167], v[196:199], v[20:23]
	v_mfma_f32_16x16x32_bf16 v[20:23], v[168:171], v[200:203], v[20:23]
	v_mfma_f32_16x16x32_bf16 v[16:19], v[172:175], v[196:199], v[16:19]
	v_mfma_f32_16x16x32_bf16 v[16:19], v[176:179], v[200:203], v[16:19]
	v_mfma_f32_16x16x32_bf16 v[4:7], v[164:167], v[204:207], v[4:7]
	v_mfma_f32_16x16x32_bf16 v[4:7], v[168:171], v[214:217], v[4:7]
	v_mfma_f32_16x16x32_bf16 v[0:3], v[172:175], v[204:207], v[0:3]
	v_mfma_f32_16x16x32_bf16 v[0:3], v[176:179], v[214:217], v[0:3]
	s_barrier
	s_add_i32 s24, s24, 2
	s_add_u32 s22, s22, 0x100
	s_addc_u32 s23, s23, 0
	s_add_u32 s36, s36, 0x100
	s_addc_u32 s37, s37, 0
	s_cmp_gt_u32 s24, 29
	s_cbranch_scc0 .LBB0_1414
	s_and_b64 vcc, exec, s[6:7]
	s_cbranch_vccz .LBB0_1417
	s_barrier

; #define GAS __attribute__((address_space(1)))
; #define PG8_STAGE(bufoff, gbase, voff) do { _Pragma("unroll") for (int _i = 0; _i < 2; ++_i) \
;         __builtin_amdgcn_global_load_lds((const GAS unsigned*)((const GAS char*)(gbase) + (voff)[_i]), (PG8_LAS unsigned*)(lds + (bufoff) + ldsw + _i * 8192), 16, 0, 0); } while (0)
; #define PG8_LDA(dst, b, h) do { _Pragma("unroll") for (int m = 0; m < 4; ++m) _Pragma("unroll") for (int k = 0; k < 2; ++k) dst[m][k] = *(const PG8_LAS bf16x8*)(lds + PG8_SA(b, h) + aoff + m * 2048 + k * 1024); } while (0)
; #define PG8_LDB(dst, b, h) do { _Pragma("unroll") for (int n = 0; n < 2; ++n) _Pragma("unroll") for (int k = 0; k < 2; ++k) dst[n][k] = *(const PG8_LAS bf16x8*)(lds + PG8_SB(b, h) + boff + n * 2048 + k * 1024); } while (0)
; #define PG8_WAIT_V(n) asm volatile("s_waitcnt vmcnt(" #n ")" ::: "memory")
; #define PG8_WAIT_L(n) asm volatile("s_waitcnt lgkmcnt(" #n ")" ::: "memory")
; #define PG8_BAR __builtin_amdgcn_s_barrier()
; #define PG8_SCHED __builtin_amdgcn_sched_barrier(0)
; template <class Epi, class Sched, bool ALIGN_EPI = false, bool SP2 = false>
; __device__ __forceinline__ void gemm_phase(PG8_LAS unsigned char* lds, PG8_LAS unsigned char* pf, const Gemm g, const Sched& S, const Epi& E, int wv) {
;     ...
;         int ntu = nt; if constexpr (Sched::SPLIT) { if (cur.kh >= 0) ntu = nt >> 1; }
;         for (int t = 0; t < ntu; t += 2) {
;             const bool last = (t == ntu - 2);
;             const GAS char* a1 = cA + (size_t)(t + 1) * kstep;
;             const GAS char* a2 = last ? nA : cA + (size_t)(t + 2) * kstep; const GAS char* b2 = last ? nB : cB + (size_t)(t + 2) * kstep;
;             const GAS char* a3 = a2 + kstep; const GAS char* b3 = b2 + kstep;
;             if (last && has_next) S.a_ready(nxt);
;             if constexpr (SP2) {
;             PG8_LDB(B0, 0, 0); PG8_LDB(B1, 0, 1); PG8_SCHED; PG8_LDA(At, 0, 0); PG8_STAGE(PG8_SA(1, 1), a1 + (Sched::SPLIT ? hsA : (long)hstepA), voffA);
;             PG8_WAIT_V(8); PG8_WAIT_L(0); PG8_BAR; PG8_MMA(0, 0, At, B0); PG8_MMA(0, 1, At, B1); PG8_BAR; PG8_SCHED;
;             PG8_LDA(At, 0, 1); PG8_STAGE(PG8_SB(0, 0), b2, voffB); PG8_STAGE(PG8_SB(0, 1), b2 + hstepB, voffB); PG8_STAGE(PG8_SA(0, 0), a2, voffA);
;             PG8_WAIT_V(8); PG8_WAIT_L(0); PG8_BAR; PG8_MMA(1, 0, At, B0); PG8_MMA(1, 1, At, B1); PG8_BAR; PG8_SCHED;
.LBB0_1456:
	s_cmp_eq_u32 s25, s60
	s_cselect_b64 s[28:29], -1, 0
	s_add_i32 s15, s15, 2
	s_add_u32 s31, s38, s60
	s_addc_u32 s62, s39, s61
	s_add_u32 s31, s31, 0x100
	s_addc_u32 s94, s62, 0
	s_add_u32 s64, s23, s60
	s_addc_u32 s65, s24, s61
	s_and_b64 s[62:63], s[28:29], exec
	s_cselect_b32 s63, s20, s65
	s_cselect_b32 s62, s21, s64
	s_add_i32 s95, 0, 0x10000
	s_and_b64 s[64:65], s[28:29], exec
	v_add_u32_e32 v160, s95, v162
	s_cselect_b32 s65, s45, s94
	s_cselect_b32 s64, s44, s31
	s_add_i32 s31, 0, 0x14000
	ds_read_b128 v[132:135], v160
	ds_read_b128 v[136:139], v160 offset:1024
	ds_read_b128 v[140:143], v160 offset:2048
	ds_read_b128 v[164:167], v160 offset:3072
	v_add_u32_e32 v160, s31, v162
	ds_read_b128 v[168:171], v160
	ds_read_b128 v[172:175], v160 offset:1024
	ds_read_b128 v[176:179], v160 offset:2048
	ds_read_b128 v[180:183], v160 offset:3072
	v_lshl_add_u64 v[208:209], v[130:131], 0, s[60:61]
	s_add_i32 m0, s5, 0xc000
	ds_read_b128 v[184:187], v163
	ds_read_b128 v[188:191], v163 offset:1024
	ds_read_b128 v[192:195], v163 offset:2048
	ds_read_b128 v[196:199], v163 offset:3072
	ds_read_b128 v[200:203], v163 offset:4096
	ds_read_b128 v[204:207], v163 offset:5120
	ds_read_b128 v[214:217], v163 offset:6144
	ds_read_b128 v[218:221], v163 offset:7168
	global_load_lds_dwordx4 v[208:209], off
	v_lshl_add_u64 v[208:209], v[128:129], 0, s[60:61]
	s_add_i32 m0, s5, 0xe000
	s_nop 0
	global_load_lds_dwordx4 v[208:209], off
	s_waitcnt vmcnt(8)
	s_waitcnt lgkmcnt(0)
	s_barrier
	s_waitcnt lgkmcnt(0)
	v_mfma_f32_16x16x32_bf16 v[124:127], v[132:135], v[184:187], v[124:127]
	v_mfma_f32_16x16x32_bf16 v[124:127], v[136:139], v[188:191], v[124:127]
	v_mfma_f32_16x16x32_bf16 v[120:123], v[140:143], v[184:187], v[120:123]
	v_mfma_f32_16x16x32_bf16 v[120:123], v[164:167], v[188:191], v[120:123]
	v_mfma_f32_16x16x32_bf16 v[108:111], v[132:135], v[192:195], v[108:111]
	v_mfma_f32_16x16x32_bf16 v[108:111], v[136:139], v[196:199], v[108:111]
	v_mfma_f32_16x16x32_bf16 v[104:107], v[140:143], v[192:195], v[104:107]
	v_mfma_f32_16x16x32_bf16 v[104:107], v[164:167], v[196:199], v[104:107]
	v_mfma_f32_16x16x32_bf16 v[92:95], v[132:135], v[200:203], v[92:95]
	v_mfma_f32_16x16x32_bf16 v[92:95], v[136:139], v[204:207], v[92:95]
	v_mfma_f32_16x16x32_bf16 v[88:91], v[140:143], v[200:203], v[88:91]
	v_mfma_f32_16x16x32_bf16 v[88:91], v[164:167], v[204:207], v[88:91]
	v_mfma_f32_16x16x32_bf16 v[76:79], v[132:135], v[214:217], v[76:79]
	v_mfma_f32_16x16x32_bf16 v[76:79], v[136:139], v[218:221], v[76:79]
	v_mfma_f32_16x16x32_bf16 v[72:75], v[140:143], v[214:217], v[72:75]
	v_mfma_f32_16x16x32_bf16 v[72:75], v[164:167], v[218:221], v[72:75]
	v_mfma_f32_16x16x32_bf16 v[116:119], v[168:171], v[184:187], v[116:119]
	v_mfma_f32_16x16x32_bf16 v[116:119], v[172:175], v[188:191], v[116:119]
	v_mfma_f32_16x16x32_bf16 v[112:115], v[176:179], v[184:187], v[112:115]
	v_mfma_f32_16x16x32_bf16 v[112:115], v[180:183], v[188:191], v[112:115]
	v_mfma_f32_16x16x32_bf16 v[100:103], v[168:171], v[192:195], v[100:103]
	v_mfma_f32_16x16x32_bf16 v[100:103], v[172:175], v[196:199], v[100:103]
	v_mfma_f32_16x16x32_bf16 v[96:99], v[176:179], v[192:195], v[96:99]
	v_mfma_f32_16x16x32_bf16 v[96:99], v[180:183], v[196:199], v[96:99]
	v_mfma_f32_16x16x32_bf16 v[84:87], v[168:171], v[200:203], v[84:87]
	v_mfma_f32_16x16x32_bf16 v[84:87], v[172:175], v[204:207], v[84:87]
	v_mfma_f32_16x16x32_bf16 v[80:83], v[176:179], v[200:203], v[80:83]
	v_mfma_f32_16x16x32_bf16 v[80:83], v[180:183], v[204:207], v[80:83]
	v_mfma_f32_16x16x32_bf16 v[68:71], v[168:171], v[214:217], v[68:71]
	v_mfma_f32_16x16x32_bf16 v[68:71], v[172:175], v[218:221], v[68:71]
	v_mfma_f32_16x16x32_bf16 v[64:67], v[176:179], v[214:217], v[64:67]
	v_mfma_f32_16x16x32_bf16 v[64:67], v[180:183], v[218:221], v[64:67]
	s_barrier
	s_add_i32 s94, s95, s27
	v_lshl_add_u64 v[208:209], s[62:63], 0, v[146:147]
	s_mov_b32 m0, s94
	ds_read_b128 v[184:187], v163 offset:16384
	ds_read_b128 v[188:191], v163 offset:17408
	ds_read_b128 v[192:195], v163 offset:18432
	ds_read_b128 v[196:199], v163 offset:19456
	ds_read_b128 v[200:203], v163 offset:20480
	ds_read_b128 v[204:207], v163 offset:21504
	ds_read_b128 v[214:217], v163 offset:22528
	ds_read_b128 v[218:221], v163 offset:23552
	global_load_lds_dwordx4 v[208:209], off
	s_add_i32 m0, s94, 0x2000
	s_add_u32 s94, s62, 0x80000
	v_lshl_add_u64 v[222:223], s[62:63], 0, v[150:151]
	s_addc_u32 s95, s63, 0
	s_add_i32 s31, s31, s27
	global_load_lds_dwordx4 v[222:223], off
	v_lshl_add_u64 v[224:225], s[94:95], 0, v[146:147]
	s_mov_b32 m0, s31
	v_lshl_add_u64 v[226:227], s[64:65], 0, v[148:149]
	global_load_lds_dwordx4 v[224:225], off
	v_lshl_add_u64 v[224:225], s[94:95], 0, v[150:151]
	s_add_i32 m0, s31, 0x2000
	s_nop 0
	global_load_lds_dwordx4 v[224:225], off
	v_lshl_add_u64 v[224:225], s[64:65], 0, v[144:145]
	s_mov_b32 m0, s5
	s_nop 0
	global_load_lds_dwordx4 v[224:225], off
	s_mov_b32 m0, s53
	s_nop 0
	global_load_lds_dwordx4 v[226:227], off
	s_waitcnt vmcnt(8)
	s_waitcnt lgkmcnt(0)
	s_barrier
; #define PG8_STAGE(bufoff, gbase, voff) do { _Pragma("unroll") for (int _i = 0; _i < 2; ++_i) \
;         __builtin_amdgcn_global_load_lds((const GAS unsigned*)((const GAS char*)(gbase) + (voff)[_i]), (PG8_LAS unsigned*)(lds + (bufoff) + ldsw + _i * 8192), 16, 0, 0); } while (0)
; #define PG8_LDA(dst, b, h) do { _Pragma("unroll") for (int m = 0; m < 4; ++m) _Pragma("unroll") for (int k = 0; k < 2; ++k) dst[m][k] = *(const PG8_LAS bf16x8*)(lds + PG8_SA(b, h) + aoff + m * 2048 + k * 1024); } while (0)
; #define PG8_LDB(dst, b, h) do { _Pragma("unroll") for (int n = 0; n < 2; ++n) _Pragma("unroll") for (int k = 0; k < 2; ++k) dst[n][k] = *(const PG8_LAS bf16x8*)(lds + PG8_SB(b, h) + boff + n * 2048 + k * 1024); } while (0)
; #define PG8_MMA(ai, bj, At, Bt) do { __builtin_amdgcn_s_setprio(1); _Pragma("unroll") for (int m = 0; m < 4; ++m) _Pragma("unroll") for (int n = 0; n < 2; ++n) _Pragma("unroll") for (int k = 0; k < 2; ++k) \
;         acc[ai][bj][m][n] = __builtin_amdgcn_mfma_f32_16x16x32_bf16(Bt[n][k], At[m][k], acc[ai][bj][m][n], 0, 0, 0); __builtin_amdgcn_s_setprio(0); } while (0)
; #define PG8_WAIT_V(n) asm volatile("s_waitcnt vmcnt(" #n ")" ::: "memory")
; #define PG8_WAIT_L(n) asm volatile("s_waitcnt lgkmcnt(" #n ")" ::: "memory")
; #define PG8_BAR __builtin_amdgcn_s_barrier()
; #define PG8_SCHED __builtin_amdgcn_sched_barrier(0)
; #define PG8_WAIT_V(n) asm volatile("s_waitcnt vmcnt(" #n ")" ::: "memory")
; #define PG8_WAIT_L(n) asm volatile("s_waitcnt lgkmcnt(" #n ")" ::: "memory")
; template <class Epi, class Sched, bool ALIGN_EPI = false, bool SP2 = false>
; __device__ __forceinline__ void gemm_phase(PG8_LAS unsigned char* lds, PG8_LAS unsigned char* pf, const Gemm g, const Sched& S, const Epi& E, int wv) {
;     ...
;             PG8_LDA(At, 0, 1); PG8_STAGE(PG8_SB(0, 0), b2, voffB); PG8_STAGE(PG8_SB(0, 1), b2 + hstepB, voffB); PG8_STAGE(PG8_SA(0, 0), a2, voffA);
;             PG8_WAIT_V(8); PG8_WAIT_L(0); PG8_BAR; PG8_MMA(1, 0, At, B0); PG8_MMA(1, 1, At, B1); PG8_BAR; PG8_SCHED;
;             PG8_LDB(B0, 1, 0); PG8_LDB(B1, 1, 1); PG8_SCHED; PG8_LDA(At, 1, 0); PG8_STAGE(PG8_SA(0, 1), a2 + (Sched::SPLIT ? ((last && has_next) ? (nxt.kh > 0 ? -(long)hstepA : (long)hstepA) : hsA) : (long)hstepA), voffA);
;             PG8_WAIT_V(8); PG8_WAIT_L(0); PG8_BAR; PG8_MMA(0, 0, At, B0); PG8_MMA(0, 1, At, B1); PG8_BAR; PG8_SCHED;
	s_waitcnt lgkmcnt(0)
	v_mfma_f32_16x16x32_bf16 v[60:63], v[132:135], v[184:187], v[60:63]
	v_mfma_f32_16x16x32_bf16 v[60:63], v[136:139], v[188:191], v[60:63]
	v_mfma_f32_16x16x32_bf16 v[56:59], v[140:143], v[184:187], v[56:59]
	v_mfma_f32_16x16x32_bf16 v[56:59], v[164:167], v[188:191], v[56:59]
	v_mfma_f32_16x16x32_bf16 v[44:47], v[132:135], v[192:195], v[44:47]
	v_mfma_f32_16x16x32_bf16 v[44:47], v[136:139], v[196:199], v[44:47]
	v_mfma_f32_16x16x32_bf16 v[40:43], v[140:143], v[192:195], v[40:43]
	v_mfma_f32_16x16x32_bf16 v[40:43], v[164:167], v[196:199], v[40:43]
	v_mfma_f32_16x16x32_bf16 v[28:31], v[132:135], v[200:203], v[28:31]
	v_mfma_f32_16x16x32_bf16 v[28:31], v[136:139], v[204:207], v[28:31]
	v_mfma_f32_16x16x32_bf16 v[24:27], v[140:143], v[200:203], v[24:27]
	v_mfma_f32_16x16x32_bf16 v[24:27], v[164:167], v[204:207], v[24:27]
	v_mfma_f32_16x16x32_bf16 v[12:15], v[132:135], v[214:217], v[12:15]
	v_mfma_f32_16x16x32_bf16 v[12:15], v[136:139], v[218:221], v[12:15]
	v_mfma_f32_16x16x32_bf16 v[8:11], v[140:143], v[214:217], v[8:11]
	v_mfma_f32_16x16x32_bf16 v[8:11], v[164:167], v[218:221], v[8:11]
	v_mfma_f32_16x16x32_bf16 v[52:55], v[168:171], v[184:187], v[52:55]
	v_mfma_f32_16x16x32_bf16 v[52:55], v[172:175], v[188:191], v[52:55]
	v_mfma_f32_16x16x32_bf16 v[48:51], v[176:179], v[184:187], v[48:51]
	v_mfma_f32_16x16x32_bf16 v[48:51], v[180:183], v[188:191], v[48:51]
	v_mfma_f32_16x16x32_bf16 v[36:39], v[168:171], v[192:195], v[36:39]
	v_mfma_f32_16x16x32_bf16 v[36:39], v[172:175], v[196:199], v[36:39]
	v_mfma_f32_16x16x32_bf16 v[32:35], v[176:179], v[192:195], v[32:35]
	v_mfma_f32_16x16x32_bf16 v[32:35], v[180:183], v[196:199], v[32:35]
	v_mfma_f32_16x16x32_bf16 v[20:23], v[168:171], v[200:203], v[20:23]
	v_mfma_f32_16x16x32_bf16 v[20:23], v[172:175], v[204:207], v[20:23]
	v_mfma_f32_16x16x32_bf16 v[16:19], v[176:179], v[200:203], v[16:19]
	v_mfma_f32_16x16x32_bf16 v[16:19], v[180:183], v[204:207], v[16:19]
	v_mfma_f32_16x16x32_bf16 v[4:7], v[168:171], v[214:217], v[4:7]
	v_mfma_f32_16x16x32_bf16 v[4:7], v[172:175], v[218:221], v[4:7]
	v_mfma_f32_16x16x32_bf16 v[0:3], v[176:179], v[214:217], v[0:3]
	v_mfma_f32_16x16x32_bf16 v[0:3], v[180:183], v[218:221], v[0:3]
	s_barrier
	s_add_i32 s31, 0, 0x18000
	v_add_u32_e32 v160, s31, v162
	s_add_i32 s94, 0, 0x1c000
	ds_read_b128 v[132:135], v160
	ds_read_b128 v[136:139], v160 offset:1024
	ds_read_b128 v[140:143], v160 offset:2048
	ds_read_b128 v[164:167], v160 offset:3072
	v_add_u32_e32 v160, s94, v162
	ds_read_b128 v[168:171], v160
	ds_read_b128 v[172:175], v160 offset:1024
	ds_read_b128 v[176:179], v160 offset:2048
	ds_read_b128 v[180:183], v160 offset:3072
	s_and_b64 s[28:29], s[56:57], s[28:29]
	s_and_b64 s[28:29], s[28:29], exec
	s_cselect_b32 s28, s40, s36
	s_cselect_b32 s29, s41, s37
	s_add_u32 s28, s64, s28
	s_addc_u32 s29, s65, s29
	s_mov_b32 m0, s75
	v_lshl_add_u64 v[228:229], s[28:29], 0, v[144:145]
	ds_read_b128 v[184:187], v163 offset:32768
	ds_read_b128 v[188:191], v163 offset:33792
	ds_read_b128 v[192:195], v163 offset:34816
	ds_read_b128 v[196:199], v163 offset:35840
	ds_read_b128 v[200:203], v163 offset:36864
	ds_read_b128 v[204:207], v163 offset:37888
	ds_read_b128 v[214:217], v163 offset:38912
	ds_read_b128 v[218:221], v163 offset:39936
	global_load_lds_dwordx4 v[228:229], off
	v_lshl_add_u64 v[228:229], s[28:29], 0, v[148:149]
	s_mov_b32 m0, s76
	s_nop 0
	global_load_lds_dwordx4 v[228:229], off
	s_waitcnt vmcnt(8)
	s_waitcnt lgkmcnt(0)
	s_barrier
	s_waitcnt lgkmcnt(0)
	v_mfma_f32_16x16x32_bf16 v[124:127], v[132:135], v[184:187], v[124:127]
	v_mfma_f32_16x16x32_bf16 v[124:127], v[136:139], v[188:191], v[124:127]
	v_mfma_f32_16x16x32_bf16 v[120:123], v[140:143], v[184:187], v[120:123]
	v_mfma_f32_16x16x32_bf16 v[120:123], v[164:167], v[188:191], v[120:123]
	v_mfma_f32_16x16x32_bf16 v[108:111], v[132:135], v[192:195], v[108:111]
	v_mfma_f32_16x16x32_bf16 v[108:111], v[136:139], v[196:199], v[108:111]
	v_mfma_f32_16x16x32_bf16 v[104:107], v[140:143], v[192:195], v[104:107]
	v_mfma_f32_16x16x32_bf16 v[104:107], v[164:167], v[196:199], v[104:107]
	v_mfma_f32_16x16x32_bf16 v[92:95], v[132:135], v[200:203], v[92:95]
	v_mfma_f32_16x16x32_bf16 v[92:95], v[136:139], v[204:207], v[92:95]
	v_mfma_f32_16x16x32_bf16 v[88:91], v[140:143], v[200:203], v[88:91]
	v_mfma_f32_16x16x32_bf16 v[88:91], v[164:167], v[204:207], v[88:91]
	v_mfma_f32_16x16x32_bf16 v[76:79], v[132:135], v[214:217], v[76:79]
	v_mfma_f32_16x16x32_bf16 v[76:79], v[136:139], v[218:221], v[76:79]
	v_mfma_f32_16x16x32_bf16 v[72:75], v[140:143], v[214:217], v[72:75]
	v_mfma_f32_16x16x32_bf16 v[72:75], v[164:167], v[218:221], v[72:75]
	v_mfma_f32_16x16x32_bf16 v[116:119], v[168:171], v[184:187], v[116:119]
	v_mfma_f32_16x16x32_bf16 v[116:119], v[172:175], v[188:191], v[116:119]
	v_mfma_f32_16x16x32_bf16 v[112:115], v[176:179], v[184:187], v[112:115]
	v_mfma_f32_16x16x32_bf16 v[112:115], v[180:183], v[188:191], v[112:115]
	v_mfma_f32_16x16x32_bf16 v[100:103], v[168:171], v[192:195], v[100:103]
	v_mfma_f32_16x16x32_bf16 v[100:103], v[172:175], v[196:199], v[100:103]
	v_mfma_f32_16x16x32_bf16 v[96:99], v[176:179], v[192:195], v[96:99]
	v_mfma_f32_16x16x32_bf16 v[96:99], v[180:183], v[196:199], v[96:99]
	v_mfma_f32_16x16x32_bf16 v[84:87], v[168:171], v[200:203], v[84:87]
	v_mfma_f32_16x16x32_bf16 v[84:87], v[172:175], v[204:207], v[84:87]
	v_mfma_f32_16x16x32_bf16 v[80:83], v[176:179], v[200:203], v[80:83]
	v_mfma_f32_16x16x32_bf16 v[80:83], v[180:183], v[204:207], v[80:83]
	v_mfma_f32_16x16x32_bf16 v[68:71], v[168:171], v[214:217], v[68:71]
	v_mfma_f32_16x16x32_bf16 v[68:71], v[172:175], v[218:221], v[68:71]
	v_mfma_f32_16x16x32_bf16 v[64:67], v[176:179], v[214:217], v[64:67]
	v_mfma_f32_16x16x32_bf16 v[64:67], v[180:183], v[218:221], v[64:67]
	s_barrier
; #define PG8_STAGE(bufoff, gbase, voff) do { _Pragma("unroll") for (int _i = 0; _i < 2; ++_i) \
;         __builtin_amdgcn_global_load_lds((const GAS unsigned*)((const GAS char*)(gbase) + (voff)[_i]), (PG8_LAS unsigned*)(lds + (bufoff) + ldsw + _i * 8192), 16, 0, 0); } while (0)
; #define PG8_LDA(dst, b, h) do { _Pragma("unroll") for (int m = 0; m < 4; ++m) _Pragma("unroll") for (int k = 0; k < 2; ++k) dst[m][k] = *(const PG8_LAS bf16x8*)(lds + PG8_SA(b, h) + aoff + m * 2048 + k * 1024); } while (0)
; #define PG8_LDB(dst, b, h) do { _Pragma("unroll") for (int n = 0; n < 2; ++n) _Pragma("unroll") for (int k = 0; k < 2; ++k) dst[n][k] = *(const PG8_LAS bf16x8*)(lds + PG8_SB(b, h) + boff + n * 2048 + k * 1024); } while (0)
; #define PG8_MMA(ai, bj, At, Bt) do { __builtin_amdgcn_s_setprio(1); _Pragma("unroll") for (int m = 0; m < 4; ++m) _Pragma("unroll") for (int n = 0; n < 2; ++n) _Pragma("unroll") for (int k = 0; k < 2; ++k) \
;         acc[ai][bj][m][n] = __builtin_amdgcn_mfma_f32_16x16x32_bf16(Bt[n][k], At[m][k], acc[ai][bj][m][n], 0, 0, 0); __builtin_amdgcn_s_setprio(0); } while (0)
; #define PG8_WAIT_V(n) asm volatile("s_waitcnt vmcnt(" #n ")" ::: "memory")
; #define PG8_WAIT_L(n) asm volatile("s_waitcnt lgkmcnt(" #n ")" ::: "memory")
; #define PG8_BAR __builtin_amdgcn_s_barrier()
; #define PG8_SCHED __builtin_amdgcn_sched_barrier(0)
; #define PG8_WAIT_V(n) asm volatile("s_waitcnt vmcnt(" #n ")" ::: "memory")
; #define PG8_WAIT_L(n) asm volatile("s_waitcnt lgkmcnt(" #n ")" ::: "memory")
; template <class Epi, class Sched, bool ALIGN_EPI = false, bool SP2 = false>
; __device__ __forceinline__ void gemm_phase(PG8_LAS unsigned char* lds, PG8_LAS unsigned char* pf, const Gemm g, const Sched& S, const Epi& E, int wv) {
;     ...
;             PG8_LDB(B0, 1, 0); PG8_LDB(B1, 1, 1); PG8_SCHED; PG8_LDA(At, 1, 0); PG8_STAGE(PG8_SA(0, 1), a2 + (Sched::SPLIT ? ((last && has_next) ? (nxt.kh > 0 ? -(long)hstepA : (long)hstepA) : hsA) : (long)hstepA), voffA);
;             PG8_WAIT_V(8); PG8_WAIT_L(0); PG8_BAR; PG8_MMA(0, 0, At, B0); PG8_MMA(0, 1, At, B1); PG8_BAR; PG8_SCHED;
;             PG8_LDA(At, 1, 1); PG8_STAGE(PG8_SB(1, 0), b3, voffB); PG8_STAGE(PG8_SB(1, 1), b3 + hstepB, voffB); PG8_STAGE(PG8_SA(1, 0), a3, voffA);
;             PG8_WAIT_V(8); PG8_WAIT_L(0); PG8_BAR; PG8_MMA(1, 0, At, B0); PG8_MMA(1, 1, At, B1); PG8_BAR; PG8_SCHED;
	s_add_i32 s28, s31, s27
	v_lshl_add_u64 v[208:209], v[208:209], 0, s[16:17]
	s_mov_b32 m0, s28
	ds_read_b128 v[184:187], v163 offset:49152
	ds_read_b128 v[188:191], v163 offset:50176
	ds_read_b128 v[192:195], v163 offset:51200
	ds_read_b128 v[196:199], v163 offset:52224
	ds_read_b128 v[200:203], v163 offset:53248
	ds_read_b128 v[204:207], v163 offset:54272
	ds_read_b128 v[214:217], v163 offset:55296
	ds_read_b128 v[218:221], v163 offset:56320
	global_load_lds_dwordx4 v[208:209], off
	s_add_i32 m0, s28, 0x2000
	s_add_u32 s28, s62, 0x80080
	v_lshl_add_u64 v[208:209], v[222:223], 0, s[16:17]
	s_addc_u32 s29, s63, 0
	s_add_i32 s31, s94, s27
	global_load_lds_dwordx4 v[208:209], off
	v_lshl_add_u64 v[208:209], s[28:29], 0, v[146:147]
	s_mov_b32 m0, s31
	s_nop 0
	global_load_lds_dwordx4 v[208:209], off
	v_lshl_add_u64 v[208:209], s[28:29], 0, v[150:151]
	s_add_i32 m0, s31, 0x2000
	s_nop 0
	global_load_lds_dwordx4 v[208:209], off
	v_lshl_add_u64 v[208:209], v[224:225], 0, s[16:17]
	s_mov_b32 m0, s77
	s_nop 0
	global_load_lds_dwordx4 v[208:209], off
	v_lshl_add_u64 v[208:209], v[226:227], 0, s[16:17]
	s_mov_b32 m0, s78
	s_nop 0
	global_load_lds_dwordx4 v[208:209], off
	s_waitcnt vmcnt(8)
	s_waitcnt lgkmcnt(0)
	s_barrier
	s_waitcnt lgkmcnt(0)
	v_mfma_f32_16x16x32_bf16 v[60:63], v[132:135], v[184:187], v[60:63]
	v_mfma_f32_16x16x32_bf16 v[60:63], v[136:139], v[188:191], v[60:63]
	v_mfma_f32_16x16x32_bf16 v[56:59], v[140:143], v[184:187], v[56:59]
	v_mfma_f32_16x16x32_bf16 v[56:59], v[164:167], v[188:191], v[56:59]
	v_mfma_f32_16x16x32_bf16 v[44:47], v[132:135], v[192:195], v[44:47]
	v_mfma_f32_16x16x32_bf16 v[44:47], v[136:139], v[196:199], v[44:47]
	v_mfma_f32_16x16x32_bf16 v[40:43], v[140:143], v[192:195], v[40:43]
	v_mfma_f32_16x16x32_bf16 v[40:43], v[164:167], v[196:199], v[40:43]
	v_mfma_f32_16x16x32_bf16 v[28:31], v[132:135], v[200:203], v[28:31]
	v_mfma_f32_16x16x32_bf16 v[28:31], v[136:139], v[204:207], v[28:31]
	v_mfma_f32_16x16x32_bf16 v[24:27], v[140:143], v[200:203], v[24:27]
	v_mfma_f32_16x16x32_bf16 v[24:27], v[164:167], v[204:207], v[24:27]
	v_mfma_f32_16x16x32_bf16 v[12:15], v[132:135], v[214:217], v[12:15]
	v_mfma_f32_16x16x32_bf16 v[12:15], v[136:139], v[218:221], v[12:15]
	v_mfma_f32_16x16x32_bf16 v[8:11], v[140:143], v[214:217], v[8:11]
	v_mfma_f32_16x16x32_bf16 v[8:11], v[164:167], v[218:221], v[8:11]
	v_mfma_f32_16x16x32_bf16 v[52:55], v[168:171], v[184:187], v[52:55]
	v_mfma_f32_16x16x32_bf16 v[52:55], v[172:175], v[188:191], v[52:55]
	v_mfma_f32_16x16x32_bf16 v[48:51], v[176:179], v[184:187], v[48:51]
	v_mfma_f32_16x16x32_bf16 v[48:51], v[180:183], v[188:191], v[48:51]
	v_mfma_f32_16x16x32_bf16 v[36:39], v[168:171], v[192:195], v[36:39]
	v_mfma_f32_16x16x32_bf16 v[36:39], v[172:175], v[196:199], v[36:39]
	v_mfma_f32_16x16x32_bf16 v[32:35], v[176:179], v[192:195], v[32:35]
	v_mfma_f32_16x16x32_bf16 v[32:35], v[180:183], v[196:199], v[32:35]
	v_mfma_f32_16x16x32_bf16 v[20:23], v[168:171], v[200:203], v[20:23]
	v_mfma_f32_16x16x32_bf16 v[20:23], v[172:175], v[204:207], v[20:23]
	v_mfma_f32_16x16x32_bf16 v[16:19], v[176:179], v[200:203], v[16:19]
	v_mfma_f32_16x16x32_bf16 v[16:19], v[180:183], v[204:207], v[16:19]
	v_mfma_f32_16x16x32_bf16 v[4:7], v[168:171], v[214:217], v[4:7]
	v_mfma_f32_16x16x32_bf16 v[4:7], v[172:175], v[218:221], v[4:7]
	v_mfma_f32_16x16x32_bf16 v[0:3], v[176:179], v[214:217], v[0:3]
	v_mfma_f32_16x16x32_bf16 v[0:3], v[180:183], v[218:221], v[0:3]
	s_barrier
	s_add_u32 s60, s60, 0x100
	s_addc_u32 s61, s61, 0
	s_cmp_ge_u32 s15, s22
	s_cbranch_scc0 .LBB0_1456
	s_and_b64 vcc, exec, s[8:9]
	s_cbranch_vccz .LBB0_1459
	s_barrier

; #define GAS __attribute__((address_space(1)))
; #define PG8_STAGE(bufoff, gbase, voff) do { _Pragma("unroll") for (int _i = 0; _i < 2; ++_i) \
;         __builtin_amdgcn_global_load_lds((const GAS unsigned*)((const GAS char*)(gbase) + (voff)[_i]), (PG8_LAS unsigned*)(lds + (bufoff) + ldsw + _i * 8192), 16, 0, 0); } while (0)
; #define PG8_LDA(dst, b, h) do { _Pragma("unroll") for (int m = 0; m < 4; ++m) _Pragma("unroll") for (int k = 0; k < 2; ++k) dst[m][k] = *(const PG8_LAS bf16x8*)(lds + PG8_SA(b, h) + aoff + m * 2048 + k * 1024); } while (0)
; #define PG8_LDB(dst, b, h) do { _Pragma("unroll") for (int n = 0; n < 2; ++n) _Pragma("unroll") for (int k = 0; k < 2; ++k) dst[n][k] = *(const PG8_LAS bf16x8*)(lds + PG8_SB(b, h) + boff + n * 2048 + k * 1024); } while (0)
; #define PG8_MMA(ai, bj, At, Bt) do { __builtin_amdgcn_s_setprio(1); _Pragma("unroll") for (int m = 0; m < 4; ++m) _Pragma("unroll") for (int n = 0; n < 2; ++n) _Pragma("unroll") for (int k = 0; k < 2; ++k) \
;         acc[ai][bj][m][n] = __builtin_amdgcn_mfma_f32_16x16x32_bf16(Bt[n][k], At[m][k], acc[ai][bj][m][n], 0, 0, 0); __builtin_amdgcn_s_setprio(0); } while (0)
; #define PG8_WAIT_V(n) asm volatile("s_waitcnt vmcnt(" #n ")" ::: "memory")
; template <class Epi, class Sched>
; __device__ __forceinline__ void gemm_phase_strip(PG8_LAS unsigned char* lds, PG8_LAS unsigned char* slds, PG8_LAS unsigned char* pf, const Gemm g, const Sched& S, const Epi& E, int wv) {
;     ...
;             const bool last = (t == ntu - 2);
;             const GAS char* a1 = cA + (size_t)(t + 1) * kstep;
;             const GAS char* a2 = last ? nA : cA + (size_t)(t + 2) * kstep; const GAS char* b2 = last ? nB : cB + (size_t)(t + 2) * kstep; const GAS char* s2 = last ? nS : cS + (size_t)(t + 2) * kstep;
;             const GAS char* a3 = a2 + kstep; const GAS char* b3 = b2 + kstep;
;             PG8_LDB(B0, 0, 0); PG8_LDB(B1, 0, 1); PG8_SCHED; PG8_LDA(At, 0, 0); PG8_STAGE(PG8_SA(1, 1), a1 + PG8_HS, voffA);
;             PG8_WAIT_V(8); PG8_WAIT_L(0); PG8_BAR; PG8_MMA(0, 0, At, B0); PG8_MMA(0, 1, At, B1); PG8_BAR; PG8_SCHED;
;             PG8_LDA(At, 0, 1); PG8_LDS_S(As, sq); PG8_STAGE(PG8_SB(0, 0), b2, voffB); PG8_STAGE(PG8_SB(0, 1), b2 + hstepB, voffB); PG8_STAGE(PG8_SA(0, 0), a2, voffA);
;             PG8_WAIT_V(8); PG8_WAIT_L(0); PG8_BAR; PG8_MMA(1, 0, At, B0); PG8_MMA(1, 1, At, B1); PG8_MMA_S(); PG8_BAR; PG8_SCHED;
.LBB0_1561:
	s_add_u32 s24, s12, s14
	s_addc_u32 s25, s13, s15
	s_add_u32 s40, s24, 0x100
	s_addc_u32 s41, s25, 0
	s_add_u32 s52, s21, s14
	s_addc_u32 s53, s22, s15
	s_add_i32 s58, 0, 0x10000
	s_add_i32 s59, 0, 0x14000
	v_add_u32_e32 v136, s58, v233
	ds_read_b128 v[148:151], v136
	ds_read_b128 v[144:147], v136 offset:1024
	ds_read_b128 v[166:169], v136 offset:2048
	ds_read_b128 v[162:165], v136 offset:3072
	v_add_u32_e32 v136, s59, v233
	ds_read_b128 v[156:159], v136
	ds_read_b128 v[152:155], v136 offset:1024
	ds_read_b128 v[174:177], v136 offset:2048
	ds_read_b128 v[170:173], v136 offset:3072
	s_cmpk_eq_i32 s14, 0x2b00
	s_cselect_b64 s[54:55], -1, 0
	s_and_b64 s[24:25], s[54:55], exec
	s_cselect_b32 s57, s11, s41
	s_cselect_b32 s56, s10, s40
	s_cselect_b32 s53, s45, s53
	s_cselect_b32 s52, s44, s52
	v_lshl_add_u64 v[222:223], v[220:221], 0, s[14:15]
	s_add_i32 m0, s66, 0xc000
	ds_read_b128 v[136:139], v236
	ds_read_b128 v[140:143], v236 offset:1024
	ds_read_b128 v[178:181], v236 offset:2048
	ds_read_b128 v[182:185], v236 offset:3072
	ds_read_b128 v[186:189], v236 offset:4096
	ds_read_b128 v[190:193], v236 offset:5120
	ds_read_b128 v[194:197], v236 offset:6144
	ds_read_b128 v[198:201], v236 offset:7168
	global_load_lds_dwordx4 v[222:223], off
	v_lshl_add_u64 v[222:223], v[218:219], 0, s[14:15]
	s_add_i32 m0, s66, 0xe000
	s_nop 0
	global_load_lds_dwordx4 v[222:223], off
	s_waitcnt vmcnt(8)
	s_waitcnt lgkmcnt(0)
	s_barrier
	s_waitcnt lgkmcnt(0)
	v_mfma_f32_16x16x32_bf16 v[132:135], v[148:151], v[136:139], v[132:135]
	v_mfma_f32_16x16x32_bf16 v[132:135], v[144:147], v[140:143], v[132:135]
	v_mfma_f32_16x16x32_bf16 v[128:131], v[166:169], v[136:139], v[128:131]
	v_mfma_f32_16x16x32_bf16 v[128:131], v[162:165], v[140:143], v[128:131]
	v_mfma_f32_16x16x32_bf16 v[124:127], v[148:151], v[178:181], v[124:127]
	v_mfma_f32_16x16x32_bf16 v[124:127], v[144:147], v[182:185], v[124:127]
	v_mfma_f32_16x16x32_bf16 v[120:123], v[166:169], v[178:181], v[120:123]
	v_mfma_f32_16x16x32_bf16 v[120:123], v[162:165], v[182:185], v[120:123]
	v_mfma_f32_16x16x32_bf16 v[116:119], v[148:151], v[186:189], v[116:119]
	v_mfma_f32_16x16x32_bf16 v[116:119], v[144:147], v[190:193], v[116:119]
	v_mfma_f32_16x16x32_bf16 v[112:115], v[166:169], v[186:189], v[112:115]
	v_mfma_f32_16x16x32_bf16 v[112:115], v[162:165], v[190:193], v[112:115]
	v_mfma_f32_16x16x32_bf16 v[108:111], v[148:151], v[194:197], v[108:111]
	v_mfma_f32_16x16x32_bf16 v[108:111], v[144:147], v[198:201], v[108:111]
	v_mfma_f32_16x16x32_bf16 v[104:107], v[166:169], v[194:197], v[104:107]
	v_mfma_f32_16x16x32_bf16 v[104:107], v[162:165], v[198:201], v[104:107]
	v_mfma_f32_16x16x32_bf16 v[68:71], v[156:159], v[136:139], v[68:71]
	v_mfma_f32_16x16x32_bf16 v[68:71], v[152:155], v[140:143], v[68:71]
	v_mfma_f32_16x16x32_bf16 v[64:67], v[174:177], v[136:139], v[64:67]
	v_mfma_f32_16x16x32_bf16 v[64:67], v[170:173], v[140:143], v[64:67]
	v_mfma_f32_16x16x32_bf16 v[60:63], v[156:159], v[178:181], v[60:63]
	v_mfma_f32_16x16x32_bf16 v[60:63], v[152:155], v[182:185], v[60:63]
	v_mfma_f32_16x16x32_bf16 v[56:59], v[174:177], v[178:181], v[56:59]
	v_mfma_f32_16x16x32_bf16 v[56:59], v[170:173], v[182:185], v[56:59]
	v_mfma_f32_16x16x32_bf16 v[52:55], v[156:159], v[186:189], v[52:55]
	v_mfma_f32_16x16x32_bf16 v[52:55], v[152:155], v[190:193], v[52:55]
	v_mfma_f32_16x16x32_bf16 v[48:51], v[174:177], v[186:189], v[48:51]
	v_mfma_f32_16x16x32_bf16 v[48:51], v[170:173], v[190:193], v[48:51]
	v_mfma_f32_16x16x32_bf16 v[44:47], v[156:159], v[194:197], v[44:47]
	v_mfma_f32_16x16x32_bf16 v[44:47], v[152:155], v[198:201], v[44:47]
	v_mfma_f32_16x16x32_bf16 v[40:43], v[174:177], v[194:197], v[40:43]
	v_mfma_f32_16x16x32_bf16 v[40:43], v[170:173], v[198:201], v[40:43]
	s_barrier
; #define PG8_STAGE(bufoff, gbase, voff) do { _Pragma("unroll") for (int _i = 0; _i < 2; ++_i) \
;         __builtin_amdgcn_global_load_lds((const GAS unsigned*)((const GAS char*)(gbase) + (voff)[_i]), (PG8_LAS unsigned*)(lds + (bufoff) + ldsw + _i * 8192), 16, 0, 0); } while (0)
; #define PG8_LDA(dst, b, h) do { _Pragma("unroll") for (int m = 0; m < 4; ++m) _Pragma("unroll") for (int k = 0; k < 2; ++k) dst[m][k] = *(const PG8_LAS bf16x8*)(lds + PG8_SA(b, h) + aoff + m * 2048 + k * 1024); } while (0)
; #define PG8_MMA(ai, bj, At, Bt) do { __builtin_amdgcn_s_setprio(1); _Pragma("unroll") for (int m = 0; m < 4; ++m) _Pragma("unroll") for (int n = 0; n < 2; ++n) _Pragma("unroll") for (int k = 0; k < 2; ++k) \
;         acc[ai][bj][m][n] = __builtin_amdgcn_mfma_f32_16x16x32_bf16(Bt[n][k], At[m][k], acc[ai][bj][m][n], 0, 0, 0); __builtin_amdgcn_s_setprio(0); } while (0)
; #define PG8_WAIT_V(n) asm volatile("s_waitcnt vmcnt(" #n ")" ::: "memory")
; #define PG8_WAIT_L(n) asm volatile("s_waitcnt lgkmcnt(" #n ")" ::: "memory")
; #define PG8_BAR __builtin_amdgcn_s_barrier()
; #define PG8_SCHED __builtin_amdgcn_sched_barrier(0)
; #define PG8_STAGE(bufoff, gbase, voff) do { _Pragma("unroll") for (int _i = 0; _i < 2; ++_i) \
;         __builtin_amdgcn_global_load_lds((const GAS unsigned*)((const GAS char*)(gbase) + (voff)[_i]), (PG8_LAS unsigned*)(lds + (bufoff) + ldsw + _i * 8192), 16, 0, 0); } while (0)
; #define PG8_LDA(dst, b, h) do { _Pragma("unroll") for (int m = 0; m < 4; ++m) _Pragma("unroll") for (int k = 0; k < 2; ++k) dst[m][k] = *(const PG8_LAS bf16x8*)(lds + PG8_SA(b, h) + aoff + m * 2048 + k * 1024); } while (0)
; #define PG8_LDS_S(dst, boffs) do { dst[0] = *(const PG8_LAS bf16x8*)(slds + (boffs) + soff0); dst[1] = *(const PG8_LAS bf16x8*)(slds + (boffs) + (soff0 ^ 64)); } while (0)
; #define PG8_BAR __builtin_amdgcn_s_barrier()
; template <class Epi, class Sched>
; __device__ __forceinline__ void gemm_phase_strip(PG8_LAS unsigned char* lds, PG8_LAS unsigned char* slds, PG8_LAS unsigned char* pf, const Gemm g, const Sched& S, const Epi& E, int wv) {
;     ...
;             PG8_LDA(At, 0, 1); PG8_LDS_S(As, sq); PG8_STAGE(PG8_SB(0, 0), b2, voffB); PG8_STAGE(PG8_SB(0, 1), b2 + hstepB, voffB); PG8_STAGE(PG8_SA(0, 0), a2, voffA);
;             PG8_WAIT_V(8); PG8_WAIT_L(0); PG8_BAR; PG8_MMA(1, 0, At, B0); PG8_MMA(1, 1, At, B1); PG8_MMA_S(); PG8_BAR; PG8_SCHED;
	s_add_i32 s24, s74, 0
	s_add_i32 s24, s24, 0x21000
	v_add_u32_e32 v160, s24, v234
	v_add_u32_e32 v237, s24, v235
	s_add_i32 s24, s58, s64
	v_lshl_add_u64 v[222:223], s[52:53], 0, v[204:205]
	s_mov_b32 m0, s24
	ds_read_b128 v[136:139], v236 offset:16384
	ds_read_b128 v[140:143], v236 offset:17408
	ds_read_b128 v[186:189], v236 offset:18432
	ds_read_b128 v[190:193], v236 offset:19456
	ds_read_b128 v[194:197], v236 offset:20480
	ds_read_b128 v[198:201], v236 offset:21504
	ds_read_b128 v[242:245], v236 offset:22528
	ds_read_b128 v[246:249], v236 offset:23552
	ds_read_b128 v[182:185], v160
	ds_read_b128 v[178:181], v237
	global_load_lds_dwordx4 v[222:223], off
	s_add_i32 m0, s24, 0x2000
	s_add_u32 s24, s52, 0x160000
	v_lshl_add_u64 v[224:225], s[52:53], 0, v[208:209]
	s_addc_u32 s25, s53, 0
	s_add_i32 s40, s59, s64
	global_load_lds_dwordx4 v[224:225], off
	v_lshl_add_u64 v[226:227], s[24:25], 0, v[204:205]
	s_mov_b32 m0, s40
	v_lshl_add_u64 v[228:229], s[56:57], 0, v[206:207]
	global_load_lds_dwordx4 v[226:227], off
	v_lshl_add_u64 v[226:227], s[24:25], 0, v[208:209]
	s_add_i32 m0, s40, 0x2000
	s_nop 0
	global_load_lds_dwordx4 v[226:227], off
	v_lshl_add_u64 v[226:227], s[56:57], 0, v[202:203]
	s_mov_b32 m0, s66
	s_nop 0
	global_load_lds_dwordx4 v[226:227], off
	s_mov_b32 m0, s67
	s_nop 0
	global_load_lds_dwordx4 v[228:229], off
	s_waitcnt vmcnt(8)
	s_waitcnt lgkmcnt(0)
	s_barrier
	s_waitcnt lgkmcnt(0)
	v_mfma_f32_16x16x32_bf16 v[100:103], v[148:151], v[136:139], v[100:103]
	v_mfma_f32_16x16x32_bf16 v[100:103], v[144:147], v[140:143], v[100:103]
	v_mfma_f32_16x16x32_bf16 v[96:99], v[166:169], v[136:139], v[96:99]
	v_mfma_f32_16x16x32_bf16 v[96:99], v[162:165], v[140:143], v[96:99]
	v_mfma_f32_16x16x32_bf16 v[92:95], v[148:151], v[186:189], v[92:95]
	v_mfma_f32_16x16x32_bf16 v[92:95], v[144:147], v[190:193], v[92:95]
	v_mfma_f32_16x16x32_bf16 v[88:91], v[166:169], v[186:189], v[88:91]
	v_mfma_f32_16x16x32_bf16 v[88:91], v[162:165], v[190:193], v[88:91]
	v_mfma_f32_16x16x32_bf16 v[84:87], v[148:151], v[194:197], v[84:87]
	v_mfma_f32_16x16x32_bf16 v[84:87], v[144:147], v[198:201], v[84:87]
	v_mfma_f32_16x16x32_bf16 v[80:83], v[166:169], v[194:197], v[80:83]
	v_mfma_f32_16x16x32_bf16 v[80:83], v[162:165], v[198:201], v[80:83]
	v_mfma_f32_16x16x32_bf16 v[76:79], v[148:151], v[242:245], v[76:79]
	v_mfma_f32_16x16x32_bf16 v[76:79], v[144:147], v[246:249], v[76:79]
	v_mfma_f32_16x16x32_bf16 v[72:75], v[166:169], v[242:245], v[72:75]
	v_mfma_f32_16x16x32_bf16 v[72:75], v[162:165], v[246:249], v[72:75]
	v_mfma_f32_16x16x32_bf16 v[36:39], v[156:159], v[136:139], v[36:39]
	v_mfma_f32_16x16x32_bf16 v[36:39], v[152:155], v[140:143], v[36:39]
	v_mfma_f32_16x16x32_bf16 v[32:35], v[174:177], v[136:139], v[32:35]
	v_mfma_f32_16x16x32_bf16 v[32:35], v[170:173], v[140:143], v[32:35]
	v_mfma_f32_16x16x32_bf16 v[28:31], v[156:159], v[186:189], v[28:31]
	v_mfma_f32_16x16x32_bf16 v[28:31], v[152:155], v[190:193], v[28:31]
	v_mfma_f32_16x16x32_bf16 v[24:27], v[174:177], v[186:189], v[24:27]
	v_mfma_f32_16x16x32_bf16 v[24:27], v[170:173], v[190:193], v[24:27]
	v_mfma_f32_16x16x32_bf16 v[20:23], v[156:159], v[194:197], v[20:23]
	v_mfma_f32_16x16x32_bf16 v[20:23], v[152:155], v[198:201], v[20:23]
	v_mfma_f32_16x16x32_bf16 v[16:19], v[174:177], v[194:197], v[16:19]
	v_mfma_f32_16x16x32_bf16 v[16:19], v[170:173], v[198:201], v[16:19]
	v_mfma_f32_16x16x32_bf16 v[12:15], v[156:159], v[242:245], v[12:15]
	v_mfma_f32_16x16x32_bf16 v[12:15], v[152:155], v[246:249], v[12:15]
	v_mfma_f32_16x16x32_bf16 v[8:11], v[174:177], v[242:245], v[8:11]
	v_mfma_f32_16x16x32_bf16 v[8:11], v[170:173], v[246:249], v[8:11]
	v_cndmask_b32_e64 v136, 0, 1, s[30:31]
	v_cmp_ne_u32_e64 s[40:41], 1, v136
	s_andn2_b64 vcc, exec, s[30:31]
	s_mov_b64 s[58:59], -1
	s_cbranch_vccnz .LBB0_1563
	v_mfma_f32_16x16x32_bf16 v[136:139], v[166:169], v[182:185], v[4:7]
	s_mov_b64 s[58:59], 0
	v_mfma_f32_16x16x32_bf16 v[140:143], v[174:177], v[182:185], v[0:3]
	v_mfma_f32_16x16x32_bf16 v[136:139], v[162:165], v[178:181], v[136:139]
	v_mfma_f32_16x16x32_bf16 v[140:143], v[170:173], v[178:181], v[140:143]

; #define PG8_STAGE(bufoff, gbase, voff) do { _Pragma("unroll") for (int _i = 0; _i < 2; ++_i) \
;         __builtin_amdgcn_global_load_lds((const GAS unsigned*)((const GAS char*)(gbase) + (voff)[_i]), (PG8_LAS unsigned*)(lds + (bufoff) + ldsw + _i * 8192), 16, 0, 0); } while (0)
; #define PG8_LDA(dst, b, h) do { _Pragma("unroll") for (int m = 0; m < 4; ++m) _Pragma("unroll") for (int k = 0; k < 2; ++k) dst[m][k] = *(const PG8_LAS bf16x8*)(lds + PG8_SA(b, h) + aoff + m * 2048 + k * 1024); } while (0)
; #define PG8_LDB(dst, b, h) do { _Pragma("unroll") for (int n = 0; n < 2; ++n) _Pragma("unroll") for (int k = 0; k < 2; ++k) dst[n][k] = *(const PG8_LAS bf16x8*)(lds + PG8_SB(b, h) + boff + n * 2048 + k * 1024); } while (0)
; #define PG8_MMA(ai, bj, At, Bt) do { __builtin_amdgcn_s_setprio(1); _Pragma("unroll") for (int m = 0; m < 4; ++m) _Pragma("unroll") for (int n = 0; n < 2; ++n) _Pragma("unroll") for (int k = 0; k < 2; ++k) \
;         acc[ai][bj][m][n] = __builtin_amdgcn_mfma_f32_16x16x32_bf16(Bt[n][k], At[m][k], acc[ai][bj][m][n], 0, 0, 0); __builtin_amdgcn_s_setprio(0); } while (0)
; #define PG8_WAIT_V(n) asm volatile("s_waitcnt vmcnt(" #n ")" ::: "memory")
; #define PG8_WAIT_L(n) asm volatile("s_waitcnt lgkmcnt(" #n ")" ::: "memory")
; #define PG8_BAR __builtin_amdgcn_s_barrier()
; #define PG8_SCHED __builtin_amdgcn_sched_barrier(0)
; #define PG8_WAIT_V(n) asm volatile("s_waitcnt vmcnt(" #n ")" ::: "memory")
; #define PG8_BAR __builtin_amdgcn_s_barrier()
; template <class Epi, class Sched>
; __device__ __forceinline__ void gemm_phase_strip(PG8_LAS unsigned char* lds, PG8_LAS unsigned char* slds, PG8_LAS unsigned char* pf, const Gemm g, const Sched& S, const Epi& E, int wv) {
;     ...
;             PG8_LDB(B0, 1, 0); PG8_LDB(B1, 1, 1); PG8_SCHED; PG8_LDA(At, 1, 0); PG8_STAGE(PG8_SA(0, 1), a2 + (Sched::SPLIT ? ((last && has_next) ? (nxt.kh > 0 ? -(long)hstepA : (long)hstepA) : hsA) : (long)hstepA), voffA); PG8_STAGE_S(sq ^ 4096u, s2);
;             PG8_WAIT_V(9); PG8_WAIT_L(0); PG8_BAR; PG8_MMA(0, 0, At, B0); PG8_MMA(0, 1, At, B1); PG8_BAR; PG8_SCHED;
;             PG8_LDA(At, 1, 1); PG8_LDS_S(As, sq + 2048u); PG8_STAGE(PG8_SB(1, 0), b3, voffB); PG8_STAGE(PG8_SB(1, 1), b3 + hstepB, voffB); PG8_STAGE(PG8_SA(1, 0), a3, voffA);
;             PG8_WAIT_V(9); PG8_WAIT_L(0); PG8_BAR; PG8_MMA(1, 0, At, B0); PG8_MMA(1, 1, At, B1); PG8_MMA_S(); PG8_BAR; PG8_SCHED;
.LBB0_1567:
	s_or_b64 exec, exec, s[56:57]
	s_waitcnt vmcnt(9)
	s_waitcnt lgkmcnt(0)
	s_barrier
	s_waitcnt lgkmcnt(0)
	v_mfma_f32_16x16x32_bf16 v[132:135], v[148:151], v[194:197], v[132:135]
	v_mfma_f32_16x16x32_bf16 v[132:135], v[144:147], v[198:201], v[132:135]
	v_mfma_f32_16x16x32_bf16 v[128:131], v[166:169], v[194:197], v[128:131]
	v_mfma_f32_16x16x32_bf16 v[128:131], v[162:165], v[198:201], v[128:131]
	v_mfma_f32_16x16x32_bf16 v[124:127], v[148:151], v[186:189], v[124:127]
	v_mfma_f32_16x16x32_bf16 v[124:127], v[144:147], v[190:193], v[124:127]
	v_mfma_f32_16x16x32_bf16 v[120:123], v[166:169], v[186:189], v[120:123]
	v_mfma_f32_16x16x32_bf16 v[120:123], v[162:165], v[190:193], v[120:123]
	v_mfma_f32_16x16x32_bf16 v[116:119], v[148:151], v[178:181], v[116:119]
	v_mfma_f32_16x16x32_bf16 v[116:119], v[144:147], v[182:185], v[116:119]
	v_mfma_f32_16x16x32_bf16 v[112:115], v[166:169], v[178:181], v[112:115]
	v_mfma_f32_16x16x32_bf16 v[112:115], v[162:165], v[182:185], v[112:115]
	v_mfma_f32_16x16x32_bf16 v[108:111], v[148:151], v[0:3], v[108:111]
	v_mfma_f32_16x16x32_bf16 v[108:111], v[144:147], v[4:7], v[108:111]
	v_mfma_f32_16x16x32_bf16 v[104:107], v[166:169], v[0:3], v[104:107]
	v_mfma_f32_16x16x32_bf16 v[104:107], v[162:165], v[4:7], v[104:107]
	v_mfma_f32_16x16x32_bf16 v[68:71], v[156:159], v[194:197], v[68:71]
	v_mfma_f32_16x16x32_bf16 v[64:67], v[174:177], v[194:197], v[64:67]
	v_mfma_f32_16x16x32_bf16 v[60:63], v[156:159], v[186:189], v[60:63]
	v_mfma_f32_16x16x32_bf16 v[56:59], v[174:177], v[186:189], v[56:59]
	v_mfma_f32_16x16x32_bf16 v[52:55], v[156:159], v[178:181], v[52:55]
	v_mfma_f32_16x16x32_bf16 v[48:51], v[174:177], v[178:181], v[48:51]
	v_mfma_f32_16x16x32_bf16 v[44:47], v[156:159], v[0:3], v[44:47]
	v_mfma_f32_16x16x32_bf16 v[0:3], v[174:177], v[0:3], v[40:43]
	v_mfma_f32_16x16x32_bf16 v[68:71], v[152:155], v[198:201], v[68:71]
	v_mfma_f32_16x16x32_bf16 v[64:67], v[170:173], v[198:201], v[64:67]
	v_mfma_f32_16x16x32_bf16 v[60:63], v[152:155], v[190:193], v[60:63]
	v_mfma_f32_16x16x32_bf16 v[56:59], v[170:173], v[190:193], v[56:59]
	v_mfma_f32_16x16x32_bf16 v[52:55], v[152:155], v[182:185], v[52:55]
	v_mfma_f32_16x16x32_bf16 v[48:51], v[170:173], v[182:185], v[48:51]
	v_mfma_f32_16x16x32_bf16 v[44:47], v[152:155], v[4:7], v[44:47]
	v_mfma_f32_16x16x32_bf16 v[40:43], v[170:173], v[4:7], v[0:3]
	s_barrier
	s_mov_b32 m0, s84
	v_lshl_add_u64 v[222:223], v[222:223], 0, s[16:17]
	s_add_u32 s24, s52, 0x160080
	ds_read_b128 v[0:3], v236 offset:49152
	ds_read_b128 v[4:7], v236 offset:50176
	ds_read_b128 v[186:189], v236 offset:51200
	ds_read_b128 v[190:193], v236 offset:52224
	ds_read_b128 v[194:197], v236 offset:53248
	ds_read_b128 v[198:201], v236 offset:54272
	ds_read_b128 v[242:245], v236 offset:55296
	ds_read_b128 v[246:249], v236 offset:56320
	ds_read_b128 v[182:185], v160 offset:2048
	ds_read_b128 v[178:181], v237 offset:2048
	global_load_lds_dwordx4 v[222:223], off
	v_lshl_add_u64 v[222:223], v[224:225], 0, s[16:17]
	s_mov_b32 m0, s85
	s_addc_u32 s25, s53, 0
	global_load_lds_dwordx4 v[222:223], off
	v_lshl_add_u64 v[222:223], s[24:25], 0, v[204:205]
	s_mov_b32 m0, s88
	s_nop 0
	global_load_lds_dwordx4 v[222:223], off
	v_lshl_add_u64 v[222:223], s[24:25], 0, v[208:209]
	s_mov_b32 m0, s89
	s_nop 0
	global_load_lds_dwordx4 v[222:223], off
	v_lshl_add_u64 v[222:223], v[226:227], 0, s[16:17]
	s_mov_b32 m0, s86
	s_nop 0
	global_load_lds_dwordx4 v[222:223], off
	v_lshl_add_u64 v[222:223], v[228:229], 0, s[16:17]
	s_mov_b32 m0, s87
	s_nop 0
	global_load_lds_dwordx4 v[222:223], off
	s_waitcnt vmcnt(9)
	s_waitcnt lgkmcnt(0)
	s_barrier
	s_waitcnt lgkmcnt(0)
	v_mfma_f32_16x16x32_bf16 v[100:103], v[148:151], v[0:3], v[100:103]
	v_mfma_f32_16x16x32_bf16 v[100:103], v[144:147], v[4:7], v[100:103]
	v_mfma_f32_16x16x32_bf16 v[96:99], v[166:169], v[0:3], v[96:99]
	v_mfma_f32_16x16x32_bf16 v[96:99], v[162:165], v[4:7], v[96:99]
	v_mfma_f32_16x16x32_bf16 v[92:95], v[148:151], v[186:189], v[92:95]
	v_mfma_f32_16x16x32_bf16 v[92:95], v[144:147], v[190:193], v[92:95]
	v_mfma_f32_16x16x32_bf16 v[88:91], v[166:169], v[186:189], v[88:91]
	v_mfma_f32_16x16x32_bf16 v[88:91], v[162:165], v[190:193], v[88:91]
	v_mfma_f32_16x16x32_bf16 v[84:87], v[148:151], v[194:197], v[84:87]
	v_mfma_f32_16x16x32_bf16 v[84:87], v[144:147], v[198:201], v[84:87]
	v_mfma_f32_16x16x32_bf16 v[80:83], v[166:169], v[194:197], v[80:83]
	v_mfma_f32_16x16x32_bf16 v[80:83], v[162:165], v[198:201], v[80:83]
	v_mfma_f32_16x16x32_bf16 v[76:79], v[148:151], v[242:245], v[76:79]
	v_mfma_f32_16x16x32_bf16 v[76:79], v[144:147], v[246:249], v[76:79]
	v_mfma_f32_16x16x32_bf16 v[72:75], v[166:169], v[242:245], v[72:75]
	v_mfma_f32_16x16x32_bf16 v[72:75], v[162:165], v[246:249], v[72:75]
	v_mfma_f32_16x16x32_bf16 v[36:39], v[156:159], v[0:3], v[36:39]
	v_mfma_f32_16x16x32_bf16 v[0:3], v[174:177], v[0:3], v[32:35]
	v_mfma_f32_16x16x32_bf16 v[32:35], v[170:173], v[4:7], v[0:3]
	v_mfma_f32_16x16x32_bf16 v[0:3], v[156:159], v[186:189], v[28:31]
	v_mfma_f32_16x16x32_bf16 v[28:31], v[152:155], v[190:193], v[0:3]
	v_mfma_f32_16x16x32_bf16 v[0:3], v[174:177], v[186:189], v[24:27]
	v_mfma_f32_16x16x32_bf16 v[24:27], v[170:173], v[190:193], v[0:3]
	v_mfma_f32_16x16x32_bf16 v[0:3], v[156:159], v[194:197], v[20:23]
	v_mfma_f32_16x16x32_bf16 v[20:23], v[152:155], v[198:201], v[0:3]
	v_mfma_f32_16x16x32_bf16 v[0:3], v[174:177], v[194:197], v[16:19]
	v_mfma_f32_16x16x32_bf16 v[16:19], v[170:173], v[198:201], v[0:3]
	v_mfma_f32_16x16x32_bf16 v[0:3], v[156:159], v[242:245], v[12:15]
	v_mfma_f32_16x16x32_bf16 v[12:15], v[152:155], v[246:249], v[0:3]
	v_mfma_f32_16x16x32_bf16 v[0:3], v[174:177], v[242:245], v[8:11]
	v_mfma_f32_16x16x32_bf16 v[36:39], v[152:155], v[4:7], v[36:39]
	v_mfma_f32_16x16x32_bf16 v[8:11], v[170:173], v[246:249], v[0:3]
	s_and_b64 vcc, exec, s[40:41]
	s_mov_b64 s[40:41], -1
	s_cbranch_vccnz .LBB0_1569
	v_mfma_f32_16x16x32_bf16 v[0:3], v[166:169], v[182:185], v[136:139]
	s_mov_b64 s[40:41], 0
	v_mfma_f32_16x16x32_bf16 v[166:169], v[174:177], v[182:185], v[140:143]
	v_mfma_f32_16x16x32_bf16 v[4:7], v[162:165], v[178:181], v[0:3]
	v_mfma_f32_16x16x32_bf16 v[0:3], v[170:173], v[178:181], v[166:169]

; #define PG8_STAGE(bufoff, gbase, voff) do { _Pragma("unroll") for (int _i = 0; _i < 2; ++_i) \
;         __builtin_amdgcn_global_load_lds((const GAS unsigned*)((const GAS char*)(gbase) + (voff)[_i]), (PG8_LAS unsigned*)(lds + (bufoff) + ldsw + _i * 8192), 16, 0, 0); } while (0)
; #define PG8_LDA(dst, b, h) do { _Pragma("unroll") for (int m = 0; m < 4; ++m) _Pragma("unroll") for (int k = 0; k < 2; ++k) dst[m][k] = *(const PG8_LAS bf16x8*)(lds + PG8_SA(b, h) + aoff + m * 2048 + k * 1024); } while (0)
; #define PG8_LDB(dst, b, h) do { _Pragma("unroll") for (int n = 0; n < 2; ++n) _Pragma("unroll") for (int k = 0; k < 2; ++k) dst[n][k] = *(const PG8_LAS bf16x8*)(lds + PG8_SB(b, h) + boff + n * 2048 + k * 1024); } while (0)
; #define PG8_MMA(ai, bj, At, Bt) do { __builtin_amdgcn_s_setprio(1); _Pragma("unroll") for (int m = 0; m < 4; ++m) _Pragma("unroll") for (int n = 0; n < 2; ++n) _Pragma("unroll") for (int k = 0; k < 2; ++k) \
;         acc[ai][bj][m][n] = __builtin_amdgcn_mfma_f32_16x16x32_bf16(Bt[n][k], At[m][k], acc[ai][bj][m][n], 0, 0, 0); __builtin_amdgcn_s_setprio(0); } while (0)
; #define PG8_WAIT_V(n) asm volatile("s_waitcnt vmcnt(" #n ")" ::: "memory")
; #define PG8_WAIT_L(n) asm volatile("s_waitcnt lgkmcnt(" #n ")" ::: "memory")
; #define PG8_BAR __builtin_amdgcn_s_barrier()
; #define PG8_SCHED __builtin_amdgcn_sched_barrier(0)
; #define PG8_LDA(dst, b, h) do { _Pragma("unroll") for (int m = 0; m < 4; ++m) _Pragma("unroll") for (int k = 0; k < 2; ++k) dst[m][k] = *(const PG8_LAS bf16x8*)(lds + PG8_SA(b, h) + aoff + m * 2048 + k * 1024); } while (0)
; template <class Epi, class Sched, bool ALIGN_EPI = false, bool SP2 = false>
; __device__ __forceinline__ void gemm_phase(PG8_LAS unsigned char* lds, PG8_LAS unsigned char* pf, const Gemm g, const Sched& S, const Epi& E, int wv) {
;     ...
;             PG8_LDB(B0, 0, 0); PG8_LDB(B1, 0, 1); PG8_SCHED; PG8_LDA(At, 0, 0); PG8_STAGE(PG8_SA(1, 1), a1 + (Sched::SPLIT ? hsA : (long)hstepA), voffA);
;             PG8_WAIT_V(8); PG8_WAIT_L(0); PG8_BAR; PG8_MMA(0, 0, At, B0); PG8_MMA(0, 1, At, B1); PG8_BAR; PG8_SCHED;
;             PG8_LDA(At, 0, 1); PG8_STAGE(PG8_SB(0, 0), b2, voffB); PG8_STAGE(PG8_SB(0, 1), b2 + hstepB, voffB); PG8_STAGE(PG8_SA(0, 0), a2, voffA);
;             PG8_WAIT_V(8); PG8_WAIT_L(0); PG8_BAR; PG8_MMA(1, 0, At, B0); PG8_MMA(1, 1, At, B1); PG8_BAR; PG8_SCHED;
.LBB0_1725:
	s_add_u32 s12, s10, 0x100
	s_addc_u32 s13, s11, 0
	s_add_i32 s23, 0, 0x10000
	s_cmpk_eq_i32 s22, 0x54
	s_cselect_b32 s29, s5, s13
	s_cselect_b32 s28, s4, s12
	s_cselect_b32 s15, s7, s21
	s_cselect_b32 s14, s6, s20
	s_add_i32 s24, 0, 0x14000
	v_add_u32_e32 v140, s23, v170
	v_add_u32_e32 v172, s24, v170
	ds_read_b128 v[128:131], v140
	ds_read_b128 v[132:135], v140 offset:1024
	ds_read_b128 v[136:139], v140 offset:2048
	ds_read_b128 v[140:143], v140 offset:3072
	ds_read_b128 v[144:147], v172
	ds_read_b128 v[148:151], v172 offset:1024
	ds_read_b128 v[152:155], v172 offset:2048
	ds_read_b128 v[172:175], v172 offset:3072
	v_lshl_add_u64 v[208:209], s[10:11], 0, v[166:167]
	s_add_i32 m0, s27, 0xc000
	ds_read_b128 v[176:179], v171
	ds_read_b128 v[180:183], v171 offset:1024
	ds_read_b128 v[184:187], v171 offset:2048
	ds_read_b128 v[188:191], v171 offset:3072
	ds_read_b128 v[192:195], v171 offset:4096
	ds_read_b128 v[196:199], v171 offset:5120
	ds_read_b128 v[200:203], v171 offset:6144
	ds_read_b128 v[204:207], v171 offset:7168
	global_load_lds_dwordx4 v[208:209], off
	v_lshl_add_u64 v[208:209], s[10:11], 0, v[164:165]
	s_add_i32 m0, s27, 0xe000
	s_nop 0
	global_load_lds_dwordx4 v[208:209], off
	s_waitcnt vmcnt(8)
	s_waitcnt lgkmcnt(0)
	s_barrier
	s_waitcnt lgkmcnt(0)
	v_mfma_f32_16x16x32_bf16 v[124:127], v[128:131], v[176:179], v[124:127]
	v_mfma_f32_16x16x32_bf16 v[124:127], v[132:135], v[180:183], v[124:127]
	v_mfma_f32_16x16x32_bf16 v[120:123], v[136:139], v[176:179], v[120:123]
	v_mfma_f32_16x16x32_bf16 v[120:123], v[140:143], v[180:183], v[120:123]
	v_mfma_f32_16x16x32_bf16 v[116:119], v[128:131], v[184:187], v[116:119]
	v_mfma_f32_16x16x32_bf16 v[116:119], v[132:135], v[188:191], v[116:119]
	v_mfma_f32_16x16x32_bf16 v[112:115], v[136:139], v[184:187], v[112:115]
	v_mfma_f32_16x16x32_bf16 v[112:115], v[140:143], v[188:191], v[112:115]
	v_mfma_f32_16x16x32_bf16 v[108:111], v[128:131], v[192:195], v[108:111]
	v_mfma_f32_16x16x32_bf16 v[108:111], v[132:135], v[196:199], v[108:111]
	v_mfma_f32_16x16x32_bf16 v[104:107], v[136:139], v[192:195], v[104:107]
	v_mfma_f32_16x16x32_bf16 v[104:107], v[140:143], v[196:199], v[104:107]
	v_mfma_f32_16x16x32_bf16 v[100:103], v[128:131], v[200:203], v[100:103]
	v_mfma_f32_16x16x32_bf16 v[100:103], v[132:135], v[204:207], v[100:103]
	v_mfma_f32_16x16x32_bf16 v[96:99], v[136:139], v[200:203], v[96:99]
	v_mfma_f32_16x16x32_bf16 v[96:99], v[140:143], v[204:207], v[96:99]
	v_mfma_f32_16x16x32_bf16 v[60:63], v[144:147], v[176:179], v[60:63]
	v_mfma_f32_16x16x32_bf16 v[60:63], v[148:151], v[180:183], v[60:63]
	v_mfma_f32_16x16x32_bf16 v[56:59], v[152:155], v[176:179], v[56:59]
	v_mfma_f32_16x16x32_bf16 v[56:59], v[172:175], v[180:183], v[56:59]
	v_mfma_f32_16x16x32_bf16 v[52:55], v[144:147], v[184:187], v[52:55]
	v_mfma_f32_16x16x32_bf16 v[52:55], v[148:151], v[188:191], v[52:55]
	v_mfma_f32_16x16x32_bf16 v[48:51], v[152:155], v[184:187], v[48:51]
	v_mfma_f32_16x16x32_bf16 v[48:51], v[172:175], v[188:191], v[48:51]
	v_mfma_f32_16x16x32_bf16 v[44:47], v[144:147], v[192:195], v[44:47]
	v_mfma_f32_16x16x32_bf16 v[44:47], v[148:151], v[196:199], v[44:47]
	v_mfma_f32_16x16x32_bf16 v[40:43], v[152:155], v[192:195], v[40:43]
	v_mfma_f32_16x16x32_bf16 v[40:43], v[172:175], v[196:199], v[40:43]
	v_mfma_f32_16x16x32_bf16 v[36:39], v[144:147], v[200:203], v[36:39]
	v_mfma_f32_16x16x32_bf16 v[36:39], v[148:151], v[204:207], v[36:39]
	v_mfma_f32_16x16x32_bf16 v[32:35], v[152:155], v[200:203], v[32:35]
	v_mfma_f32_16x16x32_bf16 v[32:35], v[172:175], v[204:207], v[32:35]
	s_barrier
	s_add_i32 s10, s23, s19
	v_lshl_add_u64 v[208:209], s[14:15], 0, v[160:161]
	s_mov_b32 m0, s10
	ds_read_b128 v[176:179], v171 offset:16384
	ds_read_b128 v[180:183], v171 offset:17408
	ds_read_b128 v[184:187], v171 offset:18432
	ds_read_b128 v[188:191], v171 offset:19456
	ds_read_b128 v[192:195], v171 offset:20480
	ds_read_b128 v[196:199], v171 offset:21504
	ds_read_b128 v[200:203], v171 offset:22528
	ds_read_b128 v[204:207], v171 offset:23552
	global_load_lds_dwordx4 v[208:209], off
	s_add_i32 m0, s10, 0x2000
	s_add_u32 s10, s14, 0x160000
	v_lshl_add_u64 v[214:215], s[14:15], 0, v[162:163]
	s_addc_u32 s11, s15, 0
	s_add_i32 s23, s24, s19
	global_load_lds_dwordx4 v[214:215], off
	v_lshl_add_u64 v[216:217], s[10:11], 0, v[160:161]
	s_mov_b32 m0, s23
	v_lshl_add_u64 v[218:219], s[28:29], 0, v[158:159]
	global_load_lds_dwordx4 v[216:217], off
	v_lshl_add_u64 v[216:217], s[10:11], 0, v[162:163]
	s_add_i32 m0, s23, 0x2000
	s_nop 0
	global_load_lds_dwordx4 v[216:217], off
	v_lshl_add_u64 v[216:217], s[28:29], 0, v[156:157]
	s_mov_b32 m0, s27
	s_nop 0
	global_load_lds_dwordx4 v[216:217], off
	s_mov_b32 m0, s30
	s_nop 0
	global_load_lds_dwordx4 v[218:219], off
	s_waitcnt vmcnt(8)
	s_waitcnt lgkmcnt(0)
	s_barrier
; #define PG8_STAGE(bufoff, gbase, voff) do { _Pragma("unroll") for (int _i = 0; _i < 2; ++_i) \
;         __builtin_amdgcn_global_load_lds((const GAS unsigned*)((const GAS char*)(gbase) + (voff)[_i]), (PG8_LAS unsigned*)(lds + (bufoff) + ldsw + _i * 8192), 16, 0, 0); } while (0)
; #define PG8_LDA(dst, b, h) do { _Pragma("unroll") for (int m = 0; m < 4; ++m) _Pragma("unroll") for (int k = 0; k < 2; ++k) dst[m][k] = *(const PG8_LAS bf16x8*)(lds + PG8_SA(b, h) + aoff + m * 2048 + k * 1024); } while (0)
; #define PG8_LDB(dst, b, h) do { _Pragma("unroll") for (int n = 0; n < 2; ++n) _Pragma("unroll") for (int k = 0; k < 2; ++k) dst[n][k] = *(const PG8_LAS bf16x8*)(lds + PG8_SB(b, h) + boff + n * 2048 + k * 1024); } while (0)
; #define PG8_MMA(ai, bj, At, Bt) do { __builtin_amdgcn_s_setprio(1); _Pragma("unroll") for (int m = 0; m < 4; ++m) _Pragma("unroll") for (int n = 0; n < 2; ++n) _Pragma("unroll") for (int k = 0; k < 2; ++k) \
;         acc[ai][bj][m][n] = __builtin_amdgcn_mfma_f32_16x16x32_bf16(Bt[n][k], At[m][k], acc[ai][bj][m][n], 0, 0, 0); __builtin_amdgcn_s_setprio(0); } while (0)
; #define PG8_WAIT_V(n) asm volatile("s_waitcnt vmcnt(" #n ")" ::: "memory")
; #define PG8_WAIT_L(n) asm volatile("s_waitcnt lgkmcnt(" #n ")" ::: "memory")
; #define PG8_BAR __builtin_amdgcn_s_barrier()
; #define PG8_SCHED __builtin_amdgcn_sched_barrier(0)
; #define PG8_WAIT_V(n) asm volatile("s_waitcnt vmcnt(" #n ")" ::: "memory")
; #define PG8_WAIT_L(n) asm volatile("s_waitcnt lgkmcnt(" #n ")" ::: "memory")
; template <class Epi, class Sched, bool ALIGN_EPI = false, bool SP2 = false>
; __device__ __forceinline__ void gemm_phase(PG8_LAS unsigned char* lds, PG8_LAS unsigned char* pf, const Gemm g, const Sched& S, const Epi& E, int wv) {
;     ...
;             PG8_LDA(At, 0, 1); PG8_STAGE(PG8_SB(0, 0), b2, voffB); PG8_STAGE(PG8_SB(0, 1), b2 + hstepB, voffB); PG8_STAGE(PG8_SA(0, 0), a2, voffA);
;             PG8_WAIT_V(8); PG8_WAIT_L(0); PG8_BAR; PG8_MMA(1, 0, At, B0); PG8_MMA(1, 1, At, B1); PG8_BAR; PG8_SCHED;
;             PG8_LDB(B0, 1, 0); PG8_LDB(B1, 1, 1); PG8_SCHED; PG8_LDA(At, 1, 0); PG8_STAGE(PG8_SA(0, 1), a2 + (Sched::SPLIT ? ((last && has_next) ? (nxt.kh > 0 ? -(long)hstepA : (long)hstepA) : hsA) : (long)hstepA), voffA);
;             PG8_WAIT_V(8); PG8_WAIT_L(0); PG8_BAR; PG8_MMA(0, 0, At, B0); PG8_MMA(0, 1, At, B1); PG8_BAR; PG8_SCHED;
	s_waitcnt lgkmcnt(0)
	v_mfma_f32_16x16x32_bf16 v[92:95], v[128:131], v[176:179], v[92:95]
	v_mfma_f32_16x16x32_bf16 v[92:95], v[132:135], v[180:183], v[92:95]
	v_mfma_f32_16x16x32_bf16 v[88:91], v[136:139], v[176:179], v[88:91]
	v_mfma_f32_16x16x32_bf16 v[88:91], v[140:143], v[180:183], v[88:91]
	v_mfma_f32_16x16x32_bf16 v[84:87], v[128:131], v[184:187], v[84:87]
	v_mfma_f32_16x16x32_bf16 v[84:87], v[132:135], v[188:191], v[84:87]
	v_mfma_f32_16x16x32_bf16 v[80:83], v[136:139], v[184:187], v[80:83]
	v_mfma_f32_16x16x32_bf16 v[80:83], v[140:143], v[188:191], v[80:83]
	v_mfma_f32_16x16x32_bf16 v[76:79], v[128:131], v[192:195], v[76:79]
	v_mfma_f32_16x16x32_bf16 v[76:79], v[132:135], v[196:199], v[76:79]
	v_mfma_f32_16x16x32_bf16 v[72:75], v[136:139], v[192:195], v[72:75]
	v_mfma_f32_16x16x32_bf16 v[72:75], v[140:143], v[196:199], v[72:75]
	v_mfma_f32_16x16x32_bf16 v[68:71], v[128:131], v[200:203], v[68:71]
	v_mfma_f32_16x16x32_bf16 v[68:71], v[132:135], v[204:207], v[68:71]
	v_mfma_f32_16x16x32_bf16 v[64:67], v[136:139], v[200:203], v[64:67]
	v_mfma_f32_16x16x32_bf16 v[64:67], v[140:143], v[204:207], v[64:67]
	v_mfma_f32_16x16x32_bf16 v[28:31], v[144:147], v[176:179], v[28:31]
	v_mfma_f32_16x16x32_bf16 v[28:31], v[148:151], v[180:183], v[28:31]
	v_mfma_f32_16x16x32_bf16 v[24:27], v[152:155], v[176:179], v[24:27]
	v_mfma_f32_16x16x32_bf16 v[24:27], v[172:175], v[180:183], v[24:27]
	v_mfma_f32_16x16x32_bf16 v[20:23], v[144:147], v[184:187], v[20:23]
	v_mfma_f32_16x16x32_bf16 v[20:23], v[148:151], v[188:191], v[20:23]
	v_mfma_f32_16x16x32_bf16 v[16:19], v[152:155], v[184:187], v[16:19]
	v_mfma_f32_16x16x32_bf16 v[16:19], v[172:175], v[188:191], v[16:19]
	v_mfma_f32_16x16x32_bf16 v[12:15], v[144:147], v[192:195], v[12:15]
	v_mfma_f32_16x16x32_bf16 v[12:15], v[148:151], v[196:199], v[12:15]
	v_mfma_f32_16x16x32_bf16 v[8:11], v[152:155], v[192:195], v[8:11]
	v_mfma_f32_16x16x32_bf16 v[8:11], v[172:175], v[196:199], v[8:11]
	v_mfma_f32_16x16x32_bf16 v[4:7], v[144:147], v[200:203], v[4:7]
	v_mfma_f32_16x16x32_bf16 v[4:7], v[148:151], v[204:207], v[4:7]
	v_mfma_f32_16x16x32_bf16 v[0:3], v[152:155], v[200:203], v[0:3]
	v_mfma_f32_16x16x32_bf16 v[0:3], v[172:175], v[204:207], v[0:3]
	s_barrier
	s_add_i32 s23, 0, 0x18000
	s_add_i32 s24, 0, 0x1c000
	v_add_u32_e32 v140, s23, v170
	v_add_u32_e32 v172, s24, v170
	ds_read_b128 v[128:131], v140
	ds_read_b128 v[132:135], v140 offset:1024
	ds_read_b128 v[136:139], v140 offset:2048
	ds_read_b128 v[140:143], v140 offset:3072
	ds_read_b128 v[144:147], v172
	ds_read_b128 v[148:151], v172 offset:1024
	ds_read_b128 v[152:155], v172 offset:2048
	ds_read_b128 v[172:175], v172 offset:3072
	s_add_u32 s10, s28, 0x160000
	s_addc_u32 s11, s29, 0
	s_mov_b32 m0, s31
	v_lshl_add_u64 v[220:221], s[10:11], 0, v[156:157]
	ds_read_b128 v[176:179], v171 offset:32768
	ds_read_b128 v[180:183], v171 offset:33792
	ds_read_b128 v[184:187], v171 offset:34816
	ds_read_b128 v[188:191], v171 offset:35840
	ds_read_b128 v[192:195], v171 offset:36864
	ds_read_b128 v[196:199], v171 offset:37888
	ds_read_b128 v[200:203], v171 offset:38912
	ds_read_b128 v[204:207], v171 offset:39936
	global_load_lds_dwordx4 v[220:221], off
	v_lshl_add_u64 v[220:221], s[10:11], 0, v[158:159]
	s_mov_b32 m0, s38
	s_nop 0
	global_load_lds_dwordx4 v[220:221], off
	s_waitcnt vmcnt(8)
	s_waitcnt lgkmcnt(0)
	s_barrier
	s_waitcnt lgkmcnt(0)
	v_mfma_f32_16x16x32_bf16 v[124:127], v[128:131], v[176:179], v[124:127]
	v_mfma_f32_16x16x32_bf16 v[124:127], v[132:135], v[180:183], v[124:127]
	v_mfma_f32_16x16x32_bf16 v[120:123], v[136:139], v[176:179], v[120:123]
	v_mfma_f32_16x16x32_bf16 v[120:123], v[140:143], v[180:183], v[120:123]
	v_mfma_f32_16x16x32_bf16 v[116:119], v[128:131], v[184:187], v[116:119]
	v_mfma_f32_16x16x32_bf16 v[116:119], v[132:135], v[188:191], v[116:119]
	v_mfma_f32_16x16x32_bf16 v[112:115], v[136:139], v[184:187], v[112:115]
	v_mfma_f32_16x16x32_bf16 v[112:115], v[140:143], v[188:191], v[112:115]
	v_mfma_f32_16x16x32_bf16 v[108:111], v[128:131], v[192:195], v[108:111]
	v_mfma_f32_16x16x32_bf16 v[108:111], v[132:135], v[196:199], v[108:111]
	v_mfma_f32_16x16x32_bf16 v[104:107], v[136:139], v[192:195], v[104:107]
	v_mfma_f32_16x16x32_bf16 v[104:107], v[140:143], v[196:199], v[104:107]
	v_mfma_f32_16x16x32_bf16 v[100:103], v[128:131], v[200:203], v[100:103]
	v_mfma_f32_16x16x32_bf16 v[100:103], v[132:135], v[204:207], v[100:103]
	v_mfma_f32_16x16x32_bf16 v[96:99], v[136:139], v[200:203], v[96:99]
	v_mfma_f32_16x16x32_bf16 v[96:99], v[140:143], v[204:207], v[96:99]
	v_mfma_f32_16x16x32_bf16 v[60:63], v[144:147], v[176:179], v[60:63]
	v_mfma_f32_16x16x32_bf16 v[60:63], v[148:151], v[180:183], v[60:63]
	v_mfma_f32_16x16x32_bf16 v[56:59], v[152:155], v[176:179], v[56:59]
	v_mfma_f32_16x16x32_bf16 v[56:59], v[172:175], v[180:183], v[56:59]
	v_mfma_f32_16x16x32_bf16 v[52:55], v[144:147], v[184:187], v[52:55]
	v_mfma_f32_16x16x32_bf16 v[52:55], v[148:151], v[188:191], v[52:55]
	v_mfma_f32_16x16x32_bf16 v[48:51], v[152:155], v[184:187], v[48:51]
	v_mfma_f32_16x16x32_bf16 v[48:51], v[172:175], v[188:191], v[48:51]
	v_mfma_f32_16x16x32_bf16 v[44:47], v[144:147], v[192:195], v[44:47]
	v_mfma_f32_16x16x32_bf16 v[44:47], v[148:151], v[196:199], v[44:47]
	v_mfma_f32_16x16x32_bf16 v[40:43], v[152:155], v[192:195], v[40:43]
	v_mfma_f32_16x16x32_bf16 v[40:43], v[172:175], v[196:199], v[40:43]
	v_mfma_f32_16x16x32_bf16 v[36:39], v[144:147], v[200:203], v[36:39]
	v_mfma_f32_16x16x32_bf16 v[36:39], v[148:151], v[204:207], v[36:39]
	v_mfma_f32_16x16x32_bf16 v[32:35], v[152:155], v[200:203], v[32:35]
	v_mfma_f32_16x16x32_bf16 v[32:35], v[172:175], v[204:207], v[32:35]
	s_barrier
; #define PG8_STAGE(bufoff, gbase, voff) do { _Pragma("unroll") for (int _i = 0; _i < 2; ++_i) \
;         __builtin_amdgcn_global_load_lds((const GAS unsigned*)((const GAS char*)(gbase) + (voff)[_i]), (PG8_LAS unsigned*)(lds + (bufoff) + ldsw + _i * 8192), 16, 0, 0); } while (0)
; #define PG8_LDA(dst, b, h) do { _Pragma("unroll") for (int m = 0; m < 4; ++m) _Pragma("unroll") for (int k = 0; k < 2; ++k) dst[m][k] = *(const PG8_LAS bf16x8*)(lds + PG8_SA(b, h) + aoff + m * 2048 + k * 1024); } while (0)
; #define PG8_LDB(dst, b, h) do { _Pragma("unroll") for (int n = 0; n < 2; ++n) _Pragma("unroll") for (int k = 0; k < 2; ++k) dst[n][k] = *(const PG8_LAS bf16x8*)(lds + PG8_SB(b, h) + boff + n * 2048 + k * 1024); } while (0)
; #define PG8_MMA(ai, bj, At, Bt) do { __builtin_amdgcn_s_setprio(1); _Pragma("unroll") for (int m = 0; m < 4; ++m) _Pragma("unroll") for (int n = 0; n < 2; ++n) _Pragma("unroll") for (int k = 0; k < 2; ++k) \
;         acc[ai][bj][m][n] = __builtin_amdgcn_mfma_f32_16x16x32_bf16(Bt[n][k], At[m][k], acc[ai][bj][m][n], 0, 0, 0); __builtin_amdgcn_s_setprio(0); } while (0)
; #define PG8_WAIT_V(n) asm volatile("s_waitcnt vmcnt(" #n ")" ::: "memory")
; #define PG8_WAIT_L(n) asm volatile("s_waitcnt lgkmcnt(" #n ")" ::: "memory")
; #define PG8_BAR __builtin_amdgcn_s_barrier()
; #define PG8_SCHED __builtin_amdgcn_sched_barrier(0)
; #define PG8_WAIT_V(n) asm volatile("s_waitcnt vmcnt(" #n ")" ::: "memory")
; #define PG8_WAIT_L(n) asm volatile("s_waitcnt lgkmcnt(" #n ")" ::: "memory")
; template <class Epi, class Sched, bool ALIGN_EPI = false, bool SP2 = false>
; __device__ __forceinline__ void gemm_phase(PG8_LAS unsigned char* lds, PG8_LAS unsigned char* pf, const Gemm g, const Sched& S, const Epi& E, int wv) {
;     ...
;             PG8_LDB(B0, 1, 0); PG8_LDB(B1, 1, 1); PG8_SCHED; PG8_LDA(At, 1, 0); PG8_STAGE(PG8_SA(0, 1), a2 + (Sched::SPLIT ? ((last && has_next) ? (nxt.kh > 0 ? -(long)hstepA : (long)hstepA) : hsA) : (long)hstepA), voffA);
;             PG8_WAIT_V(8); PG8_WAIT_L(0); PG8_BAR; PG8_MMA(0, 0, At, B0); PG8_MMA(0, 1, At, B1); PG8_BAR; PG8_SCHED;
;             PG8_LDA(At, 1, 1); PG8_STAGE(PG8_SB(1, 0), b3, voffB); PG8_STAGE(PG8_SB(1, 1), b3 + hstepB, voffB); PG8_STAGE(PG8_SA(1, 0), a3, voffA);
;             PG8_WAIT_V(8); PG8_WAIT_L(0); PG8_BAR; PG8_MMA(1, 0, At, B0); PG8_MMA(1, 1, At, B1); PG8_BAR; PG8_SCHED;
	s_add_i32 s10, s23, s19
	v_lshl_add_u64 v[208:209], v[208:209], 0, s[16:17]
	s_mov_b32 m0, s10
	ds_read_b128 v[176:179], v171 offset:49152
	ds_read_b128 v[180:183], v171 offset:50176
	ds_read_b128 v[184:187], v171 offset:51200
	ds_read_b128 v[188:191], v171 offset:52224
	ds_read_b128 v[192:195], v171 offset:53248
	ds_read_b128 v[196:199], v171 offset:54272
	ds_read_b128 v[200:203], v171 offset:55296
	ds_read_b128 v[204:207], v171 offset:56320
	global_load_lds_dwordx4 v[208:209], off
	s_add_i32 m0, s10, 0x2000
	s_add_u32 s10, s14, 0x160080
	v_lshl_add_u64 v[208:209], v[214:215], 0, s[16:17]
	s_addc_u32 s11, s15, 0
	s_add_i32 s14, s24, s19
	global_load_lds_dwordx4 v[208:209], off
	v_lshl_add_u64 v[208:209], s[10:11], 0, v[160:161]
	s_mov_b32 m0, s14
	s_nop 0
	global_load_lds_dwordx4 v[208:209], off
	v_lshl_add_u64 v[208:209], s[10:11], 0, v[162:163]
	s_add_i32 m0, s14, 0x2000
	s_nop 0
	global_load_lds_dwordx4 v[208:209], off
	v_lshl_add_u64 v[208:209], v[216:217], 0, s[16:17]
	s_mov_b32 m0, s41
	s_nop 0
	global_load_lds_dwordx4 v[208:209], off
	v_lshl_add_u64 v[208:209], v[218:219], 0, s[16:17]
	s_mov_b32 m0, s42
	s_nop 0
	global_load_lds_dwordx4 v[208:209], off
	s_waitcnt vmcnt(8)
	s_waitcnt lgkmcnt(0)
	s_barrier
	s_waitcnt lgkmcnt(0)
	v_mfma_f32_16x16x32_bf16 v[92:95], v[128:131], v[176:179], v[92:95]
	v_mfma_f32_16x16x32_bf16 v[92:95], v[132:135], v[180:183], v[92:95]
	v_mfma_f32_16x16x32_bf16 v[88:91], v[136:139], v[176:179], v[88:91]
	v_mfma_f32_16x16x32_bf16 v[88:91], v[140:143], v[180:183], v[88:91]
	v_mfma_f32_16x16x32_bf16 v[84:87], v[128:131], v[184:187], v[84:87]
	v_mfma_f32_16x16x32_bf16 v[84:87], v[132:135], v[188:191], v[84:87]
	v_mfma_f32_16x16x32_bf16 v[80:83], v[136:139], v[184:187], v[80:83]
	v_mfma_f32_16x16x32_bf16 v[80:83], v[140:143], v[188:191], v[80:83]
	v_mfma_f32_16x16x32_bf16 v[76:79], v[128:131], v[192:195], v[76:79]
	v_mfma_f32_16x16x32_bf16 v[76:79], v[132:135], v[196:199], v[76:79]
	v_mfma_f32_16x16x32_bf16 v[72:75], v[136:139], v[192:195], v[72:75]
	v_mfma_f32_16x16x32_bf16 v[72:75], v[140:143], v[196:199], v[72:75]
	v_mfma_f32_16x16x32_bf16 v[68:71], v[128:131], v[200:203], v[68:71]
	v_mfma_f32_16x16x32_bf16 v[68:71], v[132:135], v[204:207], v[68:71]
	v_mfma_f32_16x16x32_bf16 v[64:67], v[136:139], v[200:203], v[64:67]
	v_mfma_f32_16x16x32_bf16 v[64:67], v[140:143], v[204:207], v[64:67]
	v_mfma_f32_16x16x32_bf16 v[28:31], v[144:147], v[176:179], v[28:31]
	v_mfma_f32_16x16x32_bf16 v[28:31], v[148:151], v[180:183], v[28:31]
	v_mfma_f32_16x16x32_bf16 v[24:27], v[152:155], v[176:179], v[24:27]
	v_mfma_f32_16x16x32_bf16 v[24:27], v[172:175], v[180:183], v[24:27]
	v_mfma_f32_16x16x32_bf16 v[20:23], v[144:147], v[184:187], v[20:23]
	v_mfma_f32_16x16x32_bf16 v[20:23], v[148:151], v[188:191], v[20:23]
	v_mfma_f32_16x16x32_bf16 v[16:19], v[152:155], v[184:187], v[16:19]
	v_mfma_f32_16x16x32_bf16 v[16:19], v[172:175], v[188:191], v[16:19]
	v_mfma_f32_16x16x32_bf16 v[12:15], v[144:147], v[192:195], v[12:15]
	v_mfma_f32_16x16x32_bf16 v[12:15], v[148:151], v[196:199], v[12:15]
	v_mfma_f32_16x16x32_bf16 v[8:11], v[152:155], v[192:195], v[8:11]
	v_mfma_f32_16x16x32_bf16 v[8:11], v[172:175], v[196:199], v[8:11]
	v_mfma_f32_16x16x32_bf16 v[4:7], v[144:147], v[200:203], v[4:7]
	v_mfma_f32_16x16x32_bf16 v[4:7], v[148:151], v[204:207], v[4:7]
	v_mfma_f32_16x16x32_bf16 v[0:3], v[152:155], v[200:203], v[0:3]
	v_mfma_f32_16x16x32_bf16 v[0:3], v[172:175], v[204:207], v[0:3]
	s_barrier
	s_add_i32 s22, s22, 2
	s_add_u32 s20, s20, 0x100
	s_addc_u32 s21, s21, 0
	s_cmpk_gt_u32 s22, 0x55
	s_mov_b64 s[10:11], s[12:13]
	s_cbranch_scc0 .LBB0_1725
	s_and_b64 vcc, exec, s[2:3]
	s_cbranch_vccz .LBB0_1728
	s_barrier

; #define PG8_STAGE(bufoff, gbase, voff) do { _Pragma("unroll") for (int _i = 0; _i < 2; ++_i) \
;         __builtin_amdgcn_global_load_lds((const GAS unsigned*)((const GAS char*)(gbase) + (voff)[_i]), (PG8_LAS unsigned*)(lds + (bufoff) + ldsw + _i * 8192), 16, 0, 0); } while (0)
; #define PG8_LDA(dst, b, h) do { _Pragma("unroll") for (int m = 0; m < 4; ++m) _Pragma("unroll") for (int k = 0; k < 2; ++k) dst[m][k] = *(const PG8_LAS bf16x8*)(lds + PG8_SA(b, h) + aoff + m * 2048 + k * 1024); } while (0)
; #define PG8_LDB(dst, b, h) do { _Pragma("unroll") for (int n = 0; n < 2; ++n) _Pragma("unroll") for (int k = 0; k < 2; ++k) dst[n][k] = *(const PG8_LAS bf16x8*)(lds + PG8_SB(b, h) + boff + n * 2048 + k * 1024); } while (0)
; #define PG8_MMA(ai, bj, At, Bt) do { __builtin_amdgcn_s_setprio(1); _Pragma("unroll") for (int m = 0; m < 4; ++m) _Pragma("unroll") for (int n = 0; n < 2; ++n) _Pragma("unroll") for (int k = 0; k < 2; ++k) \
;         acc[ai][bj][m][n] = __builtin_amdgcn_mfma_f32_16x16x32_bf16(Bt[n][k], At[m][k], acc[ai][bj][m][n], 0, 0, 0); __builtin_amdgcn_s_setprio(0); } while (0)
; #define PG8_WAIT_V(n) asm volatile("s_waitcnt vmcnt(" #n ")" ::: "memory")
; #define PG8_WAIT_L(n) asm volatile("s_waitcnt lgkmcnt(" #n ")" ::: "memory")
; #define PG8_BAR __builtin_amdgcn_s_barrier()
; #define PG8_SCHED __builtin_amdgcn_sched_barrier(0)
; #define PG8_LDA(dst, b, h) do { _Pragma("unroll") for (int m = 0; m < 4; ++m) _Pragma("unroll") for (int k = 0; k < 2; ++k) dst[m][k] = *(const PG8_LAS bf16x8*)(lds + PG8_SA(b, h) + aoff + m * 2048 + k * 1024); } while (0)
; template <class Epi, class Sched, bool ALIGN_EPI = false, bool SP2 = false>
; __device__ __forceinline__ void gemm_phase(PG8_LAS unsigned char* lds, PG8_LAS unsigned char* pf, const Gemm g, const Sched& S, const Epi& E, int wv) {
;     ...
;             PG8_LDB(B0, 0, 0); PG8_LDB(B1, 0, 1); PG8_SCHED; PG8_LDA(At, 0, 0); PG8_STAGE(PG8_SA(1, 1), a1 + (Sched::SPLIT ? hsA : (long)hstepA), voffA);
;             PG8_WAIT_V(8); PG8_WAIT_L(0); PG8_BAR; PG8_MMA(0, 0, At, B0); PG8_MMA(0, 1, At, B1); PG8_BAR; PG8_SCHED;
;             PG8_LDA(At, 0, 1); PG8_STAGE(PG8_SB(0, 0), b2, voffB); PG8_STAGE(PG8_SB(0, 1), b2 + hstepB, voffB); PG8_STAGE(PG8_SA(0, 0), a2, voffA);
;             PG8_WAIT_V(8); PG8_WAIT_L(0); PG8_BAR; PG8_MMA(1, 0, At, B0); PG8_MMA(1, 1, At, B1); PG8_BAR; PG8_SCHED;
.LBB0_1760:
	s_add_u32 s12, s10, 0x100
	s_addc_u32 s13, s11, 0
	s_add_i32 s24, 0, 0x10000
	s_cmpk_eq_i32 s23, 0x54
	s_cselect_b32 s37, s9, s13
	s_cselect_b32 s36, s8, s12
	s_cselect_b32 s15, s29, s22
	s_cselect_b32 s14, s28, s21
	s_add_i32 s25, 0, 0x14000
	v_add_u32_e32 v108, s24, v224
	v_add_u32_e32 v160, s25, v224
	ds_read_b128 v[92:95], v108
	ds_read_b128 v[100:103], v108 offset:1024
	ds_read_b128 v[104:107], v108 offset:2048
	ds_read_b128 v[108:111], v108 offset:3072
	ds_read_b128 v[112:115], v160
	ds_read_b128 v[116:119], v160 offset:1024
	ds_read_b128 v[152:155], v160 offset:2048
	ds_read_b128 v[170:173], v160 offset:3072
	v_lshl_add_u64 v[206:207], s[10:11], 0, v[168:169]
	s_add_i32 m0, s57, 0xc000
	ds_read_b128 v[174:177], v225
	ds_read_b128 v[178:181], v225 offset:1024
	ds_read_b128 v[182:185], v225 offset:2048
	ds_read_b128 v[186:189], v225 offset:3072
	ds_read_b128 v[190:193], v225 offset:4096
	ds_read_b128 v[194:197], v225 offset:5120
	ds_read_b128 v[198:201], v225 offset:6144
	ds_read_b128 v[202:205], v225 offset:7168
	global_load_lds_dwordx4 v[206:207], off
	v_lshl_add_u64 v[206:207], s[10:11], 0, v[166:167]
	s_add_i32 m0, s57, 0xe000
	s_nop 0
	global_load_lds_dwordx4 v[206:207], off
	s_waitcnt vmcnt(8)
	s_waitcnt lgkmcnt(0)
	s_barrier
	s_waitcnt lgkmcnt(0)
	v_mfma_f32_16x16x32_bf16 v[148:151], v[92:95], v[174:177], v[148:151]
	v_mfma_f32_16x16x32_bf16 v[148:151], v[100:103], v[178:181], v[148:151]
	v_mfma_f32_16x16x32_bf16 v[144:147], v[104:107], v[174:177], v[144:147]
	v_mfma_f32_16x16x32_bf16 v[144:147], v[108:111], v[178:181], v[144:147]
	v_mfma_f32_16x16x32_bf16 v[140:143], v[92:95], v[182:185], v[140:143]
	v_mfma_f32_16x16x32_bf16 v[140:143], v[100:103], v[186:189], v[140:143]
	v_mfma_f32_16x16x32_bf16 v[136:139], v[104:107], v[182:185], v[136:139]
	v_mfma_f32_16x16x32_bf16 v[136:139], v[108:111], v[186:189], v[136:139]
	v_mfma_f32_16x16x32_bf16 v[132:135], v[92:95], v[190:193], v[132:135]
	v_mfma_f32_16x16x32_bf16 v[132:135], v[100:103], v[194:197], v[132:135]
	v_mfma_f32_16x16x32_bf16 v[128:131], v[104:107], v[190:193], v[128:131]
	v_mfma_f32_16x16x32_bf16 v[128:131], v[108:111], v[194:197], v[128:131]
	v_mfma_f32_16x16x32_bf16 v[124:127], v[92:95], v[198:201], v[124:127]
	v_mfma_f32_16x16x32_bf16 v[124:127], v[100:103], v[202:205], v[124:127]
	v_mfma_f32_16x16x32_bf16 v[120:123], v[104:107], v[198:201], v[120:123]
	v_mfma_f32_16x16x32_bf16 v[120:123], v[108:111], v[202:205], v[120:123]
	v_mfma_f32_16x16x32_bf16 v[96:99], v[112:115], v[174:177], v[96:99]
	v_mfma_f32_16x16x32_bf16 v[96:99], v[116:119], v[178:181], v[96:99]
	v_mfma_f32_16x16x32_bf16 v[88:91], v[152:155], v[174:177], v[88:91]
	v_mfma_f32_16x16x32_bf16 v[88:91], v[170:173], v[178:181], v[88:91]
	v_mfma_f32_16x16x32_bf16 v[84:87], v[112:115], v[182:185], v[84:87]
	v_mfma_f32_16x16x32_bf16 v[84:87], v[116:119], v[186:189], v[84:87]
	v_mfma_f32_16x16x32_bf16 v[80:83], v[152:155], v[182:185], v[80:83]
	v_mfma_f32_16x16x32_bf16 v[80:83], v[170:173], v[186:189], v[80:83]
	v_mfma_f32_16x16x32_bf16 v[76:79], v[112:115], v[190:193], v[76:79]
	v_mfma_f32_16x16x32_bf16 v[76:79], v[116:119], v[194:197], v[76:79]
	v_mfma_f32_16x16x32_bf16 v[72:75], v[152:155], v[190:193], v[72:75]
	v_mfma_f32_16x16x32_bf16 v[72:75], v[170:173], v[194:197], v[72:75]
	v_mfma_f32_16x16x32_bf16 v[68:71], v[112:115], v[198:201], v[68:71]
	v_mfma_f32_16x16x32_bf16 v[68:71], v[116:119], v[202:205], v[68:71]
	v_mfma_f32_16x16x32_bf16 v[64:67], v[152:155], v[198:201], v[64:67]
	v_mfma_f32_16x16x32_bf16 v[64:67], v[170:173], v[202:205], v[64:67]
	s_barrier
	s_add_i32 s10, s24, s27
	v_lshl_add_u64 v[206:207], s[14:15], 0, v[158:159]
	s_mov_b32 m0, s10
	ds_read_b128 v[174:177], v225 offset:16384
	ds_read_b128 v[178:181], v225 offset:17408
	ds_read_b128 v[182:185], v225 offset:18432
	ds_read_b128 v[186:189], v225 offset:19456
	ds_read_b128 v[190:193], v225 offset:20480
	ds_read_b128 v[194:197], v225 offset:21504
	ds_read_b128 v[198:201], v225 offset:22528
	ds_read_b128 v[202:205], v225 offset:23552
	global_load_lds_dwordx4 v[206:207], off
	s_add_i32 m0, s10, 0x2000
	s_add_u32 s10, s14, 0x160000
	v_lshl_add_u64 v[208:209], s[14:15], 0, v[164:165]
	s_addc_u32 s11, s15, 0
	s_add_i32 s24, s25, s27
	global_load_lds_dwordx4 v[208:209], off
	v_lshl_add_u64 v[214:215], s[10:11], 0, v[158:159]
	s_mov_b32 m0, s24
	v_lshl_add_u64 v[216:217], s[36:37], 0, v[162:163]
	global_load_lds_dwordx4 v[214:215], off
	v_lshl_add_u64 v[214:215], s[10:11], 0, v[164:165]
	s_add_i32 m0, s24, 0x2000
	s_nop 0
	global_load_lds_dwordx4 v[214:215], off
	v_lshl_add_u64 v[214:215], s[36:37], 0, v[156:157]
	s_mov_b32 m0, s57
	s_nop 0
	global_load_lds_dwordx4 v[214:215], off
	s_mov_b32 m0, s58
	s_nop 0
	global_load_lds_dwordx4 v[216:217], off
	s_waitcnt vmcnt(8)
	s_waitcnt lgkmcnt(0)
	s_barrier
; #define PG8_STAGE(bufoff, gbase, voff) do { _Pragma("unroll") for (int _i = 0; _i < 2; ++_i) \
;         __builtin_amdgcn_global_load_lds((const GAS unsigned*)((const GAS char*)(gbase) + (voff)[_i]), (PG8_LAS unsigned*)(lds + (bufoff) + ldsw + _i * 8192), 16, 0, 0); } while (0)
; #define PG8_LDA(dst, b, h) do { _Pragma("unroll") for (int m = 0; m < 4; ++m) _Pragma("unroll") for (int k = 0; k < 2; ++k) dst[m][k] = *(const PG8_LAS bf16x8*)(lds + PG8_SA(b, h) + aoff + m * 2048 + k * 1024); } while (0)
; #define PG8_LDB(dst, b, h) do { _Pragma("unroll") for (int n = 0; n < 2; ++n) _Pragma("unroll") for (int k = 0; k < 2; ++k) dst[n][k] = *(const PG8_LAS bf16x8*)(lds + PG8_SB(b, h) + boff + n * 2048 + k * 1024); } while (0)
; #define PG8_MMA(ai, bj, At, Bt) do { __builtin_amdgcn_s_setprio(1); _Pragma("unroll") for (int m = 0; m < 4; ++m) _Pragma("unroll") for (int n = 0; n < 2; ++n) _Pragma("unroll") for (int k = 0; k < 2; ++k) \
;         acc[ai][bj][m][n] = __builtin_amdgcn_mfma_f32_16x16x32_bf16(Bt[n][k], At[m][k], acc[ai][bj][m][n], 0, 0, 0); __builtin_amdgcn_s_setprio(0); } while (0)
; #define PG8_WAIT_V(n) asm volatile("s_waitcnt vmcnt(" #n ")" ::: "memory")
; #define PG8_WAIT_L(n) asm volatile("s_waitcnt lgkmcnt(" #n ")" ::: "memory")
; #define PG8_BAR __builtin_amdgcn_s_barrier()
; #define PG8_SCHED __builtin_amdgcn_sched_barrier(0)
; #define PG8_WAIT_V(n) asm volatile("s_waitcnt vmcnt(" #n ")" ::: "memory")
; #define PG8_WAIT_L(n) asm volatile("s_waitcnt lgkmcnt(" #n ")" ::: "memory")
; template <class Epi, class Sched, bool ALIGN_EPI = false, bool SP2 = false>
; __device__ __forceinline__ void gemm_phase(PG8_LAS unsigned char* lds, PG8_LAS unsigned char* pf, const Gemm g, const Sched& S, const Epi& E, int wv) {
;     ...
;             PG8_LDA(At, 0, 1); PG8_STAGE(PG8_SB(0, 0), b2, voffB); PG8_STAGE(PG8_SB(0, 1), b2 + hstepB, voffB); PG8_STAGE(PG8_SA(0, 0), a2, voffA);
;             PG8_WAIT_V(8); PG8_WAIT_L(0); PG8_BAR; PG8_MMA(1, 0, At, B0); PG8_MMA(1, 1, At, B1); PG8_BAR; PG8_SCHED;
;             PG8_LDB(B0, 1, 0); PG8_LDB(B1, 1, 1); PG8_SCHED; PG8_LDA(At, 1, 0); PG8_STAGE(PG8_SA(0, 1), a2 + (Sched::SPLIT ? ((last && has_next) ? (nxt.kh > 0 ? -(long)hstepA : (long)hstepA) : hsA) : (long)hstepA), voffA);
;             PG8_WAIT_V(8); PG8_WAIT_L(0); PG8_BAR; PG8_MMA(0, 0, At, B0); PG8_MMA(0, 1, At, B1); PG8_BAR; PG8_SCHED;
	s_waitcnt lgkmcnt(0)
	v_mfma_f32_16x16x32_bf16 v[60:63], v[92:95], v[174:177], v[60:63]
	v_mfma_f32_16x16x32_bf16 v[60:63], v[100:103], v[178:181], v[60:63]
	v_mfma_f32_16x16x32_bf16 v[56:59], v[104:107], v[174:177], v[56:59]
	v_mfma_f32_16x16x32_bf16 v[56:59], v[108:111], v[178:181], v[56:59]
	v_mfma_f32_16x16x32_bf16 v[52:55], v[92:95], v[182:185], v[52:55]
	v_mfma_f32_16x16x32_bf16 v[52:55], v[100:103], v[186:189], v[52:55]
	v_mfma_f32_16x16x32_bf16 v[48:51], v[104:107], v[182:185], v[48:51]
	v_mfma_f32_16x16x32_bf16 v[48:51], v[108:111], v[186:189], v[48:51]
	v_mfma_f32_16x16x32_bf16 v[44:47], v[92:95], v[190:193], v[44:47]
	v_mfma_f32_16x16x32_bf16 v[44:47], v[100:103], v[194:197], v[44:47]
	v_mfma_f32_16x16x32_bf16 v[40:43], v[104:107], v[190:193], v[40:43]
	v_mfma_f32_16x16x32_bf16 v[40:43], v[108:111], v[194:197], v[40:43]
	v_mfma_f32_16x16x32_bf16 v[36:39], v[92:95], v[198:201], v[36:39]
	v_mfma_f32_16x16x32_bf16 v[36:39], v[100:103], v[202:205], v[36:39]
	v_mfma_f32_16x16x32_bf16 v[32:35], v[104:107], v[198:201], v[32:35]
	v_mfma_f32_16x16x32_bf16 v[32:35], v[108:111], v[202:205], v[32:35]
	v_mfma_f32_16x16x32_bf16 v[28:31], v[112:115], v[174:177], v[28:31]
	v_mfma_f32_16x16x32_bf16 v[28:31], v[116:119], v[178:181], v[28:31]
	v_mfma_f32_16x16x32_bf16 v[24:27], v[152:155], v[174:177], v[24:27]
	v_mfma_f32_16x16x32_bf16 v[24:27], v[170:173], v[178:181], v[24:27]
	v_mfma_f32_16x16x32_bf16 v[20:23], v[112:115], v[182:185], v[20:23]
	v_mfma_f32_16x16x32_bf16 v[20:23], v[116:119], v[186:189], v[20:23]
	v_mfma_f32_16x16x32_bf16 v[16:19], v[152:155], v[182:185], v[16:19]
	v_mfma_f32_16x16x32_bf16 v[16:19], v[170:173], v[186:189], v[16:19]
	v_mfma_f32_16x16x32_bf16 v[12:15], v[112:115], v[190:193], v[12:15]
	v_mfma_f32_16x16x32_bf16 v[12:15], v[116:119], v[194:197], v[12:15]
	v_mfma_f32_16x16x32_bf16 v[8:11], v[152:155], v[190:193], v[8:11]
	v_mfma_f32_16x16x32_bf16 v[8:11], v[170:173], v[194:197], v[8:11]
	v_mfma_f32_16x16x32_bf16 v[4:7], v[112:115], v[198:201], v[4:7]
	v_mfma_f32_16x16x32_bf16 v[4:7], v[116:119], v[202:205], v[4:7]
	v_mfma_f32_16x16x32_bf16 v[0:3], v[152:155], v[198:201], v[0:3]
	v_mfma_f32_16x16x32_bf16 v[0:3], v[170:173], v[202:205], v[0:3]
	s_barrier
	s_add_i32 s24, 0, 0x18000
	s_add_i32 s25, 0, 0x1c000
	v_add_u32_e32 v108, s24, v224
	v_add_u32_e32 v160, s25, v224
	ds_read_b128 v[92:95], v108
	ds_read_b128 v[100:103], v108 offset:1024
	ds_read_b128 v[104:107], v108 offset:2048
	ds_read_b128 v[108:111], v108 offset:3072
	ds_read_b128 v[112:115], v160
	ds_read_b128 v[116:119], v160 offset:1024
	ds_read_b128 v[152:155], v160 offset:2048
	ds_read_b128 v[170:173], v160 offset:3072
	s_add_u32 s10, s36, 0x160000
	s_addc_u32 s11, s37, 0
	s_mov_b32 m0, s59
	v_lshl_add_u64 v[218:219], s[10:11], 0, v[156:157]
	ds_read_b128 v[174:177], v225 offset:32768
	ds_read_b128 v[178:181], v225 offset:33792
	ds_read_b128 v[182:185], v225 offset:34816
	ds_read_b128 v[186:189], v225 offset:35840
	ds_read_b128 v[190:193], v225 offset:36864
	ds_read_b128 v[194:197], v225 offset:37888
	ds_read_b128 v[198:201], v225 offset:38912
	ds_read_b128 v[202:205], v225 offset:39936
	global_load_lds_dwordx4 v[218:219], off
	v_lshl_add_u64 v[218:219], s[10:11], 0, v[162:163]
	s_mov_b32 m0, s60
	s_nop 0
	global_load_lds_dwordx4 v[218:219], off
	s_waitcnt vmcnt(8)
	s_waitcnt lgkmcnt(0)
	s_barrier
	s_waitcnt lgkmcnt(0)
	v_mfma_f32_16x16x32_bf16 v[148:151], v[92:95], v[174:177], v[148:151]
	v_mfma_f32_16x16x32_bf16 v[148:151], v[100:103], v[178:181], v[148:151]
	v_mfma_f32_16x16x32_bf16 v[144:147], v[104:107], v[174:177], v[144:147]
	v_mfma_f32_16x16x32_bf16 v[144:147], v[108:111], v[178:181], v[144:147]
	v_mfma_f32_16x16x32_bf16 v[140:143], v[92:95], v[182:185], v[140:143]
	v_mfma_f32_16x16x32_bf16 v[140:143], v[100:103], v[186:189], v[140:143]
	v_mfma_f32_16x16x32_bf16 v[136:139], v[104:107], v[182:185], v[136:139]
	v_mfma_f32_16x16x32_bf16 v[136:139], v[108:111], v[186:189], v[136:139]
	v_mfma_f32_16x16x32_bf16 v[132:135], v[92:95], v[190:193], v[132:135]
	v_mfma_f32_16x16x32_bf16 v[132:135], v[100:103], v[194:197], v[132:135]
	v_mfma_f32_16x16x32_bf16 v[128:131], v[104:107], v[190:193], v[128:131]
	v_mfma_f32_16x16x32_bf16 v[128:131], v[108:111], v[194:197], v[128:131]
	v_mfma_f32_16x16x32_bf16 v[124:127], v[92:95], v[198:201], v[124:127]
	v_mfma_f32_16x16x32_bf16 v[124:127], v[100:103], v[202:205], v[124:127]
	v_mfma_f32_16x16x32_bf16 v[120:123], v[104:107], v[198:201], v[120:123]
	v_mfma_f32_16x16x32_bf16 v[120:123], v[108:111], v[202:205], v[120:123]
	v_mfma_f32_16x16x32_bf16 v[96:99], v[112:115], v[174:177], v[96:99]
	v_mfma_f32_16x16x32_bf16 v[96:99], v[116:119], v[178:181], v[96:99]
	v_mfma_f32_16x16x32_bf16 v[88:91], v[152:155], v[174:177], v[88:91]
	v_mfma_f32_16x16x32_bf16 v[88:91], v[170:173], v[178:181], v[88:91]
	v_mfma_f32_16x16x32_bf16 v[84:87], v[112:115], v[182:185], v[84:87]
	v_mfma_f32_16x16x32_bf16 v[84:87], v[116:119], v[186:189], v[84:87]
	v_mfma_f32_16x16x32_bf16 v[80:83], v[152:155], v[182:185], v[80:83]
	v_mfma_f32_16x16x32_bf16 v[80:83], v[170:173], v[186:189], v[80:83]
	v_mfma_f32_16x16x32_bf16 v[76:79], v[112:115], v[190:193], v[76:79]
	v_mfma_f32_16x16x32_bf16 v[76:79], v[116:119], v[194:197], v[76:79]
	v_mfma_f32_16x16x32_bf16 v[72:75], v[152:155], v[190:193], v[72:75]
	v_mfma_f32_16x16x32_bf16 v[72:75], v[170:173], v[194:197], v[72:75]
	v_mfma_f32_16x16x32_bf16 v[68:71], v[112:115], v[198:201], v[68:71]
	v_mfma_f32_16x16x32_bf16 v[68:71], v[116:119], v[202:205], v[68:71]
	v_mfma_f32_16x16x32_bf16 v[64:67], v[152:155], v[198:201], v[64:67]
	v_mfma_f32_16x16x32_bf16 v[64:67], v[170:173], v[202:205], v[64:67]
	s_barrier
; #define PG8_STAGE(bufoff, gbase, voff) do { _Pragma("unroll") for (int _i = 0; _i < 2; ++_i) \
;         __builtin_amdgcn_global_load_lds((const GAS unsigned*)((const GAS char*)(gbase) + (voff)[_i]), (PG8_LAS unsigned*)(lds + (bufoff) + ldsw + _i * 8192), 16, 0, 0); } while (0)
; #define PG8_LDA(dst, b, h) do { _Pragma("unroll") for (int m = 0; m < 4; ++m) _Pragma("unroll") for (int k = 0; k < 2; ++k) dst[m][k] = *(const PG8_LAS bf16x8*)(lds + PG8_SA(b, h) + aoff + m * 2048 + k * 1024); } while (0)
; #define PG8_LDB(dst, b, h) do { _Pragma("unroll") for (int n = 0; n < 2; ++n) _Pragma("unroll") for (int k = 0; k < 2; ++k) dst[n][k] = *(const PG8_LAS bf16x8*)(lds + PG8_SB(b, h) + boff + n * 2048 + k * 1024); } while (0)
; #define PG8_MMA(ai, bj, At, Bt) do { __builtin_amdgcn_s_setprio(1); _Pragma("unroll") for (int m = 0; m < 4; ++m) _Pragma("unroll") for (int n = 0; n < 2; ++n) _Pragma("unroll") for (int k = 0; k < 2; ++k) \
;         acc[ai][bj][m][n] = __builtin_amdgcn_mfma_f32_16x16x32_bf16(Bt[n][k], At[m][k], acc[ai][bj][m][n], 0, 0, 0); __builtin_amdgcn_s_setprio(0); } while (0)
; #define PG8_WAIT_V(n) asm volatile("s_waitcnt vmcnt(" #n ")" ::: "memory")
; #define PG8_WAIT_L(n) asm volatile("s_waitcnt lgkmcnt(" #n ")" ::: "memory")
; #define PG8_BAR __builtin_amdgcn_s_barrier()
; #define PG8_SCHED __builtin_amdgcn_sched_barrier(0)
; #define PG8_WAIT_V(n) asm volatile("s_waitcnt vmcnt(" #n ")" ::: "memory")
; #define PG8_WAIT_L(n) asm volatile("s_waitcnt lgkmcnt(" #n ")" ::: "memory")
; template <class Epi, class Sched, bool ALIGN_EPI = false, bool SP2 = false>
; __device__ __forceinline__ void gemm_phase(PG8_LAS unsigned char* lds, PG8_LAS unsigned char* pf, const Gemm g, const Sched& S, const Epi& E, int wv) {
;     ...
;             PG8_LDB(B0, 1, 0); PG8_LDB(B1, 1, 1); PG8_SCHED; PG8_LDA(At, 1, 0); PG8_STAGE(PG8_SA(0, 1), a2 + (Sched::SPLIT ? ((last && has_next) ? (nxt.kh > 0 ? -(long)hstepA : (long)hstepA) : hsA) : (long)hstepA), voffA);
;             PG8_WAIT_V(8); PG8_WAIT_L(0); PG8_BAR; PG8_MMA(0, 0, At, B0); PG8_MMA(0, 1, At, B1); PG8_BAR; PG8_SCHED;
;             PG8_LDA(At, 1, 1); PG8_STAGE(PG8_SB(1, 0), b3, voffB); PG8_STAGE(PG8_SB(1, 1), b3 + hstepB, voffB); PG8_STAGE(PG8_SA(1, 0), a3, voffA);
;             PG8_WAIT_V(8); PG8_WAIT_L(0); PG8_BAR; PG8_MMA(1, 0, At, B0); PG8_MMA(1, 1, At, B1); PG8_BAR; PG8_SCHED;
	s_add_i32 s10, s24, s27
	v_lshl_add_u64 v[206:207], v[206:207], 0, s[16:17]
	s_mov_b32 m0, s10
	ds_read_b128 v[174:177], v225 offset:49152
	ds_read_b128 v[178:181], v225 offset:50176
	ds_read_b128 v[182:185], v225 offset:51200
	ds_read_b128 v[186:189], v225 offset:52224
	ds_read_b128 v[190:193], v225 offset:53248
	ds_read_b128 v[194:197], v225 offset:54272
	ds_read_b128 v[198:201], v225 offset:55296
	ds_read_b128 v[202:205], v225 offset:56320
	global_load_lds_dwordx4 v[206:207], off
	s_add_i32 m0, s10, 0x2000
	s_add_u32 s10, s14, 0x160080
	v_lshl_add_u64 v[206:207], v[208:209], 0, s[16:17]
	s_addc_u32 s11, s15, 0
	s_add_i32 s14, s25, s27
	global_load_lds_dwordx4 v[206:207], off
	v_lshl_add_u64 v[206:207], s[10:11], 0, v[158:159]
	s_mov_b32 m0, s14
	s_nop 0
	global_load_lds_dwordx4 v[206:207], off
	v_lshl_add_u64 v[206:207], s[10:11], 0, v[164:165]
	s_add_i32 m0, s14, 0x2000
	s_nop 0
	global_load_lds_dwordx4 v[206:207], off
	v_lshl_add_u64 v[206:207], v[214:215], 0, s[16:17]
	s_mov_b32 m0, s64
	s_nop 0
	global_load_lds_dwordx4 v[206:207], off
	v_lshl_add_u64 v[206:207], v[216:217], 0, s[16:17]
	s_mov_b32 m0, s65
	s_nop 0
	global_load_lds_dwordx4 v[206:207], off
	s_waitcnt vmcnt(8)
	s_waitcnt lgkmcnt(0)
	s_barrier
	s_waitcnt lgkmcnt(0)
	v_mfma_f32_16x16x32_bf16 v[60:63], v[92:95], v[174:177], v[60:63]
	v_mfma_f32_16x16x32_bf16 v[60:63], v[100:103], v[178:181], v[60:63]
	v_mfma_f32_16x16x32_bf16 v[56:59], v[104:107], v[174:177], v[56:59]
	v_mfma_f32_16x16x32_bf16 v[56:59], v[108:111], v[178:181], v[56:59]
	v_mfma_f32_16x16x32_bf16 v[52:55], v[92:95], v[182:185], v[52:55]
	v_mfma_f32_16x16x32_bf16 v[52:55], v[100:103], v[186:189], v[52:55]
	v_mfma_f32_16x16x32_bf16 v[48:51], v[104:107], v[182:185], v[48:51]
	v_mfma_f32_16x16x32_bf16 v[48:51], v[108:111], v[186:189], v[48:51]
	v_mfma_f32_16x16x32_bf16 v[44:47], v[92:95], v[190:193], v[44:47]
	v_mfma_f32_16x16x32_bf16 v[44:47], v[100:103], v[194:197], v[44:47]
	v_mfma_f32_16x16x32_bf16 v[40:43], v[104:107], v[190:193], v[40:43]
	v_mfma_f32_16x16x32_bf16 v[40:43], v[108:111], v[194:197], v[40:43]
	v_mfma_f32_16x16x32_bf16 v[36:39], v[92:95], v[198:201], v[36:39]
	v_mfma_f32_16x16x32_bf16 v[36:39], v[100:103], v[202:205], v[36:39]
	v_mfma_f32_16x16x32_bf16 v[32:35], v[104:107], v[198:201], v[32:35]
	v_mfma_f32_16x16x32_bf16 v[32:35], v[108:111], v[202:205], v[32:35]
	v_mfma_f32_16x16x32_bf16 v[28:31], v[112:115], v[174:177], v[28:31]
	v_mfma_f32_16x16x32_bf16 v[28:31], v[116:119], v[178:181], v[28:31]
	v_mfma_f32_16x16x32_bf16 v[24:27], v[152:155], v[174:177], v[24:27]
	v_mfma_f32_16x16x32_bf16 v[24:27], v[170:173], v[178:181], v[24:27]
	v_mfma_f32_16x16x32_bf16 v[20:23], v[112:115], v[182:185], v[20:23]
	v_mfma_f32_16x16x32_bf16 v[20:23], v[116:119], v[186:189], v[20:23]
	v_mfma_f32_16x16x32_bf16 v[16:19], v[152:155], v[182:185], v[16:19]
	v_mfma_f32_16x16x32_bf16 v[16:19], v[170:173], v[186:189], v[16:19]
	v_mfma_f32_16x16x32_bf16 v[12:15], v[112:115], v[190:193], v[12:15]
	v_mfma_f32_16x16x32_bf16 v[12:15], v[116:119], v[194:197], v[12:15]
	v_mfma_f32_16x16x32_bf16 v[8:11], v[152:155], v[190:193], v[8:11]
	v_mfma_f32_16x16x32_bf16 v[8:11], v[170:173], v[194:197], v[8:11]
	v_mfma_f32_16x16x32_bf16 v[4:7], v[112:115], v[198:201], v[4:7]
	v_mfma_f32_16x16x32_bf16 v[4:7], v[116:119], v[202:205], v[4:7]
	v_mfma_f32_16x16x32_bf16 v[0:3], v[152:155], v[198:201], v[0:3]
	v_mfma_f32_16x16x32_bf16 v[0:3], v[170:173], v[202:205], v[0:3]
	s_barrier
	s_add_i32 s23, s23, 2
	s_add_u32 s21, s21, 0x100
	s_addc_u32 s22, s22, 0
	s_cmpk_gt_u32 s23, 0x55
	s_mov_b64 s[10:11], s[12:13]
	s_cbranch_scc0 .LBB0_1760
	s_and_b64 vcc, exec, s[4:5]
	s_cbranch_vccz .LBB0_1763
	s_barrier
